# loop-edge: in all 7 GEMM K-loops the counter/pointer SALU block moved from after the last barrier of the iteration to before it
# baseline (speedup 1.0000x reference)
; #define PG8_STAGE(bufoff, gbase, voff) do { _Pragma("unroll") for (int _i = 0; _i < 2; ++_i) \
;         __builtin_amdgcn_global_load_lds((const unsigned*)((const char*)(gbase) + (voff)[_i]), (PG8_LAS unsigned*)(lds + (bufoff) + ldsw + _i * 8192), 16, 0, 0); } while (0)
; #define PG8_LDA(dst, b, h) do { _Pragma("unroll") for (int m = 0; m < 4; ++m) _Pragma("unroll") for (int k = 0; k < 2; ++k) dst[m][k] = *(const PG8_LAS bf16x8*)(lds + PG8_SA(b, h) + aoff + m * 2048 + k * 1024); } while (0)
; #define PG8_LDB(dst, b, h) do { _Pragma("unroll") for (int n = 0; n < 2; ++n) _Pragma("unroll") for (int k = 0; k < 2; ++k) dst[n][k] = *(const PG8_LAS bf16x8*)(lds + PG8_SB(b, h) + boff + n * 2048 + k * 1024); } while (0)
; #define PG8_MMA(ai, bj, At, Bt) do { __builtin_amdgcn_s_setprio(1); _Pragma("unroll") for (int m = 0; m < 4; ++m) _Pragma("unroll") for (int n = 0; n < 2; ++n) _Pragma("unroll") for (int k = 0; k < 2; ++k) \
;         acc[ai][bj][m][n] = __builtin_amdgcn_mfma_f32_16x16x32_bf16(Bt[n][k], At[m][k], acc[ai][bj][m][n], 0, 0, 0); __builtin_amdgcn_s_setprio(0); } while (0)
; #define PG8_WAIT_V(n) asm volatile("s_waitcnt vmcnt(" #n ")" ::: "memory")
; template <class Epi, class Sched, bool ALIGN_EPI = false, bool SP2 = false, bool A_TILED = false, bool B_TILED = false>
; __device__ __forceinline__ void gemm_phase(PG8_LAS unsigned char* lds, const Gemm g, const Sched& S, const Epi& E) {
;     ...
;         for (int t = 0; t < nt; t += 2) {
;             const bool last = (t == nt - 2);
;             const char* a1 = cA + (size_t)(t + 1) * kstepA;
;             const char* a2 = last ? nA : cA + (size_t)(t + 2) * kstepA; const char* b2 = last ? nB : cB + (size_t)(t + 2) * kstepB;
;             const char* a3 = a2 + kstepA; const char* b3 = b2 + kstepB;
;             if (last && has_next) S.a_ready(nxt);
;             if constexpr (SP2) {
;             PG8_LDB(B0, 0, 0); PG8_LDB(B1, 0, 1); PG8_SCHED; PG8_LDA(At, 0, 0); PG8_STAGE(PG8_SA(1, 1), a1 + hstepA, voffA);
;             PG8_WAIT_V(8); PG8_WAIT_L(0); PG8_BAR; PG8_MMA(0, 0, At, B0); PG8_MMA(0, 1, At, B1); PG8_BAR; PG8_SCHED;
;             PG8_LDA(At, 0, 1); PG8_STAGE(PG8_SB(0, 0), b2, voffB); PG8_STAGE(PG8_SB(0, 1), b2 + hstepB, voffB); PG8_STAGE(PG8_SA(0, 0), a2, voffA);
;             PG8_WAIT_V(8); PG8_WAIT_L(0); PG8_BAR; PG8_MMA(1, 0, At, B0); PG8_MMA(1, 1, At, B1); PG8_BAR; PG8_SCHED;
.LBB0_102:
	ds_read_b128 v[142:145], v148
	ds_read_b128 v[152:155], v148 offset:1024
	ds_read_b128 v[156:159], v148 offset:2048
	ds_read_b128 v[160:163], v148 offset:3072
	ds_read_b128 v[164:167], v149
	ds_read_b128 v[168:171], v149 offset:1024
	ds_read_b128 v[172:175], v149 offset:2048
	ds_read_b128 v[176:179], v149 offset:3072
	s_add_u32 s36, s34, 0xfff00080
	s_addc_u32 s37, s35, -1
	s_cmp_eq_u32 s68, 60
	s_cselect_b32 s39, s21, s37
	s_cselect_b32 s38, s23, s36
	s_cselect_b32 s37, s19, s67
	s_cselect_b32 s36, s65, s66
	v_lshl_add_u64 v[214:215], s[34:35], 0, v[138:139]
	s_add_i32 m0, s25, 0xc000
	ds_read_b128 v[180:183], v150
	ds_read_b128 v[184:187], v150 offset:1024
	ds_read_b128 v[190:193], v150 offset:2048
	ds_read_b128 v[194:197], v150 offset:3072
	ds_read_b128 v[198:201], v150 offset:4096
	ds_read_b128 v[202:205], v150 offset:5120
	ds_read_b128 v[206:209], v150 offset:6144
	ds_read_b128 v[210:213], v150 offset:7168
	global_load_lds_dwordx4 v[214:215], off
	v_lshl_add_u64 v[214:215], s[34:35], 0, v[140:141]
	s_add_i32 m0, s25, 0xe000
	s_nop 0
	global_load_lds_dwordx4 v[214:215], off
	s_waitcnt vmcnt(8)
	s_waitcnt lgkmcnt(0)
	s_barrier
	v_mfma_f32_16x16x32_bf16 v[126:129], v[142:145], v[180:183], v[126:129]
	v_mfma_f32_16x16x32_bf16 v[122:125], v[156:159], v[180:183], v[122:125]
	v_mfma_f32_16x16x32_bf16 v[118:121], v[142:145], v[190:193], v[118:121]
	v_mfma_f32_16x16x32_bf16 v[110:113], v[156:159], v[190:193], v[110:113]
	v_mfma_f32_16x16x32_bf16 v[102:105], v[142:145], v[198:201], v[102:105]
	v_mfma_f32_16x16x32_bf16 v[94:97], v[156:159], v[198:201], v[94:97]
	v_mfma_f32_16x16x32_bf16 v[86:89], v[142:145], v[206:209], v[86:89]
	v_mfma_f32_16x16x32_bf16 v[78:81], v[156:159], v[206:209], v[78:81]
	v_mfma_f32_16x16x32_bf16 v[126:129], v[152:155], v[184:187], v[126:129]
	v_mfma_f32_16x16x32_bf16 v[122:125], v[160:163], v[184:187], v[122:125]
	v_mfma_f32_16x16x32_bf16 v[118:121], v[152:155], v[194:197], v[118:121]
	v_mfma_f32_16x16x32_bf16 v[110:113], v[160:163], v[194:197], v[110:113]
	v_mfma_f32_16x16x32_bf16 v[102:105], v[152:155], v[202:205], v[102:105]
	v_mfma_f32_16x16x32_bf16 v[94:97], v[160:163], v[202:205], v[94:97]
	v_mfma_f32_16x16x32_bf16 v[86:89], v[152:155], v[210:213], v[86:89]
	v_mfma_f32_16x16x32_bf16 v[78:81], v[160:163], v[210:213], v[78:81]
	v_mfma_f32_16x16x32_bf16 v[114:117], v[164:167], v[180:183], v[114:117]
	v_mfma_f32_16x16x32_bf16 v[106:109], v[172:175], v[180:183], v[106:109]
	v_mfma_f32_16x16x32_bf16 v[98:101], v[164:167], v[190:193], v[98:101]
	v_mfma_f32_16x16x32_bf16 v[90:93], v[172:175], v[190:193], v[90:93]
	v_mfma_f32_16x16x32_bf16 v[82:85], v[164:167], v[198:201], v[82:85]
	v_mfma_f32_16x16x32_bf16 v[74:77], v[172:175], v[198:201], v[74:77]
	v_mfma_f32_16x16x32_bf16 v[70:73], v[164:167], v[206:209], v[70:73]
	v_mfma_f32_16x16x32_bf16 v[66:69], v[172:175], v[206:209], v[66:69]
	v_mfma_f32_16x16x32_bf16 v[114:117], v[168:171], v[184:187], v[114:117]
	v_mfma_f32_16x16x32_bf16 v[106:109], v[176:179], v[184:187], v[106:109]
	v_mfma_f32_16x16x32_bf16 v[98:101], v[168:171], v[194:197], v[98:101]
	v_mfma_f32_16x16x32_bf16 v[90:93], v[176:179], v[194:197], v[90:93]
	v_mfma_f32_16x16x32_bf16 v[82:85], v[168:171], v[202:205], v[82:85]
	v_mfma_f32_16x16x32_bf16 v[74:77], v[176:179], v[202:205], v[74:77]
	v_mfma_f32_16x16x32_bf16 v[70:73], v[168:171], v[210:213], v[70:73]
	v_mfma_f32_16x16x32_bf16 v[66:69], v[176:179], v[210:213], v[66:69]
	s_barrier
	s_add_i32 s69, s61, s43
	v_lshl_add_u64 v[214:215], s[36:37], 0, v[132:133]
	s_mov_b32 m0, s69
	ds_read_b128 v[180:183], v150 offset:16384
	ds_read_b128 v[184:187], v150 offset:17408
	ds_read_b128 v[190:193], v150 offset:18432
	ds_read_b128 v[194:197], v150 offset:19456
	ds_read_b128 v[198:201], v150 offset:20480
	ds_read_b128 v[202:205], v150 offset:21504
	ds_read_b128 v[206:209], v150 offset:22528
	ds_read_b128 v[210:213], v150 offset:23552
	global_load_lds_dwordx4 v[214:215], off
	s_add_i32 m0, s69, 0x2000
	s_add_u32 s70, s36, 0x100000
	v_lshl_add_u64 v[216:217], s[36:37], 0, v[136:137]
	s_addc_u32 s71, s37, 0
	s_add_i32 s69, s62, s43
	global_load_lds_dwordx4 v[216:217], off
	v_lshl_add_u64 v[218:219], s[70:71], 0, v[132:133]
	s_mov_b32 m0, s69
	v_lshl_add_u64 v[220:221], s[38:39], 0, v[134:135]
	global_load_lds_dwordx4 v[218:219], off
	v_lshl_add_u64 v[218:219], s[70:71], 0, v[136:137]
	s_add_i32 m0, s69, 0x2000
	s_nop 0
	global_load_lds_dwordx4 v[218:219], off
	v_lshl_add_u64 v[218:219], s[38:39], 0, v[130:131]
	s_mov_b32 m0, s25
	s_nop 0
	global_load_lds_dwordx4 v[218:219], off
	s_mov_b32 m0, s44
	s_nop 0
	global_load_lds_dwordx4 v[220:221], off
	s_waitcnt vmcnt(8)
	s_waitcnt lgkmcnt(0)
	s_barrier
; #define PG8_STAGE(bufoff, gbase, voff) do { _Pragma("unroll") for (int _i = 0; _i < 2; ++_i) \
;         __builtin_amdgcn_global_load_lds((const unsigned*)((const char*)(gbase) + (voff)[_i]), (PG8_LAS unsigned*)(lds + (bufoff) + ldsw + _i * 8192), 16, 0, 0); } while (0)
; #define PG8_LDA(dst, b, h) do { _Pragma("unroll") for (int m = 0; m < 4; ++m) _Pragma("unroll") for (int k = 0; k < 2; ++k) dst[m][k] = *(const PG8_LAS bf16x8*)(lds + PG8_SA(b, h) + aoff + m * 2048 + k * 1024); } while (0)
; #define PG8_LDB(dst, b, h) do { _Pragma("unroll") for (int n = 0; n < 2; ++n) _Pragma("unroll") for (int k = 0; k < 2; ++k) dst[n][k] = *(const PG8_LAS bf16x8*)(lds + PG8_SB(b, h) + boff + n * 2048 + k * 1024); } while (0)
; #define PG8_MMA(ai, bj, At, Bt) do { __builtin_amdgcn_s_setprio(1); _Pragma("unroll") for (int m = 0; m < 4; ++m) _Pragma("unroll") for (int n = 0; n < 2; ++n) _Pragma("unroll") for (int k = 0; k < 2; ++k) \
;         acc[ai][bj][m][n] = __builtin_amdgcn_mfma_f32_16x16x32_bf16(Bt[n][k], At[m][k], acc[ai][bj][m][n], 0, 0, 0); __builtin_amdgcn_s_setprio(0); } while (0)
; #define PG8_WAIT_V(n) asm volatile("s_waitcnt vmcnt(" #n ")" ::: "memory")
; #define PG8_WAIT_L(n) asm volatile("s_waitcnt lgkmcnt(" #n ")" ::: "memory")
; #define PG8_BAR __builtin_amdgcn_s_barrier()
; #define PG8_SCHED __builtin_amdgcn_sched_barrier(0)
; template <class Epi, class Sched, bool ALIGN_EPI = false, bool SP2 = false, bool A_TILED = false, bool B_TILED = false>
; __device__ __forceinline__ void gemm_phase(PG8_LAS unsigned char* lds, const Gemm g, const Sched& S, const Epi& E) {
;     ...
;             PG8_WAIT_V(8); PG8_WAIT_L(0); PG8_BAR; PG8_MMA(1, 0, At, B0); PG8_MMA(1, 1, At, B1); PG8_BAR; PG8_SCHED;
;             PG8_LDB(B0, 1, 0); PG8_LDB(B1, 1, 1); PG8_SCHED; PG8_LDA(At, 1, 0); PG8_STAGE(PG8_SA(0, 1), a2 + hstepA, voffA);
;             PG8_WAIT_V(8); PG8_WAIT_L(0); PG8_BAR; PG8_MMA(0, 0, At, B0); PG8_MMA(0, 1, At, B1); PG8_BAR; PG8_SCHED;
	v_mfma_f32_16x16x32_bf16 v[62:65], v[142:145], v[180:183], v[62:65]
	v_mfma_f32_16x16x32_bf16 v[58:61], v[156:159], v[180:183], v[58:61]
	v_mfma_f32_16x16x32_bf16 v[54:57], v[142:145], v[190:193], v[54:57]
	v_mfma_f32_16x16x32_bf16 v[46:49], v[156:159], v[190:193], v[46:49]
	v_mfma_f32_16x16x32_bf16 v[38:41], v[142:145], v[198:201], v[38:41]
	v_mfma_f32_16x16x32_bf16 v[30:33], v[156:159], v[198:201], v[30:33]
	v_mfma_f32_16x16x32_bf16 v[22:25], v[142:145], v[206:209], v[22:25]
	v_mfma_f32_16x16x32_bf16 v[14:17], v[156:159], v[206:209], v[14:17]
	v_mfma_f32_16x16x32_bf16 v[62:65], v[152:155], v[184:187], v[62:65]
	v_mfma_f32_16x16x32_bf16 v[58:61], v[160:163], v[184:187], v[58:61]
	v_mfma_f32_16x16x32_bf16 v[54:57], v[152:155], v[194:197], v[54:57]
	v_mfma_f32_16x16x32_bf16 v[46:49], v[160:163], v[194:197], v[46:49]
	v_mfma_f32_16x16x32_bf16 v[38:41], v[152:155], v[202:205], v[38:41]
	v_mfma_f32_16x16x32_bf16 v[30:33], v[160:163], v[202:205], v[30:33]
	v_mfma_f32_16x16x32_bf16 v[22:25], v[152:155], v[210:213], v[22:25]
	v_mfma_f32_16x16x32_bf16 v[14:17], v[160:163], v[210:213], v[14:17]
	v_mfma_f32_16x16x32_bf16 v[50:53], v[164:167], v[180:183], v[50:53]
	v_mfma_f32_16x16x32_bf16 v[42:45], v[172:175], v[180:183], v[42:45]
	v_mfma_f32_16x16x32_bf16 v[34:37], v[164:167], v[190:193], v[34:37]
	v_mfma_f32_16x16x32_bf16 v[26:29], v[172:175], v[190:193], v[26:29]
	v_mfma_f32_16x16x32_bf16 v[18:21], v[164:167], v[198:201], v[18:21]
	v_mfma_f32_16x16x32_bf16 v[10:13], v[172:175], v[198:201], v[10:13]
	v_mfma_f32_16x16x32_bf16 v[6:9], v[164:167], v[206:209], v[6:9]
	v_mfma_f32_16x16x32_bf16 v[2:5], v[172:175], v[206:209], v[2:5]
	v_mfma_f32_16x16x32_bf16 v[50:53], v[168:171], v[184:187], v[50:53]
	v_mfma_f32_16x16x32_bf16 v[42:45], v[176:179], v[184:187], v[42:45]
	v_mfma_f32_16x16x32_bf16 v[34:37], v[168:171], v[194:197], v[34:37]
	v_mfma_f32_16x16x32_bf16 v[26:29], v[176:179], v[194:197], v[26:29]
	v_mfma_f32_16x16x32_bf16 v[18:21], v[168:171], v[202:205], v[18:21]
	v_mfma_f32_16x16x32_bf16 v[10:13], v[176:179], v[202:205], v[10:13]
	v_mfma_f32_16x16x32_bf16 v[6:9], v[168:171], v[210:213], v[6:9]
	v_mfma_f32_16x16x32_bf16 v[2:5], v[176:179], v[210:213], v[2:5]
	s_barrier
	s_add_i32 s69, 0, 0x18000
	v_add_u32_e32 v151, s69, v146
	s_add_i32 s70, 0, 0x1c000
	ds_read_b128 v[142:145], v151
	ds_read_b128 v[152:155], v151 offset:1024
	ds_read_b128 v[156:159], v151 offset:2048
	ds_read_b128 v[160:163], v151 offset:3072
	v_add_u32_e32 v151, s70, v146
	ds_read_b128 v[164:167], v151
	ds_read_b128 v[168:171], v151 offset:1024
	ds_read_b128 v[172:175], v151 offset:2048
	ds_read_b128 v[176:179], v151 offset:3072
	s_add_u32 s38, s38, 0x100000
	s_addc_u32 s39, s39, 0
	s_mov_b32 m0, s45
	v_lshl_add_u64 v[222:223], s[38:39], 0, v[130:131]
	ds_read_b128 v[180:183], v150 offset:32768
	ds_read_b128 v[184:187], v150 offset:33792
	ds_read_b128 v[190:193], v150 offset:34816
	ds_read_b128 v[194:197], v150 offset:35840
	ds_read_b128 v[198:201], v150 offset:36864
	ds_read_b128 v[202:205], v150 offset:37888
	ds_read_b128 v[206:209], v150 offset:38912
	ds_read_b128 v[210:213], v150 offset:39936
	global_load_lds_dwordx4 v[222:223], off
	v_lshl_add_u64 v[222:223], s[38:39], 0, v[134:135]
	s_mov_b32 m0, s46
	s_nop 0
	global_load_lds_dwordx4 v[222:223], off
	s_waitcnt vmcnt(8)
	s_waitcnt lgkmcnt(0)
	s_barrier
	v_mfma_f32_16x16x32_bf16 v[126:129], v[142:145], v[180:183], v[126:129]
	v_mfma_f32_16x16x32_bf16 v[122:125], v[156:159], v[180:183], v[122:125]
	v_mfma_f32_16x16x32_bf16 v[118:121], v[142:145], v[190:193], v[118:121]
	v_mfma_f32_16x16x32_bf16 v[110:113], v[156:159], v[190:193], v[110:113]
	v_mfma_f32_16x16x32_bf16 v[102:105], v[142:145], v[198:201], v[102:105]
	v_mfma_f32_16x16x32_bf16 v[94:97], v[156:159], v[198:201], v[94:97]
	v_mfma_f32_16x16x32_bf16 v[86:89], v[142:145], v[206:209], v[86:89]
	v_mfma_f32_16x16x32_bf16 v[78:81], v[156:159], v[206:209], v[78:81]
	v_mfma_f32_16x16x32_bf16 v[126:129], v[152:155], v[184:187], v[126:129]
	v_mfma_f32_16x16x32_bf16 v[122:125], v[160:163], v[184:187], v[122:125]
	v_mfma_f32_16x16x32_bf16 v[118:121], v[152:155], v[194:197], v[118:121]
	v_mfma_f32_16x16x32_bf16 v[110:113], v[160:163], v[194:197], v[110:113]
	v_mfma_f32_16x16x32_bf16 v[102:105], v[152:155], v[202:205], v[102:105]
	v_mfma_f32_16x16x32_bf16 v[94:97], v[160:163], v[202:205], v[94:97]
	v_mfma_f32_16x16x32_bf16 v[86:89], v[152:155], v[210:213], v[86:89]
	v_mfma_f32_16x16x32_bf16 v[78:81], v[160:163], v[210:213], v[78:81]
	v_mfma_f32_16x16x32_bf16 v[114:117], v[164:167], v[180:183], v[114:117]
	v_mfma_f32_16x16x32_bf16 v[106:109], v[172:175], v[180:183], v[106:109]
	v_mfma_f32_16x16x32_bf16 v[98:101], v[164:167], v[190:193], v[98:101]
	v_mfma_f32_16x16x32_bf16 v[90:93], v[172:175], v[190:193], v[90:93]
	v_mfma_f32_16x16x32_bf16 v[82:85], v[164:167], v[198:201], v[82:85]
	v_mfma_f32_16x16x32_bf16 v[74:77], v[172:175], v[198:201], v[74:77]
	v_mfma_f32_16x16x32_bf16 v[70:73], v[164:167], v[206:209], v[70:73]
	v_mfma_f32_16x16x32_bf16 v[66:69], v[172:175], v[206:209], v[66:69]
	v_mfma_f32_16x16x32_bf16 v[114:117], v[168:171], v[184:187], v[114:117]
	v_mfma_f32_16x16x32_bf16 v[106:109], v[176:179], v[184:187], v[106:109]
	v_mfma_f32_16x16x32_bf16 v[98:101], v[168:171], v[194:197], v[98:101]
	v_mfma_f32_16x16x32_bf16 v[90:93], v[176:179], v[194:197], v[90:93]
	v_mfma_f32_16x16x32_bf16 v[82:85], v[168:171], v[202:205], v[82:85]
	v_mfma_f32_16x16x32_bf16 v[74:77], v[176:179], v[202:205], v[74:77]
	v_mfma_f32_16x16x32_bf16 v[70:73], v[168:171], v[210:213], v[70:73]
	v_mfma_f32_16x16x32_bf16 v[66:69], v[176:179], v[210:213], v[66:69]
	s_barrier
; #define PG8_STAGE(bufoff, gbase, voff) do { _Pragma("unroll") for (int _i = 0; _i < 2; ++_i) \
;         __builtin_amdgcn_global_load_lds((const unsigned*)((const char*)(gbase) + (voff)[_i]), (PG8_LAS unsigned*)(lds + (bufoff) + ldsw + _i * 8192), 16, 0, 0); } while (0)
; #define PG8_LDA(dst, b, h) do { _Pragma("unroll") for (int m = 0; m < 4; ++m) _Pragma("unroll") for (int k = 0; k < 2; ++k) dst[m][k] = *(const PG8_LAS bf16x8*)(lds + PG8_SA(b, h) + aoff + m * 2048 + k * 1024); } while (0)
; #define PG8_MMA(ai, bj, At, Bt) do { __builtin_amdgcn_s_setprio(1); _Pragma("unroll") for (int m = 0; m < 4; ++m) _Pragma("unroll") for (int n = 0; n < 2; ++n) _Pragma("unroll") for (int k = 0; k < 2; ++k) \
;         acc[ai][bj][m][n] = __builtin_amdgcn_mfma_f32_16x16x32_bf16(Bt[n][k], At[m][k], acc[ai][bj][m][n], 0, 0, 0); __builtin_amdgcn_s_setprio(0); } while (0)
; #define PG8_WAIT_V(n) asm volatile("s_waitcnt vmcnt(" #n ")" ::: "memory")
; #define PG8_WAIT_L(n) asm volatile("s_waitcnt lgkmcnt(" #n ")" ::: "memory")
; #define PG8_BAR __builtin_amdgcn_s_barrier()
; #define PG8_SCHED __builtin_amdgcn_sched_barrier(0)
; template <class Epi, class Sched, bool ALIGN_EPI = false, bool SP2 = false, bool A_TILED = false, bool B_TILED = false>
; __device__ __forceinline__ void gemm_phase(PG8_LAS unsigned char* lds, const Gemm g, const Sched& S, const Epi& E) {
;     ...
;         for (int t = 0; t < nt; t += 2) {
;     ...
;             PG8_WAIT_V(8); PG8_WAIT_L(0); PG8_BAR; PG8_MMA(0, 0, At, B0); PG8_MMA(0, 1, At, B1); PG8_BAR; PG8_SCHED;
;             PG8_LDA(At, 1, 1); PG8_STAGE(PG8_SB(1, 0), b3, voffB); PG8_STAGE(PG8_SB(1, 1), b3 + hstepB, voffB); PG8_STAGE(PG8_SA(1, 0), a3, voffA);
;             PG8_WAIT_V(8); PG8_WAIT_L(0); PG8_BAR; PG8_MMA(1, 0, At, B0); PG8_MMA(1, 1, At, B1); PG8_BAR; PG8_SCHED;
	s_add_i32 s38, s69, s43
	v_lshl_add_u64 v[214:215], v[214:215], 0, s[12:13]
	s_mov_b32 m0, s38
	ds_read_b128 v[180:183], v150 offset:49152
	ds_read_b128 v[184:187], v150 offset:50176
	ds_read_b128 v[190:193], v150 offset:51200
	ds_read_b128 v[194:197], v150 offset:52224
	ds_read_b128 v[198:201], v150 offset:53248
	ds_read_b128 v[202:205], v150 offset:54272
	ds_read_b128 v[206:209], v150 offset:55296
	ds_read_b128 v[210:213], v150 offset:56320
	global_load_lds_dwordx4 v[214:215], off
	s_add_i32 m0, s38, 0x2000
	s_add_u32 s36, s36, 0x100080
	v_lshl_add_u64 v[214:215], v[216:217], 0, s[12:13]
	s_addc_u32 s37, s37, 0
	s_add_i32 s38, s70, s43
	global_load_lds_dwordx4 v[214:215], off
	v_lshl_add_u64 v[214:215], s[36:37], 0, v[132:133]
	s_mov_b32 m0, s38
	s_nop 0
	global_load_lds_dwordx4 v[214:215], off
	v_lshl_add_u64 v[214:215], s[36:37], 0, v[136:137]
	s_add_i32 m0, s38, 0x2000
	s_nop 0
	global_load_lds_dwordx4 v[214:215], off
	v_lshl_add_u64 v[214:215], v[218:219], 0, s[12:13]
	s_mov_b32 m0, s47
	s_nop 0
	global_load_lds_dwordx4 v[214:215], off
	v_lshl_add_u64 v[214:215], v[220:221], 0, s[12:13]
	s_mov_b32 m0, s52
	s_nop 0
	global_load_lds_dwordx4 v[214:215], off
	s_waitcnt vmcnt(8)
	s_waitcnt lgkmcnt(0)
	s_barrier
	v_mfma_f32_16x16x32_bf16 v[62:65], v[142:145], v[180:183], v[62:65]
	v_mfma_f32_16x16x32_bf16 v[58:61], v[156:159], v[180:183], v[58:61]
	v_mfma_f32_16x16x32_bf16 v[54:57], v[142:145], v[190:193], v[54:57]
	v_mfma_f32_16x16x32_bf16 v[46:49], v[156:159], v[190:193], v[46:49]
	v_mfma_f32_16x16x32_bf16 v[38:41], v[142:145], v[198:201], v[38:41]
	v_mfma_f32_16x16x32_bf16 v[30:33], v[156:159], v[198:201], v[30:33]
	v_mfma_f32_16x16x32_bf16 v[22:25], v[142:145], v[206:209], v[22:25]
	v_mfma_f32_16x16x32_bf16 v[14:17], v[156:159], v[206:209], v[14:17]
	v_mfma_f32_16x16x32_bf16 v[62:65], v[152:155], v[184:187], v[62:65]
	v_mfma_f32_16x16x32_bf16 v[58:61], v[160:163], v[184:187], v[58:61]
	v_mfma_f32_16x16x32_bf16 v[54:57], v[152:155], v[194:197], v[54:57]
	v_mfma_f32_16x16x32_bf16 v[46:49], v[160:163], v[194:197], v[46:49]
	v_mfma_f32_16x16x32_bf16 v[38:41], v[152:155], v[202:205], v[38:41]
	v_mfma_f32_16x16x32_bf16 v[30:33], v[160:163], v[202:205], v[30:33]
	v_mfma_f32_16x16x32_bf16 v[22:25], v[152:155], v[210:213], v[22:25]
	v_mfma_f32_16x16x32_bf16 v[14:17], v[160:163], v[210:213], v[14:17]
	v_mfma_f32_16x16x32_bf16 v[50:53], v[164:167], v[180:183], v[50:53]
	v_mfma_f32_16x16x32_bf16 v[42:45], v[172:175], v[180:183], v[42:45]
	v_mfma_f32_16x16x32_bf16 v[34:37], v[164:167], v[190:193], v[34:37]
	v_mfma_f32_16x16x32_bf16 v[26:29], v[172:175], v[190:193], v[26:29]
	v_mfma_f32_16x16x32_bf16 v[18:21], v[164:167], v[198:201], v[18:21]
	v_mfma_f32_16x16x32_bf16 v[10:13], v[172:175], v[198:201], v[10:13]
	v_mfma_f32_16x16x32_bf16 v[6:9], v[164:167], v[206:209], v[6:9]
	v_mfma_f32_16x16x32_bf16 v[2:5], v[172:175], v[206:209], v[2:5]
	v_mfma_f32_16x16x32_bf16 v[50:53], v[168:171], v[184:187], v[50:53]
	v_mfma_f32_16x16x32_bf16 v[42:45], v[176:179], v[184:187], v[42:45]
	v_mfma_f32_16x16x32_bf16 v[34:37], v[168:171], v[194:197], v[34:37]
	v_mfma_f32_16x16x32_bf16 v[26:29], v[176:179], v[194:197], v[26:29]
	v_mfma_f32_16x16x32_bf16 v[18:21], v[168:171], v[202:205], v[18:21]
	v_mfma_f32_16x16x32_bf16 v[10:13], v[176:179], v[202:205], v[10:13]
	v_mfma_f32_16x16x32_bf16 v[6:9], v[168:171], v[210:213], v[6:9]
	v_mfma_f32_16x16x32_bf16 v[2:5], v[176:179], v[210:213], v[2:5]
	s_add_i32 s68, s68, 2
	s_add_u32 s34, s34, 0x100
	s_addc_u32 s35, s35, 0
	s_add_u32 s66, s66, 0x100
	s_addc_u32 s67, s67, 0
	s_cmp_gt_u32 s68, 61
	s_barrier
	s_cbranch_scc0 .LBB0_102
	s_and_b64 vcc, exec, s[14:15]
	s_cbranch_vccz .LBB0_105
	s_barrier

; #define PG8_STAGE(bufoff, gbase, voff) do { _Pragma("unroll") for (int _i = 0; _i < 2; ++_i) \
;         __builtin_amdgcn_global_load_lds((const unsigned*)((const char*)(gbase) + (voff)[_i]), (PG8_LAS unsigned*)(lds + (bufoff) + ldsw + _i * 8192), 16, 0, 0); } while (0)
; #define PG8_LDA(dst, b, h) do { _Pragma("unroll") for (int m = 0; m < 4; ++m) _Pragma("unroll") for (int k = 0; k < 2; ++k) dst[m][k] = *(const PG8_LAS bf16x8*)(lds + PG8_SA(b, h) + aoff + m * 2048 + k * 1024); } while (0)
; #define PG8_LDB(dst, b, h) do { _Pragma("unroll") for (int n = 0; n < 2; ++n) _Pragma("unroll") for (int k = 0; k < 2; ++k) dst[n][k] = *(const PG8_LAS bf16x8*)(lds + PG8_SB(b, h) + boff + n * 2048 + k * 1024); } while (0)
; #define PG8_MMA(ai, bj, At, Bt) do { __builtin_amdgcn_s_setprio(1); _Pragma("unroll") for (int m = 0; m < 4; ++m) _Pragma("unroll") for (int n = 0; n < 2; ++n) _Pragma("unroll") for (int k = 0; k < 2; ++k) \
;         acc[ai][bj][m][n] = __builtin_amdgcn_mfma_f32_16x16x32_bf16(Bt[n][k], At[m][k], acc[ai][bj][m][n], 0, 0, 0); __builtin_amdgcn_s_setprio(0); } while (0)
; #define PG8_WAIT_V(n) asm volatile("s_waitcnt vmcnt(" #n ")" ::: "memory")
; #define PG8_WAIT_L(n) asm volatile("s_waitcnt lgkmcnt(" #n ")" ::: "memory")
; #define PG8_BAR __builtin_amdgcn_s_barrier()
; #define PG8_SCHED __builtin_amdgcn_sched_barrier(0)
; template <class Epi, class Sched, bool ALIGN_EPI = false, bool SP2 = false, bool A_TILED = false, bool B_TILED = false>
; __device__ __forceinline__ void gemm_phase(PG8_LAS unsigned char* lds, const Gemm g, const Sched& S, const Epi& E) {
;     ...
;             if constexpr (SP2) {
;             PG8_LDB(B0, 0, 0); PG8_LDB(B1, 0, 1); PG8_SCHED; PG8_LDA(At, 0, 0); PG8_STAGE(PG8_SA(1, 1), a1 + hstepA, voffA);
;             PG8_WAIT_V(8); PG8_WAIT_L(0); PG8_BAR; PG8_MMA(0, 0, At, B0); PG8_MMA(0, 1, At, B1); PG8_BAR; PG8_SCHED;
;             PG8_LDA(At, 0, 1); PG8_STAGE(PG8_SB(0, 0), b2, voffB); PG8_STAGE(PG8_SB(0, 1), b2 + hstepB, voffB); PG8_STAGE(PG8_SA(0, 0), a2, voffA);
;             PG8_WAIT_V(8); PG8_WAIT_L(0); PG8_BAR; PG8_MMA(1, 0, At, B0); PG8_MMA(1, 1, At, B1); PG8_BAR; PG8_SCHED;
.LBB0_513:
	v_add_u32_e32 v3, s62, v161
	s_waitcnt lgkmcnt(0)
	ds_read_b128 v[152:155], v3
	ds_read_b128 v[174:177], v3 offset:1024
	ds_read_b128 v[178:181], v3 offset:2048
	ds_read_b128 v[182:185], v3 offset:3072
	v_add_u32_e32 v3, s63, v161
	ds_read_b128 v[190:193], v3
	ds_read_b128 v[196:199], v3 offset:1024
	ds_read_b128 v[200:203], v3 offset:2048
	ds_read_b128 v[204:207], v3 offset:3072
	s_add_u32 s42, s12, 0xfff00080
	s_addc_u32 s43, s13, -1
	s_cmp_eq_u32 s68, 28
	s_cselect_b32 s45, s11, s43
	s_cselect_b32 s44, s35, s42
	s_cselect_b32 s43, s31, s67
	s_cselect_b32 s42, s37, s66
	v_lshl_add_u64 v[4:5], s[12:13], 0, v[144:145]
	s_add_i32 m0, s54, 0xc000
	ds_read_b128 v[208:211], v170
	ds_read_b128 v[212:215], v170 offset:1024
	ds_read_b128 v[216:219], v170 offset:2048
	ds_read_b128 v[220:223], v170 offset:3072
	ds_read_b128 v[224:227], v170 offset:4096
	ds_read_b128 v[228:231], v170 offset:5120
	ds_read_b128 v[232:235], v170 offset:6144
	ds_read_b128 v[236:239], v170 offset:7168
	global_load_lds_dwordx4 v[4:5], off
	v_lshl_add_u64 v[4:5], s[12:13], 0, v[146:147]
	s_add_i32 m0, s54, 0xe000
	s_nop 0
	global_load_lds_dwordx4 v[4:5], off
	s_waitcnt vmcnt(8)
	s_waitcnt lgkmcnt(0)
	s_barrier
	v_mfma_f32_16x16x32_bf16 v[130:133], v[152:155], v[208:211], v[130:133]
	v_mfma_f32_16x16x32_bf16 v[126:129], v[178:181], v[208:211], v[126:129]
	v_mfma_f32_16x16x32_bf16 v[122:125], v[152:155], v[216:219], v[122:125]
	v_mfma_f32_16x16x32_bf16 v[118:121], v[178:181], v[216:219], v[118:121]
	v_mfma_f32_16x16x32_bf16 v[114:117], v[152:155], v[224:227], v[114:117]
	v_mfma_f32_16x16x32_bf16 v[110:113], v[178:181], v[224:227], v[110:113]
	v_mfma_f32_16x16x32_bf16 v[106:109], v[152:155], v[232:235], v[106:109]
	v_mfma_f32_16x16x32_bf16 v[102:105], v[178:181], v[232:235], v[102:105]
	v_mfma_f32_16x16x32_bf16 v[130:133], v[174:177], v[212:215], v[130:133]
	v_mfma_f32_16x16x32_bf16 v[126:129], v[182:185], v[212:215], v[126:129]
	v_mfma_f32_16x16x32_bf16 v[122:125], v[174:177], v[220:223], v[122:125]
	v_mfma_f32_16x16x32_bf16 v[118:121], v[182:185], v[220:223], v[118:121]
	v_mfma_f32_16x16x32_bf16 v[114:117], v[174:177], v[228:231], v[114:117]
	v_mfma_f32_16x16x32_bf16 v[110:113], v[182:185], v[228:231], v[110:113]
	v_mfma_f32_16x16x32_bf16 v[106:109], v[174:177], v[236:239], v[106:109]
	v_mfma_f32_16x16x32_bf16 v[102:105], v[182:185], v[236:239], v[102:105]
	v_mfma_f32_16x16x32_bf16 v[98:101], v[190:193], v[208:211], v[98:101]
	v_mfma_f32_16x16x32_bf16 v[94:97], v[200:203], v[208:211], v[94:97]
	v_mfma_f32_16x16x32_bf16 v[90:93], v[190:193], v[216:219], v[90:93]
	v_mfma_f32_16x16x32_bf16 v[86:89], v[200:203], v[216:219], v[86:89]
	v_mfma_f32_16x16x32_bf16 v[82:85], v[190:193], v[224:227], v[82:85]
	v_mfma_f32_16x16x32_bf16 v[78:81], v[200:203], v[224:227], v[78:81]
	v_mfma_f32_16x16x32_bf16 v[74:77], v[190:193], v[232:235], v[74:77]
	v_mfma_f32_16x16x32_bf16 v[70:73], v[200:203], v[232:235], v[70:73]
	v_mfma_f32_16x16x32_bf16 v[98:101], v[196:199], v[212:215], v[98:101]
	v_mfma_f32_16x16x32_bf16 v[94:97], v[204:207], v[212:215], v[94:97]
	v_mfma_f32_16x16x32_bf16 v[90:93], v[196:199], v[220:223], v[90:93]
	v_mfma_f32_16x16x32_bf16 v[86:89], v[204:207], v[220:223], v[86:89]
	v_mfma_f32_16x16x32_bf16 v[82:85], v[196:199], v[228:231], v[82:85]
	v_mfma_f32_16x16x32_bf16 v[78:81], v[204:207], v[228:231], v[78:81]
	v_mfma_f32_16x16x32_bf16 v[74:77], v[196:199], v[236:239], v[74:77]
	v_mfma_f32_16x16x32_bf16 v[70:73], v[204:207], v[236:239], v[70:73]
	s_barrier
	s_add_i32 s69, s62, s53
	v_lshl_add_u64 v[186:187], s[42:43], 0, v[140:141]
	s_mov_b32 m0, s69
	ds_read_b128 v[208:211], v170 offset:16384
	ds_read_b128 v[212:215], v170 offset:17408
	ds_read_b128 v[216:219], v170 offset:18432
	ds_read_b128 v[220:223], v170 offset:19456
	ds_read_b128 v[224:227], v170 offset:20480
	ds_read_b128 v[228:231], v170 offset:21504
	ds_read_b128 v[232:235], v170 offset:22528
	ds_read_b128 v[236:239], v170 offset:23552
	global_load_lds_dwordx4 v[186:187], off
	s_add_i32 m0, s69, 0x2000
	s_add_u32 s70, s42, 0x100000
	v_lshl_add_u64 v[240:241], s[42:43], 0, v[142:143]
	s_addc_u32 s71, s43, 0
	s_add_i32 s69, s63, s53
	global_load_lds_dwordx4 v[240:241], off
	v_lshl_add_u64 v[4:5], s[70:71], 0, v[140:141]
	s_mov_b32 m0, s69
	v_lshl_add_u64 v[242:243], s[44:45], 0, v[134:135]
	global_load_lds_dwordx4 v[4:5], off
	v_lshl_add_u64 v[4:5], s[70:71], 0, v[142:143]
	s_add_i32 m0, s69, 0x2000
	v_lshl_add_u64 v[244:245], s[44:45], 0, v[136:137]
	global_load_lds_dwordx4 v[4:5], off
	s_mov_b32 m0, s54
	s_nop 0
	global_load_lds_dwordx4 v[242:243], off
	s_mov_b32 m0, s55
	s_nop 0
	global_load_lds_dwordx4 v[244:245], off
	s_waitcnt vmcnt(8)
	s_waitcnt lgkmcnt(0)
	s_barrier
; #define PG8_STAGE(bufoff, gbase, voff) do { _Pragma("unroll") for (int _i = 0; _i < 2; ++_i) \
;         __builtin_amdgcn_global_load_lds((const unsigned*)((const char*)(gbase) + (voff)[_i]), (PG8_LAS unsigned*)(lds + (bufoff) + ldsw + _i * 8192), 16, 0, 0); } while (0)
; #define PG8_LDA(dst, b, h) do { _Pragma("unroll") for (int m = 0; m < 4; ++m) _Pragma("unroll") for (int k = 0; k < 2; ++k) dst[m][k] = *(const PG8_LAS bf16x8*)(lds + PG8_SA(b, h) + aoff + m * 2048 + k * 1024); } while (0)
; #define PG8_LDB(dst, b, h) do { _Pragma("unroll") for (int n = 0; n < 2; ++n) _Pragma("unroll") for (int k = 0; k < 2; ++k) dst[n][k] = *(const PG8_LAS bf16x8*)(lds + PG8_SB(b, h) + boff + n * 2048 + k * 1024); } while (0)
; #define PG8_MMA(ai, bj, At, Bt) do { __builtin_amdgcn_s_setprio(1); _Pragma("unroll") for (int m = 0; m < 4; ++m) _Pragma("unroll") for (int n = 0; n < 2; ++n) _Pragma("unroll") for (int k = 0; k < 2; ++k) \
;         acc[ai][bj][m][n] = __builtin_amdgcn_mfma_f32_16x16x32_bf16(Bt[n][k], At[m][k], acc[ai][bj][m][n], 0, 0, 0); __builtin_amdgcn_s_setprio(0); } while (0)
; #define PG8_WAIT_V(n) asm volatile("s_waitcnt vmcnt(" #n ")" ::: "memory")
; #define PG8_WAIT_L(n) asm volatile("s_waitcnt lgkmcnt(" #n ")" ::: "memory")
; #define PG8_BAR __builtin_amdgcn_s_barrier()
; #define PG8_SCHED __builtin_amdgcn_sched_barrier(0)
; template <class Epi, class Sched, bool ALIGN_EPI = false, bool SP2 = false, bool A_TILED = false, bool B_TILED = false>
; __device__ __forceinline__ void gemm_phase(PG8_LAS unsigned char* lds, const Gemm g, const Sched& S, const Epi& E) {
;     ...
;             PG8_WAIT_V(8); PG8_WAIT_L(0); PG8_BAR; PG8_MMA(1, 0, At, B0); PG8_MMA(1, 1, At, B1); PG8_BAR; PG8_SCHED;
;             PG8_LDB(B0, 1, 0); PG8_LDB(B1, 1, 1); PG8_SCHED; PG8_LDA(At, 1, 0); PG8_STAGE(PG8_SA(0, 1), a2 + hstepA, voffA);
;             PG8_WAIT_V(8); PG8_WAIT_L(0); PG8_BAR; PG8_MMA(0, 0, At, B0); PG8_MMA(0, 1, At, B1); PG8_BAR; PG8_SCHED;
	v_mfma_f32_16x16x32_bf16 v[66:69], v[152:155], v[208:211], v[66:69]
	v_mfma_f32_16x16x32_bf16 v[62:65], v[178:181], v[208:211], v[62:65]
	v_mfma_f32_16x16x32_bf16 v[58:61], v[152:155], v[216:219], v[58:61]
	v_mfma_f32_16x16x32_bf16 v[54:57], v[178:181], v[216:219], v[54:57]
	v_mfma_f32_16x16x32_bf16 v[50:53], v[152:155], v[224:227], v[50:53]
	v_mfma_f32_16x16x32_bf16 v[46:49], v[178:181], v[224:227], v[46:49]
	v_mfma_f32_16x16x32_bf16 v[42:45], v[152:155], v[232:235], v[42:45]
	v_mfma_f32_16x16x32_bf16 v[38:41], v[178:181], v[232:235], v[38:41]
	v_mfma_f32_16x16x32_bf16 v[66:69], v[174:177], v[212:215], v[66:69]
	v_mfma_f32_16x16x32_bf16 v[62:65], v[182:185], v[212:215], v[62:65]
	v_mfma_f32_16x16x32_bf16 v[58:61], v[174:177], v[220:223], v[58:61]
	v_mfma_f32_16x16x32_bf16 v[54:57], v[182:185], v[220:223], v[54:57]
	v_mfma_f32_16x16x32_bf16 v[50:53], v[174:177], v[228:231], v[50:53]
	v_mfma_f32_16x16x32_bf16 v[46:49], v[182:185], v[228:231], v[46:49]
	v_mfma_f32_16x16x32_bf16 v[42:45], v[174:177], v[236:239], v[42:45]
	v_mfma_f32_16x16x32_bf16 v[38:41], v[182:185], v[236:239], v[38:41]
	v_mfma_f32_16x16x32_bf16 v[34:37], v[190:193], v[208:211], v[34:37]
	v_mfma_f32_16x16x32_bf16 v[30:33], v[200:203], v[208:211], v[30:33]
	v_mfma_f32_16x16x32_bf16 v[26:29], v[190:193], v[216:219], v[26:29]
	v_mfma_f32_16x16x32_bf16 v[22:25], v[200:203], v[216:219], v[22:25]
	v_mfma_f32_16x16x32_bf16 v[18:21], v[190:193], v[224:227], v[18:21]
	v_mfma_f32_16x16x32_bf16 v[14:17], v[200:203], v[224:227], v[14:17]
	v_mfma_f32_16x16x32_bf16 v[10:13], v[190:193], v[232:235], v[10:13]
	v_mfma_f32_16x16x32_bf16 v[4:7], v[200:203], v[232:235], v[6:9]
	v_mfma_f32_16x16x32_bf16 v[34:37], v[196:199], v[212:215], v[34:37]
	v_mfma_f32_16x16x32_bf16 v[30:33], v[204:207], v[212:215], v[30:33]
	v_mfma_f32_16x16x32_bf16 v[26:29], v[196:199], v[220:223], v[26:29]
	v_mfma_f32_16x16x32_bf16 v[22:25], v[204:207], v[220:223], v[22:25]
	v_mfma_f32_16x16x32_bf16 v[18:21], v[196:199], v[228:231], v[18:21]
	v_mfma_f32_16x16x32_bf16 v[14:17], v[204:207], v[228:231], v[14:17]
	v_mfma_f32_16x16x32_bf16 v[10:13], v[196:199], v[236:239], v[10:13]
	v_mfma_f32_16x16x32_bf16 v[4:7], v[204:207], v[236:239], v[4:7]
	s_barrier
	s_add_i32 s69, 0, 0x18000
	v_add_u32_e32 v3, s69, v161
	s_add_i32 s70, 0, 0x1c000
	ds_read_b128 v[152:155], v3
	ds_read_b128 v[174:177], v3 offset:1024
	ds_read_b128 v[178:181], v3 offset:2048
	ds_read_b128 v[182:185], v3 offset:3072
	v_add_u32_e32 v3, s70, v161
	ds_read_b128 v[190:193], v3
	ds_read_b128 v[196:199], v3 offset:1024
	ds_read_b128 v[200:203], v3 offset:2048
	ds_read_b128 v[204:207], v3 offset:3072
	s_add_u32 s44, s44, 0x100000
	s_addc_u32 s45, s45, 0
	s_mov_b32 m0, s56
	v_lshl_add_u64 v[8:9], s[44:45], 0, v[134:135]
	ds_read_b128 v[208:211], v170 offset:32768
	ds_read_b128 v[212:215], v170 offset:33792
	ds_read_b128 v[216:219], v170 offset:34816
	ds_read_b128 v[220:223], v170 offset:35840
	ds_read_b128 v[224:227], v170 offset:36864
	ds_read_b128 v[228:231], v170 offset:37888
	ds_read_b128 v[232:235], v170 offset:38912
	ds_read_b128 v[236:239], v170 offset:39936
	global_load_lds_dwordx4 v[8:9], off
	v_lshl_add_u64 v[8:9], s[44:45], 0, v[136:137]
	s_mov_b32 m0, s57
	s_nop 0
	global_load_lds_dwordx4 v[8:9], off
	s_waitcnt vmcnt(8)
	s_waitcnt lgkmcnt(0)
	s_barrier
	v_mfma_f32_16x16x32_bf16 v[130:133], v[152:155], v[208:211], v[130:133]
	v_mfma_f32_16x16x32_bf16 v[126:129], v[178:181], v[208:211], v[126:129]
	v_mfma_f32_16x16x32_bf16 v[122:125], v[152:155], v[216:219], v[122:125]
	v_mfma_f32_16x16x32_bf16 v[118:121], v[178:181], v[216:219], v[118:121]
	v_mfma_f32_16x16x32_bf16 v[114:117], v[152:155], v[224:227], v[114:117]
	v_mfma_f32_16x16x32_bf16 v[110:113], v[178:181], v[224:227], v[110:113]
	v_mfma_f32_16x16x32_bf16 v[106:109], v[152:155], v[232:235], v[106:109]
	v_mfma_f32_16x16x32_bf16 v[102:105], v[178:181], v[232:235], v[102:105]
	v_mfma_f32_16x16x32_bf16 v[130:133], v[174:177], v[212:215], v[130:133]
	v_mfma_f32_16x16x32_bf16 v[126:129], v[182:185], v[212:215], v[126:129]
	v_mfma_f32_16x16x32_bf16 v[122:125], v[174:177], v[220:223], v[122:125]
	v_mfma_f32_16x16x32_bf16 v[118:121], v[182:185], v[220:223], v[118:121]
	v_mfma_f32_16x16x32_bf16 v[114:117], v[174:177], v[228:231], v[114:117]
	v_mfma_f32_16x16x32_bf16 v[110:113], v[182:185], v[228:231], v[110:113]
	v_mfma_f32_16x16x32_bf16 v[106:109], v[174:177], v[236:239], v[106:109]
	v_mfma_f32_16x16x32_bf16 v[102:105], v[182:185], v[236:239], v[102:105]
	v_mfma_f32_16x16x32_bf16 v[98:101], v[190:193], v[208:211], v[98:101]
	v_mfma_f32_16x16x32_bf16 v[94:97], v[200:203], v[208:211], v[94:97]
	v_mfma_f32_16x16x32_bf16 v[90:93], v[190:193], v[216:219], v[90:93]
	v_mfma_f32_16x16x32_bf16 v[86:89], v[200:203], v[216:219], v[86:89]
	v_mfma_f32_16x16x32_bf16 v[82:85], v[190:193], v[224:227], v[82:85]
	v_mfma_f32_16x16x32_bf16 v[78:81], v[200:203], v[224:227], v[78:81]
	v_mfma_f32_16x16x32_bf16 v[74:77], v[190:193], v[232:235], v[74:77]
	v_mfma_f32_16x16x32_bf16 v[70:73], v[200:203], v[232:235], v[70:73]
	v_mfma_f32_16x16x32_bf16 v[98:101], v[196:199], v[212:215], v[98:101]
	v_mfma_f32_16x16x32_bf16 v[94:97], v[204:207], v[212:215], v[94:97]
	v_mfma_f32_16x16x32_bf16 v[90:93], v[196:199], v[220:223], v[90:93]
	v_mfma_f32_16x16x32_bf16 v[86:89], v[204:207], v[220:223], v[86:89]
	v_mfma_f32_16x16x32_bf16 v[82:85], v[196:199], v[228:231], v[82:85]
	v_mfma_f32_16x16x32_bf16 v[78:81], v[204:207], v[228:231], v[78:81]
	v_mfma_f32_16x16x32_bf16 v[74:77], v[196:199], v[236:239], v[74:77]
	v_mfma_f32_16x16x32_bf16 v[70:73], v[204:207], v[236:239], v[70:73]
	s_barrier
; #define PG8_STAGE(bufoff, gbase, voff) do { _Pragma("unroll") for (int _i = 0; _i < 2; ++_i) \
;         __builtin_amdgcn_global_load_lds((const unsigned*)((const char*)(gbase) + (voff)[_i]), (PG8_LAS unsigned*)(lds + (bufoff) + ldsw + _i * 8192), 16, 0, 0); } while (0)
; #define PG8_LDA(dst, b, h) do { _Pragma("unroll") for (int m = 0; m < 4; ++m) _Pragma("unroll") for (int k = 0; k < 2; ++k) dst[m][k] = *(const PG8_LAS bf16x8*)(lds + PG8_SA(b, h) + aoff + m * 2048 + k * 1024); } while (0)
; #define PG8_MMA(ai, bj, At, Bt) do { __builtin_amdgcn_s_setprio(1); _Pragma("unroll") for (int m = 0; m < 4; ++m) _Pragma("unroll") for (int n = 0; n < 2; ++n) _Pragma("unroll") for (int k = 0; k < 2; ++k) \
;         acc[ai][bj][m][n] = __builtin_amdgcn_mfma_f32_16x16x32_bf16(Bt[n][k], At[m][k], acc[ai][bj][m][n], 0, 0, 0); __builtin_amdgcn_s_setprio(0); } while (0)
; #define PG8_WAIT_V(n) asm volatile("s_waitcnt vmcnt(" #n ")" ::: "memory")
; #define PG8_WAIT_L(n) asm volatile("s_waitcnt lgkmcnt(" #n ")" ::: "memory")
; #define PG8_BAR __builtin_amdgcn_s_barrier()
; #define PG8_SCHED __builtin_amdgcn_sched_barrier(0)
; template <class Epi, class Sched, bool ALIGN_EPI = false, bool SP2 = false, bool A_TILED = false, bool B_TILED = false>
; __device__ __forceinline__ void gemm_phase(PG8_LAS unsigned char* lds, const Gemm g, const Sched& S, const Epi& E) {
;     ...
;         for (int t = 0; t < nt; t += 2) {
;             const bool last = (t == nt - 2);
;     ...
;             PG8_LDA(At, 1, 1); PG8_STAGE(PG8_SB(1, 0), b3, voffB); PG8_STAGE(PG8_SB(1, 1), b3 + hstepB, voffB); PG8_STAGE(PG8_SA(1, 0), a3, voffA);
;             PG8_WAIT_V(8); PG8_WAIT_L(0); PG8_BAR; PG8_MMA(1, 0, At, B0); PG8_MMA(1, 1, At, B1); PG8_BAR; PG8_SCHED;
	s_add_i32 s44, s69, s53
	v_lshl_add_u64 v[8:9], v[186:187], 0, s[26:27]
	s_mov_b32 m0, s44
	ds_read_b128 v[208:211], v170 offset:49152
	ds_read_b128 v[212:215], v170 offset:50176
	ds_read_b128 v[216:219], v170 offset:51200
	ds_read_b128 v[220:223], v170 offset:52224
	ds_read_b128 v[224:227], v170 offset:53248
	ds_read_b128 v[228:231], v170 offset:54272
	ds_read_b128 v[232:235], v170 offset:55296
	ds_read_b128 v[236:239], v170 offset:56320
	global_load_lds_dwordx4 v[8:9], off
	s_add_i32 m0, s44, 0x2000
	s_add_u32 s42, s42, 0x100080
	v_lshl_add_u64 v[8:9], v[240:241], 0, s[26:27]
	s_addc_u32 s43, s43, 0
	s_add_i32 s44, s70, s53
	global_load_lds_dwordx4 v[8:9], off
	v_lshl_add_u64 v[8:9], s[42:43], 0, v[140:141]
	s_mov_b32 m0, s44
	s_nop 0
	global_load_lds_dwordx4 v[8:9], off
	v_lshl_add_u64 v[8:9], s[42:43], 0, v[142:143]
	s_add_i32 m0, s44, 0x2000
	s_nop 0
	global_load_lds_dwordx4 v[8:9], off
	v_lshl_add_u64 v[8:9], v[242:243], 0, s[26:27]
	s_mov_b32 m0, s59
	s_nop 0
	global_load_lds_dwordx4 v[8:9], off
	v_lshl_add_u64 v[8:9], v[244:245], 0, s[26:27]
	s_mov_b32 m0, s60
	s_nop 0
	global_load_lds_dwordx4 v[8:9], off
	s_waitcnt vmcnt(8)
	s_waitcnt lgkmcnt(0)
	s_barrier
	v_mfma_f32_16x16x32_bf16 v[66:69], v[152:155], v[208:211], v[66:69]
	v_mfma_f32_16x16x32_bf16 v[62:65], v[178:181], v[208:211], v[62:65]
	v_mfma_f32_16x16x32_bf16 v[58:61], v[152:155], v[216:219], v[58:61]
	v_mfma_f32_16x16x32_bf16 v[54:57], v[178:181], v[216:219], v[54:57]
	v_mfma_f32_16x16x32_bf16 v[50:53], v[152:155], v[224:227], v[50:53]
	v_mfma_f32_16x16x32_bf16 v[46:49], v[178:181], v[224:227], v[46:49]
	v_mfma_f32_16x16x32_bf16 v[42:45], v[152:155], v[232:235], v[42:45]
	v_mfma_f32_16x16x32_bf16 v[38:41], v[178:181], v[232:235], v[38:41]
	v_mfma_f32_16x16x32_bf16 v[66:69], v[174:177], v[212:215], v[66:69]
	v_mfma_f32_16x16x32_bf16 v[62:65], v[182:185], v[212:215], v[62:65]
	v_mfma_f32_16x16x32_bf16 v[58:61], v[174:177], v[220:223], v[58:61]
	v_mfma_f32_16x16x32_bf16 v[54:57], v[182:185], v[220:223], v[54:57]
	v_mfma_f32_16x16x32_bf16 v[50:53], v[174:177], v[228:231], v[50:53]
	v_mfma_f32_16x16x32_bf16 v[46:49], v[182:185], v[228:231], v[46:49]
	v_mfma_f32_16x16x32_bf16 v[42:45], v[174:177], v[236:239], v[42:45]
	v_mfma_f32_16x16x32_bf16 v[38:41], v[182:185], v[236:239], v[38:41]
	v_mfma_f32_16x16x32_bf16 v[34:37], v[190:193], v[208:211], v[34:37]
	v_mfma_f32_16x16x32_bf16 v[30:33], v[200:203], v[208:211], v[30:33]
	v_mfma_f32_16x16x32_bf16 v[26:29], v[190:193], v[216:219], v[26:29]
	v_mfma_f32_16x16x32_bf16 v[22:25], v[200:203], v[216:219], v[22:25]
	v_mfma_f32_16x16x32_bf16 v[18:21], v[190:193], v[224:227], v[18:21]
	v_mfma_f32_16x16x32_bf16 v[14:17], v[200:203], v[224:227], v[14:17]
	v_mfma_f32_16x16x32_bf16 v[8:11], v[190:193], v[232:235], v[10:13]
	v_mfma_f32_16x16x32_bf16 v[4:7], v[200:203], v[232:235], v[4:7]
	v_mfma_f32_16x16x32_bf16 v[34:37], v[196:199], v[212:215], v[34:37]
	v_mfma_f32_16x16x32_bf16 v[30:33], v[204:207], v[212:215], v[30:33]
	v_mfma_f32_16x16x32_bf16 v[26:29], v[196:199], v[220:223], v[26:29]
	v_mfma_f32_16x16x32_bf16 v[22:25], v[204:207], v[220:223], v[22:25]
	v_mfma_f32_16x16x32_bf16 v[18:21], v[196:199], v[228:231], v[18:21]
	v_mfma_f32_16x16x32_bf16 v[14:17], v[204:207], v[228:231], v[14:17]
	v_mfma_f32_16x16x32_bf16 v[10:13], v[196:199], v[236:239], v[8:11]
	v_mfma_f32_16x16x32_bf16 v[6:9], v[204:207], v[236:239], v[4:7]
	s_add_i32 s68, s68, 2
	s_add_u32 s12, s12, 0x100
	s_addc_u32 s13, s13, 0
	s_add_u32 s66, s66, 0x100
	s_addc_u32 s67, s67, 0
	s_cmp_gt_u32 s68, 29
	s_barrier
	s_cbranch_scc0 .LBB0_513
	s_and_b64 vcc, exec, s[28:29]
	s_cbranch_vccz .LBB0_516
	s_barrier

; #define PG8_STAGE(bufoff, gbase, voff) do { _Pragma("unroll") for (int _i = 0; _i < 2; ++_i) \
;         __builtin_amdgcn_global_load_lds((const unsigned*)((const char*)(gbase) + (voff)[_i]), (PG8_LAS unsigned*)(lds + (bufoff) + ldsw + _i * 8192), 16, 0, 0); } while (0)
; #define PG8_LDA(dst, b, h) do { _Pragma("unroll") for (int m = 0; m < 4; ++m) _Pragma("unroll") for (int k = 0; k < 2; ++k) dst[m][k] = *(const PG8_LAS bf16x8*)(lds + PG8_SA(b, h) + aoff + m * 2048 + k * 1024); } while (0)
; #define PG8_LDB(dst, b, h) do { _Pragma("unroll") for (int n = 0; n < 2; ++n) _Pragma("unroll") for (int k = 0; k < 2; ++k) dst[n][k] = *(const PG8_LAS bf16x8*)(lds + PG8_SB(b, h) + boff + n * 2048 + k * 1024); } while (0)
; #define PG8_MMA(ai, bj, At, Bt) do { __builtin_amdgcn_s_setprio(1); _Pragma("unroll") for (int m = 0; m < 4; ++m) _Pragma("unroll") for (int n = 0; n < 2; ++n) _Pragma("unroll") for (int k = 0; k < 2; ++k) \
;         acc[ai][bj][m][n] = __builtin_amdgcn_mfma_f32_16x16x32_bf16(Bt[n][k], At[m][k], acc[ai][bj][m][n], 0, 0, 0); __builtin_amdgcn_s_setprio(0); } while (0)
; #define PG8_WAIT_V(n) asm volatile("s_waitcnt vmcnt(" #n ")" ::: "memory")
; #define PG8_WAIT_L(n) asm volatile("s_waitcnt lgkmcnt(" #n ")" ::: "memory")
; #define PG8_BAR __builtin_amdgcn_s_barrier()
; #define PG8_SCHED __builtin_amdgcn_sched_barrier(0)
; template <class Epi, class Sched, bool ALIGN_EPI = false, bool SP2 = false, bool A_TILED = false, bool B_TILED = false>
; __device__ __forceinline__ void gemm_phase(PG8_LAS unsigned char* lds, const Gemm g, const Sched& S, const Epi& E) {
;     ...
;             const char* a1 = cA + (size_t)(t + 1) * kstepA;
;             const char* a2 = last ? nA : cA + (size_t)(t + 2) * kstepA; const char* b2 = last ? nB : cB + (size_t)(t + 2) * kstepB;
;             const char* a3 = a2 + kstepA; const char* b3 = b2 + kstepB;
;             if (last && has_next) S.a_ready(nxt);
;             if constexpr (SP2) {
;             PG8_LDB(B0, 0, 0); PG8_LDB(B1, 0, 1); PG8_SCHED; PG8_LDA(At, 0, 0); PG8_STAGE(PG8_SA(1, 1), a1 + hstepA, voffA);
;             PG8_WAIT_V(8); PG8_WAIT_L(0); PG8_BAR; PG8_MMA(0, 0, At, B0); PG8_MMA(0, 1, At, B1); PG8_BAR; PG8_SCHED;
;             PG8_LDA(At, 0, 1); PG8_STAGE(PG8_SB(0, 0), b2, voffB); PG8_STAGE(PG8_SB(0, 1), b2 + hstepB, voffB); PG8_STAGE(PG8_SA(0, 0), a2, voffA);
.LBB0_553:
	ds_read_b128 v[158:161], v1
	ds_read_b128 v[162:165], v1 offset:1024
	ds_read_b128 v[166:169], v1 offset:2048
	ds_read_b128 v[170:173], v1 offset:3072
	ds_read_b128 v[174:177], v153
	ds_read_b128 v[178:181], v153 offset:1024
	ds_read_b128 v[182:185], v153 offset:2048
	ds_read_b128 v[190:193], v153 offset:3072
	s_add_u32 s38, s36, 0xfff00080
	s_addc_u32 s39, s37, -1
	s_cmp_eq_u32 s59, 12
	s_cselect_b32 s41, s5, s39
	s_cselect_b32 s40, s7, s38
	s_cselect_b32 s39, s23, s58
	s_cselect_b32 s38, s25, s27
	v_lshl_add_u64 v[140:141], s[36:37], 0, v[132:133]
	s_add_i32 m0, s19, 0xc000
	ds_read_b128 v[196:199], v154
	ds_read_b128 v[200:203], v154 offset:1024
	ds_read_b128 v[204:207], v154 offset:2048
	ds_read_b128 v[208:211], v154 offset:3072
	ds_read_b128 v[212:215], v154 offset:4096
	ds_read_b128 v[216:219], v154 offset:5120
	ds_read_b128 v[220:223], v154 offset:6144
	ds_read_b128 v[224:227], v154 offset:7168
	global_load_lds_dwordx4 v[140:141], off
	v_lshl_add_u64 v[140:141], s[36:37], 0, v[138:139]
	s_add_i32 m0, s19, 0xe000
	s_nop 0
	global_load_lds_dwordx4 v[140:141], off
	s_waitcnt vmcnt(8)
	s_waitcnt lgkmcnt(0)
	s_barrier
	v_mfma_f32_16x16x32_bf16 v[126:129], v[158:161], v[196:199], v[126:129]
	v_mfma_f32_16x16x32_bf16 v[122:125], v[166:169], v[196:199], v[122:125]
	v_mfma_f32_16x16x32_bf16 v[110:113], v[158:161], v[204:207], v[110:113]
	v_mfma_f32_16x16x32_bf16 v[106:109], v[166:169], v[204:207], v[106:109]
	v_mfma_f32_16x16x32_bf16 v[94:97], v[158:161], v[212:215], v[94:97]
	v_mfma_f32_16x16x32_bf16 v[90:93], v[166:169], v[212:215], v[90:93]
	v_mfma_f32_16x16x32_bf16 v[78:81], v[158:161], v[220:223], v[78:81]
	v_mfma_f32_16x16x32_bf16 v[74:77], v[166:169], v[220:223], v[74:77]
	v_mfma_f32_16x16x32_bf16 v[126:129], v[162:165], v[200:203], v[126:129]
	v_mfma_f32_16x16x32_bf16 v[122:125], v[170:173], v[200:203], v[122:125]
	v_mfma_f32_16x16x32_bf16 v[110:113], v[162:165], v[208:211], v[110:113]
	v_mfma_f32_16x16x32_bf16 v[106:109], v[170:173], v[208:211], v[106:109]
	v_mfma_f32_16x16x32_bf16 v[94:97], v[162:165], v[216:219], v[94:97]
	v_mfma_f32_16x16x32_bf16 v[90:93], v[170:173], v[216:219], v[90:93]
	v_mfma_f32_16x16x32_bf16 v[78:81], v[162:165], v[224:227], v[78:81]
	v_mfma_f32_16x16x32_bf16 v[74:77], v[170:173], v[224:227], v[74:77]
	v_mfma_f32_16x16x32_bf16 v[118:121], v[174:177], v[196:199], v[118:121]
	v_mfma_f32_16x16x32_bf16 v[114:117], v[182:185], v[196:199], v[114:117]
	v_mfma_f32_16x16x32_bf16 v[102:105], v[174:177], v[204:207], v[102:105]
	v_mfma_f32_16x16x32_bf16 v[98:101], v[182:185], v[204:207], v[98:101]
	v_mfma_f32_16x16x32_bf16 v[86:89], v[174:177], v[212:215], v[86:89]
	v_mfma_f32_16x16x32_bf16 v[82:85], v[182:185], v[212:215], v[82:85]
	v_mfma_f32_16x16x32_bf16 v[70:73], v[174:177], v[220:223], v[70:73]
	v_mfma_f32_16x16x32_bf16 v[66:69], v[182:185], v[220:223], v[66:69]
	v_mfma_f32_16x16x32_bf16 v[118:121], v[178:181], v[200:203], v[118:121]
	v_mfma_f32_16x16x32_bf16 v[114:117], v[190:193], v[200:203], v[114:117]
	v_mfma_f32_16x16x32_bf16 v[102:105], v[178:181], v[208:211], v[102:105]
	v_mfma_f32_16x16x32_bf16 v[98:101], v[190:193], v[208:211], v[98:101]
	v_mfma_f32_16x16x32_bf16 v[86:89], v[178:181], v[216:219], v[86:89]
	v_mfma_f32_16x16x32_bf16 v[82:85], v[190:193], v[216:219], v[82:85]
	v_mfma_f32_16x16x32_bf16 v[70:73], v[178:181], v[224:227], v[70:73]
	v_mfma_f32_16x16x32_bf16 v[66:69], v[190:193], v[224:227], v[66:69]
	s_barrier
	s_add_i32 s60, s8, s42
	v_lshl_add_u64 v[140:141], s[38:39], 0, v[134:135]
	s_mov_b32 m0, s60
	ds_read_b128 v[196:199], v154 offset:16384
	ds_read_b128 v[200:203], v154 offset:17408
	ds_read_b128 v[204:207], v154 offset:18432
	ds_read_b128 v[208:211], v154 offset:19456
	ds_read_b128 v[212:215], v154 offset:20480
	ds_read_b128 v[216:219], v154 offset:21504
	ds_read_b128 v[220:223], v154 offset:22528
	ds_read_b128 v[224:227], v154 offset:23552
	global_load_lds_dwordx4 v[140:141], off
	s_add_i32 m0, s60, 0x2000
	s_add_u32 s60, s38, 0x100000
	v_lshl_add_u64 v[186:187], s[38:39], 0, v[136:137]
	s_addc_u32 s61, s39, 0
	s_add_i32 s62, s55, s42
	global_load_lds_dwordx4 v[186:187], off
	v_lshl_add_u64 v[228:229], s[60:61], 0, v[134:135]
	s_mov_b32 m0, s62
	v_lshl_add_u64 v[230:231], s[40:41], 0, v[136:137]
	global_load_lds_dwordx4 v[228:229], off
	v_lshl_add_u64 v[228:229], s[60:61], 0, v[136:137]
	s_add_i32 m0, s62, 0x2000
	s_nop 0
	global_load_lds_dwordx4 v[228:229], off
	v_lshl_add_u64 v[228:229], s[40:41], 0, v[134:135]
	s_mov_b32 m0, s19
	s_nop 0
	global_load_lds_dwordx4 v[228:229], off
	s_mov_b32 m0, s43
	s_nop 0
	global_load_lds_dwordx4 v[230:231], off
	s_waitcnt vmcnt(8)
	s_waitcnt lgkmcnt(0)
	s_barrier
; #define PG8_STAGE(bufoff, gbase, voff) do { _Pragma("unroll") for (int _i = 0; _i < 2; ++_i) \
;         __builtin_amdgcn_global_load_lds((const unsigned*)((const char*)(gbase) + (voff)[_i]), (PG8_LAS unsigned*)(lds + (bufoff) + ldsw + _i * 8192), 16, 0, 0); } while (0)
; #define PG8_LDA(dst, b, h) do { _Pragma("unroll") for (int m = 0; m < 4; ++m) _Pragma("unroll") for (int k = 0; k < 2; ++k) dst[m][k] = *(const PG8_LAS bf16x8*)(lds + PG8_SA(b, h) + aoff + m * 2048 + k * 1024); } while (0)
; #define PG8_LDB(dst, b, h) do { _Pragma("unroll") for (int n = 0; n < 2; ++n) _Pragma("unroll") for (int k = 0; k < 2; ++k) dst[n][k] = *(const PG8_LAS bf16x8*)(lds + PG8_SB(b, h) + boff + n * 2048 + k * 1024); } while (0)
; #define PG8_MMA(ai, bj, At, Bt) do { __builtin_amdgcn_s_setprio(1); _Pragma("unroll") for (int m = 0; m < 4; ++m) _Pragma("unroll") for (int n = 0; n < 2; ++n) _Pragma("unroll") for (int k = 0; k < 2; ++k) \
;         acc[ai][bj][m][n] = __builtin_amdgcn_mfma_f32_16x16x32_bf16(Bt[n][k], At[m][k], acc[ai][bj][m][n], 0, 0, 0); __builtin_amdgcn_s_setprio(0); } while (0)
; #define PG8_WAIT_V(n) asm volatile("s_waitcnt vmcnt(" #n ")" ::: "memory")
; #define PG8_WAIT_L(n) asm volatile("s_waitcnt lgkmcnt(" #n ")" ::: "memory")
; #define PG8_BAR __builtin_amdgcn_s_barrier()
; #define PG8_SCHED __builtin_amdgcn_sched_barrier(0)
; template <class Epi, class Sched, bool ALIGN_EPI = false, bool SP2 = false, bool A_TILED = false, bool B_TILED = false>
; __device__ __forceinline__ void gemm_phase(PG8_LAS unsigned char* lds, const Gemm g, const Sched& S, const Epi& E) {
;     ...
;             PG8_WAIT_V(8); PG8_WAIT_L(0); PG8_BAR; PG8_MMA(1, 0, At, B0); PG8_MMA(1, 1, At, B1); PG8_BAR; PG8_SCHED;
;             PG8_LDB(B0, 1, 0); PG8_LDB(B1, 1, 1); PG8_SCHED; PG8_LDA(At, 1, 0); PG8_STAGE(PG8_SA(0, 1), a2 + hstepA, voffA);
;             PG8_WAIT_V(8); PG8_WAIT_L(0); PG8_BAR; PG8_MMA(0, 0, At, B0); PG8_MMA(0, 1, At, B1); PG8_BAR; PG8_SCHED;
	v_mfma_f32_16x16x32_bf16 v[62:65], v[158:161], v[196:199], v[62:65]
	v_mfma_f32_16x16x32_bf16 v[58:61], v[166:169], v[196:199], v[58:61]
	v_mfma_f32_16x16x32_bf16 v[46:49], v[158:161], v[204:207], v[46:49]
	v_mfma_f32_16x16x32_bf16 v[42:45], v[166:169], v[204:207], v[42:45]
	v_mfma_f32_16x16x32_bf16 v[30:33], v[158:161], v[212:215], v[30:33]
	v_mfma_f32_16x16x32_bf16 v[26:29], v[166:169], v[212:215], v[26:29]
	v_mfma_f32_16x16x32_bf16 v[14:17], v[158:161], v[220:223], v[14:17]
	v_mfma_f32_16x16x32_bf16 v[10:13], v[166:169], v[220:223], v[10:13]
	v_mfma_f32_16x16x32_bf16 v[62:65], v[162:165], v[200:203], v[62:65]
	v_mfma_f32_16x16x32_bf16 v[58:61], v[170:173], v[200:203], v[58:61]
	v_mfma_f32_16x16x32_bf16 v[46:49], v[162:165], v[208:211], v[46:49]
	v_mfma_f32_16x16x32_bf16 v[42:45], v[170:173], v[208:211], v[42:45]
	v_mfma_f32_16x16x32_bf16 v[30:33], v[162:165], v[216:219], v[30:33]
	v_mfma_f32_16x16x32_bf16 v[26:29], v[170:173], v[216:219], v[26:29]
	v_mfma_f32_16x16x32_bf16 v[14:17], v[162:165], v[224:227], v[14:17]
	v_mfma_f32_16x16x32_bf16 v[10:13], v[170:173], v[224:227], v[10:13]
	v_mfma_f32_16x16x32_bf16 v[54:57], v[174:177], v[196:199], v[54:57]
	v_mfma_f32_16x16x32_bf16 v[50:53], v[182:185], v[196:199], v[50:53]
	v_mfma_f32_16x16x32_bf16 v[38:41], v[174:177], v[204:207], v[38:41]
	v_mfma_f32_16x16x32_bf16 v[34:37], v[182:185], v[204:207], v[34:37]
	v_mfma_f32_16x16x32_bf16 v[22:25], v[174:177], v[212:215], v[22:25]
	v_mfma_f32_16x16x32_bf16 v[18:21], v[182:185], v[212:215], v[18:21]
	v_mfma_f32_16x16x32_bf16 v[6:9], v[174:177], v[220:223], v[6:9]
	v_mfma_f32_16x16x32_bf16 v[2:5], v[182:185], v[220:223], v[2:5]
	v_mfma_f32_16x16x32_bf16 v[54:57], v[178:181], v[200:203], v[54:57]
	v_mfma_f32_16x16x32_bf16 v[50:53], v[190:193], v[200:203], v[50:53]
	v_mfma_f32_16x16x32_bf16 v[38:41], v[178:181], v[208:211], v[38:41]
	v_mfma_f32_16x16x32_bf16 v[34:37], v[190:193], v[208:211], v[34:37]
	v_mfma_f32_16x16x32_bf16 v[22:25], v[178:181], v[216:219], v[22:25]
	v_mfma_f32_16x16x32_bf16 v[18:21], v[190:193], v[216:219], v[18:21]
	v_mfma_f32_16x16x32_bf16 v[6:9], v[178:181], v[224:227], v[6:9]
	v_mfma_f32_16x16x32_bf16 v[2:5], v[190:193], v[224:227], v[2:5]
	s_barrier
	s_add_i32 s60, 0, 0x18000
	v_add_u32_e32 v142, s60, v145
	s_add_i32 s61, 0, 0x1c000
	ds_read_b128 v[158:161], v142
	ds_read_b128 v[162:165], v142 offset:1024
	ds_read_b128 v[166:169], v142 offset:2048
	ds_read_b128 v[170:173], v142 offset:3072
	v_add_u32_e32 v142, s61, v145
	ds_read_b128 v[174:177], v142
	ds_read_b128 v[178:181], v142 offset:1024
	ds_read_b128 v[182:185], v142 offset:2048
	ds_read_b128 v[190:193], v142 offset:3072
	s_add_u32 s40, s40, 0x100000
	s_addc_u32 s41, s41, 0
	s_mov_b32 m0, s44
	v_lshl_add_u64 v[232:233], s[40:41], 0, v[134:135]
	ds_read_b128 v[196:199], v154 offset:32768
	ds_read_b128 v[200:203], v154 offset:33792
	ds_read_b128 v[204:207], v154 offset:34816
	ds_read_b128 v[208:211], v154 offset:35840
	ds_read_b128 v[212:215], v154 offset:36864
	ds_read_b128 v[216:219], v154 offset:37888
	ds_read_b128 v[220:223], v154 offset:38912
	ds_read_b128 v[224:227], v154 offset:39936
	global_load_lds_dwordx4 v[232:233], off
	v_lshl_add_u64 v[232:233], s[40:41], 0, v[136:137]
	s_mov_b32 m0, s45
	s_nop 0
	global_load_lds_dwordx4 v[232:233], off
	s_waitcnt vmcnt(8)
	s_waitcnt lgkmcnt(0)
	s_barrier
	v_mfma_f32_16x16x32_bf16 v[126:129], v[158:161], v[196:199], v[126:129]
	v_mfma_f32_16x16x32_bf16 v[122:125], v[166:169], v[196:199], v[122:125]
	v_mfma_f32_16x16x32_bf16 v[110:113], v[158:161], v[204:207], v[110:113]
	v_mfma_f32_16x16x32_bf16 v[106:109], v[166:169], v[204:207], v[106:109]
	v_mfma_f32_16x16x32_bf16 v[94:97], v[158:161], v[212:215], v[94:97]
	v_mfma_f32_16x16x32_bf16 v[90:93], v[166:169], v[212:215], v[90:93]
	v_mfma_f32_16x16x32_bf16 v[78:81], v[158:161], v[220:223], v[78:81]
	v_mfma_f32_16x16x32_bf16 v[74:77], v[166:169], v[220:223], v[74:77]
	v_mfma_f32_16x16x32_bf16 v[126:129], v[162:165], v[200:203], v[126:129]
	v_mfma_f32_16x16x32_bf16 v[122:125], v[170:173], v[200:203], v[122:125]
	v_mfma_f32_16x16x32_bf16 v[110:113], v[162:165], v[208:211], v[110:113]
	v_mfma_f32_16x16x32_bf16 v[106:109], v[170:173], v[208:211], v[106:109]
	v_mfma_f32_16x16x32_bf16 v[94:97], v[162:165], v[216:219], v[94:97]
	v_mfma_f32_16x16x32_bf16 v[90:93], v[170:173], v[216:219], v[90:93]
	v_mfma_f32_16x16x32_bf16 v[78:81], v[162:165], v[224:227], v[78:81]
	v_mfma_f32_16x16x32_bf16 v[74:77], v[170:173], v[224:227], v[74:77]
	v_mfma_f32_16x16x32_bf16 v[118:121], v[174:177], v[196:199], v[118:121]
	v_mfma_f32_16x16x32_bf16 v[114:117], v[182:185], v[196:199], v[114:117]
	v_mfma_f32_16x16x32_bf16 v[102:105], v[174:177], v[204:207], v[102:105]
	v_mfma_f32_16x16x32_bf16 v[98:101], v[182:185], v[204:207], v[98:101]
	v_mfma_f32_16x16x32_bf16 v[86:89], v[174:177], v[212:215], v[86:89]
	v_mfma_f32_16x16x32_bf16 v[82:85], v[182:185], v[212:215], v[82:85]
	v_mfma_f32_16x16x32_bf16 v[70:73], v[174:177], v[220:223], v[70:73]
	v_mfma_f32_16x16x32_bf16 v[66:69], v[182:185], v[220:223], v[66:69]
	v_mfma_f32_16x16x32_bf16 v[118:121], v[178:181], v[200:203], v[118:121]
	v_mfma_f32_16x16x32_bf16 v[114:117], v[190:193], v[200:203], v[114:117]
	v_mfma_f32_16x16x32_bf16 v[102:105], v[178:181], v[208:211], v[102:105]
	v_mfma_f32_16x16x32_bf16 v[98:101], v[190:193], v[208:211], v[98:101]
	v_mfma_f32_16x16x32_bf16 v[86:89], v[178:181], v[216:219], v[86:89]
	v_mfma_f32_16x16x32_bf16 v[82:85], v[190:193], v[216:219], v[82:85]
	v_mfma_f32_16x16x32_bf16 v[70:73], v[178:181], v[224:227], v[70:73]
	v_mfma_f32_16x16x32_bf16 v[66:69], v[190:193], v[224:227], v[66:69]
	s_barrier
; #define PG8_STAGE(bufoff, gbase, voff) do { _Pragma("unroll") for (int _i = 0; _i < 2; ++_i) \
;         __builtin_amdgcn_global_load_lds((const unsigned*)((const char*)(gbase) + (voff)[_i]), (PG8_LAS unsigned*)(lds + (bufoff) + ldsw + _i * 8192), 16, 0, 0); } while (0)
; #define PG8_LDA(dst, b, h) do { _Pragma("unroll") for (int m = 0; m < 4; ++m) _Pragma("unroll") for (int k = 0; k < 2; ++k) dst[m][k] = *(const PG8_LAS bf16x8*)(lds + PG8_SA(b, h) + aoff + m * 2048 + k * 1024); } while (0)
; #define PG8_MMA(ai, bj, At, Bt) do { __builtin_amdgcn_s_setprio(1); _Pragma("unroll") for (int m = 0; m < 4; ++m) _Pragma("unroll") for (int n = 0; n < 2; ++n) _Pragma("unroll") for (int k = 0; k < 2; ++k) \
;         acc[ai][bj][m][n] = __builtin_amdgcn_mfma_f32_16x16x32_bf16(Bt[n][k], At[m][k], acc[ai][bj][m][n], 0, 0, 0); __builtin_amdgcn_s_setprio(0); } while (0)
; #define PG8_WAIT_V(n) asm volatile("s_waitcnt vmcnt(" #n ")" ::: "memory")
; #define PG8_WAIT_L(n) asm volatile("s_waitcnt lgkmcnt(" #n ")" ::: "memory")
; #define PG8_BAR __builtin_amdgcn_s_barrier()
; #define PG8_SCHED __builtin_amdgcn_sched_barrier(0)
; template <class Epi, class Sched, bool ALIGN_EPI = false, bool SP2 = false, bool A_TILED = false, bool B_TILED = false>
; __device__ __forceinline__ void gemm_phase(PG8_LAS unsigned char* lds, const Gemm g, const Sched& S, const Epi& E) {
;     ...
;         for (int t = 0; t < nt; t += 2) {
;     ...
;             PG8_LDA(At, 1, 1); PG8_STAGE(PG8_SB(1, 0), b3, voffB); PG8_STAGE(PG8_SB(1, 1), b3 + hstepB, voffB); PG8_STAGE(PG8_SA(1, 0), a3, voffA);
;             PG8_WAIT_V(8); PG8_WAIT_L(0); PG8_BAR; PG8_MMA(1, 0, At, B0); PG8_MMA(1, 1, At, B1); PG8_BAR; PG8_SCHED;
	s_add_i32 s40, s60, s42
	v_lshl_add_u64 v[140:141], v[140:141], 0, s[12:13]
	s_mov_b32 m0, s40
	ds_read_b128 v[196:199], v154 offset:49152
	ds_read_b128 v[200:203], v154 offset:50176
	ds_read_b128 v[204:207], v154 offset:51200
	ds_read_b128 v[208:211], v154 offset:52224
	ds_read_b128 v[212:215], v154 offset:53248
	ds_read_b128 v[216:219], v154 offset:54272
	ds_read_b128 v[220:223], v154 offset:55296
	ds_read_b128 v[224:227], v154 offset:56320
	global_load_lds_dwordx4 v[140:141], off
	s_add_i32 m0, s40, 0x2000
	s_add_u32 s38, s38, 0x100080
	v_lshl_add_u64 v[140:141], v[186:187], 0, s[12:13]
	s_addc_u32 s39, s39, 0
	s_add_i32 s40, s61, s42
	global_load_lds_dwordx4 v[140:141], off
	v_lshl_add_u64 v[140:141], s[38:39], 0, v[134:135]
	s_mov_b32 m0, s40
	s_nop 0
	global_load_lds_dwordx4 v[140:141], off
	v_lshl_add_u64 v[140:141], s[38:39], 0, v[136:137]
	s_add_i32 m0, s40, 0x2000
	s_nop 0
	global_load_lds_dwordx4 v[140:141], off
	v_lshl_add_u64 v[140:141], v[228:229], 0, s[12:13]
	s_mov_b32 m0, s53
	s_nop 0
	global_load_lds_dwordx4 v[140:141], off
	v_lshl_add_u64 v[140:141], v[230:231], 0, s[12:13]
	s_mov_b32 m0, s54
	s_nop 0
	global_load_lds_dwordx4 v[140:141], off
	s_waitcnt vmcnt(8)
	s_waitcnt lgkmcnt(0)
	s_barrier
	v_mfma_f32_16x16x32_bf16 v[62:65], v[158:161], v[196:199], v[62:65]
	v_mfma_f32_16x16x32_bf16 v[58:61], v[166:169], v[196:199], v[58:61]
	v_mfma_f32_16x16x32_bf16 v[46:49], v[158:161], v[204:207], v[46:49]
	v_mfma_f32_16x16x32_bf16 v[42:45], v[166:169], v[204:207], v[42:45]
	v_mfma_f32_16x16x32_bf16 v[30:33], v[158:161], v[212:215], v[30:33]
	v_mfma_f32_16x16x32_bf16 v[26:29], v[166:169], v[212:215], v[26:29]
	v_mfma_f32_16x16x32_bf16 v[14:17], v[158:161], v[220:223], v[14:17]
	v_mfma_f32_16x16x32_bf16 v[10:13], v[166:169], v[220:223], v[10:13]
	v_mfma_f32_16x16x32_bf16 v[62:65], v[162:165], v[200:203], v[62:65]
	v_mfma_f32_16x16x32_bf16 v[58:61], v[170:173], v[200:203], v[58:61]
	v_mfma_f32_16x16x32_bf16 v[46:49], v[162:165], v[208:211], v[46:49]
	v_mfma_f32_16x16x32_bf16 v[42:45], v[170:173], v[208:211], v[42:45]
	v_mfma_f32_16x16x32_bf16 v[30:33], v[162:165], v[216:219], v[30:33]
	v_mfma_f32_16x16x32_bf16 v[26:29], v[170:173], v[216:219], v[26:29]
	v_mfma_f32_16x16x32_bf16 v[14:17], v[162:165], v[224:227], v[14:17]
	v_mfma_f32_16x16x32_bf16 v[10:13], v[170:173], v[224:227], v[10:13]
	v_mfma_f32_16x16x32_bf16 v[54:57], v[174:177], v[196:199], v[54:57]
	v_mfma_f32_16x16x32_bf16 v[50:53], v[182:185], v[196:199], v[50:53]
	v_mfma_f32_16x16x32_bf16 v[38:41], v[174:177], v[204:207], v[38:41]
	v_mfma_f32_16x16x32_bf16 v[34:37], v[182:185], v[204:207], v[34:37]
	v_mfma_f32_16x16x32_bf16 v[22:25], v[174:177], v[212:215], v[22:25]
	v_mfma_f32_16x16x32_bf16 v[18:21], v[182:185], v[212:215], v[18:21]
	v_mfma_f32_16x16x32_bf16 v[6:9], v[174:177], v[220:223], v[6:9]
	v_mfma_f32_16x16x32_bf16 v[2:5], v[182:185], v[220:223], v[2:5]
	v_mfma_f32_16x16x32_bf16 v[54:57], v[178:181], v[200:203], v[54:57]
	v_mfma_f32_16x16x32_bf16 v[50:53], v[190:193], v[200:203], v[50:53]
	v_mfma_f32_16x16x32_bf16 v[38:41], v[178:181], v[208:211], v[38:41]
	v_mfma_f32_16x16x32_bf16 v[34:37], v[190:193], v[208:211], v[34:37]
	v_mfma_f32_16x16x32_bf16 v[22:25], v[178:181], v[216:219], v[22:25]
	v_mfma_f32_16x16x32_bf16 v[18:21], v[190:193], v[216:219], v[18:21]
	v_mfma_f32_16x16x32_bf16 v[6:9], v[178:181], v[224:227], v[6:9]
	v_mfma_f32_16x16x32_bf16 v[2:5], v[190:193], v[224:227], v[2:5]
	s_add_i32 s59, s59, 2
	s_add_u32 s36, s36, 0x100
	s_addc_u32 s37, s37, 0
	s_add_u32 s27, s27, 0x100
	s_addc_u32 s58, s58, 0
	s_cmp_gt_u32 s59, 13
	s_barrier
	s_cbranch_scc0 .LBB0_553
	s_and_b64 vcc, exec, s[20:21]
	s_cbranch_vccz .LBB0_556
	s_barrier

; #define PG8_STAGE(bufoff, gbase, voff) do { _Pragma("unroll") for (int _i = 0; _i < 2; ++_i) \
;         __builtin_amdgcn_global_load_lds((const unsigned*)((const char*)(gbase) + (voff)[_i]), (PG8_LAS unsigned*)(lds + (bufoff) + ldsw + _i * 8192), 16, 0, 0); } while (0)
; #define PG8_LDA(dst, b, h) do { _Pragma("unroll") for (int m = 0; m < 4; ++m) _Pragma("unroll") for (int k = 0; k < 2; ++k) dst[m][k] = *(const PG8_LAS bf16x8*)(lds + PG8_SA(b, h) + aoff + m * 2048 + k * 1024); } while (0)
; #define PG8_LDB(dst, b, h) do { _Pragma("unroll") for (int n = 0; n < 2; ++n) _Pragma("unroll") for (int k = 0; k < 2; ++k) dst[n][k] = *(const PG8_LAS bf16x8*)(lds + PG8_SB(b, h) + boff + n * 2048 + k * 1024); } while (0)
; #define PG8_MMA(ai, bj, At, Bt) do { __builtin_amdgcn_s_setprio(1); _Pragma("unroll") for (int m = 0; m < 4; ++m) _Pragma("unroll") for (int n = 0; n < 2; ++n) _Pragma("unroll") for (int k = 0; k < 2; ++k) \
;         acc[ai][bj][m][n] = __builtin_amdgcn_mfma_f32_16x16x32_bf16(Bt[n][k], At[m][k], acc[ai][bj][m][n], 0, 0, 0); __builtin_amdgcn_s_setprio(0); } while (0)
; #define PG8_WAIT_V(n) asm volatile("s_waitcnt vmcnt(" #n ")" ::: "memory")
; #define PG8_WAIT_L(n) asm volatile("s_waitcnt lgkmcnt(" #n ")" ::: "memory")
; #define PG8_BAR __builtin_amdgcn_s_barrier()
; #define PG8_SCHED __builtin_amdgcn_sched_barrier(0)
; template <class Epi, class Sched, bool ALIGN_EPI = false, bool SP2 = false, bool A_TILED = false, bool B_TILED = false>
; __device__ __forceinline__ void gemm_phase(PG8_LAS unsigned char* lds, const Gemm g, const Sched& S, const Epi& E) {
;     ...
;             const char* a1 = cA + (size_t)(t + 1) * kstepA;
;             const char* a2 = last ? nA : cA + (size_t)(t + 2) * kstepA; const char* b2 = last ? nB : cB + (size_t)(t + 2) * kstepB;
;             const char* a3 = a2 + kstepA; const char* b3 = b2 + kstepB;
;             if (last && has_next) S.a_ready(nxt);
;             if constexpr (SP2) {
;             PG8_LDB(B0, 0, 0); PG8_LDB(B1, 0, 1); PG8_SCHED; PG8_LDA(At, 0, 0); PG8_STAGE(PG8_SA(1, 1), a1 + hstepA, voffA);
;             PG8_WAIT_V(8); PG8_WAIT_L(0); PG8_BAR; PG8_MMA(0, 0, At, B0); PG8_MMA(0, 1, At, B1); PG8_BAR; PG8_SCHED;
;             PG8_LDA(At, 0, 1); PG8_STAGE(PG8_SB(0, 0), b2, voffB); PG8_STAGE(PG8_SB(0, 1), b2 + hstepB, voffB); PG8_STAGE(PG8_SA(0, 0), a2, voffA);
.Lg3h_done:
.LBB0_726:
	ds_read_b128 v[126:129], v207
	ds_read_b128 v[130:133], v207 offset:1024
	ds_read_b128 v[134:137], v207 offset:2048
	ds_read_b128 v[138:141], v207 offset:3072
	ds_read_b128 v[150:153], v208
	ds_read_b128 v[154:157], v208 offset:1024
	ds_read_b128 v[158:161], v208 offset:2048
	ds_read_b128 v[162:165], v208 offset:3072
	s_add_u32 s10, s8, 0xfff00080
	s_addc_u32 s11, s9, -1
	s_cmp_eq_u32 s19, 60
	s_cselect_b32 s13, s7, s11
	s_cselect_b32 s12, s14, s10
	s_cselect_b32 s11, s15, s18
	s_cselect_b32 s10, s16, s17
	v_lshl_add_u64 v[236:237], s[8:9], 0, v[180:181]
	s_add_i32 m0, s93, 0xc000
	ds_read_b128 v[166:169], v209
	ds_read_b128 v[184:187], v209 offset:1024
	ds_read_b128 v[190:193], v209 offset:2048
	ds_read_b128 v[216:219], v209 offset:3072
	ds_read_b128 v[220:223], v209 offset:4096
	ds_read_b128 v[224:227], v209 offset:5120
	ds_read_b128 v[228:231], v209 offset:6144
	ds_read_b128 v[232:235], v209 offset:7168
	global_load_lds_dwordx4 v[236:237], off
	v_lshl_add_u64 v[236:237], s[8:9], 0, v[182:183]
	s_add_i32 m0, s93, 0xe000
	s_nop 0
	global_load_lds_dwordx4 v[236:237], off
	s_waitcnt vmcnt(8)
	s_waitcnt lgkmcnt(0)
	s_barrier
	v_mfma_f32_16x16x32_bf16 v[146:149], v[126:129], v[166:169], v[146:149]
	v_mfma_f32_16x16x32_bf16 v[62:65], v[134:137], v[166:169], v[62:65]
	v_mfma_f32_16x16x32_bf16 v[122:125], v[126:129], v[190:193], v[122:125]
	v_mfma_f32_16x16x32_bf16 v[54:57], v[134:137], v[190:193], v[54:57]
	v_mfma_f32_16x16x32_bf16 v[106:109], v[126:129], v[220:223], v[106:109]
	v_mfma_f32_16x16x32_bf16 v[42:45], v[134:137], v[220:223], v[42:45]
	v_mfma_f32_16x16x32_bf16 v[110:113], v[126:129], v[228:231], v[110:113]
	v_mfma_f32_16x16x32_bf16 v[46:49], v[134:137], v[228:231], v[46:49]
	v_mfma_f32_16x16x32_bf16 v[146:149], v[130:133], v[184:187], v[146:149]
	v_mfma_f32_16x16x32_bf16 v[62:65], v[138:141], v[184:187], v[62:65]
	v_mfma_f32_16x16x32_bf16 v[122:125], v[130:133], v[216:219], v[122:125]
	v_mfma_f32_16x16x32_bf16 v[54:57], v[138:141], v[216:219], v[54:57]
	v_mfma_f32_16x16x32_bf16 v[106:109], v[130:133], v[224:227], v[106:109]
	v_mfma_f32_16x16x32_bf16 v[42:45], v[138:141], v[224:227], v[42:45]
	v_mfma_f32_16x16x32_bf16 v[110:113], v[130:133], v[232:235], v[110:113]
	v_mfma_f32_16x16x32_bf16 v[46:49], v[138:141], v[232:235], v[46:49]
	v_mfma_f32_16x16x32_bf16 v[118:121], v[150:153], v[166:169], v[118:121]
	v_mfma_f32_16x16x32_bf16 v[66:69], v[158:161], v[166:169], v[66:69]
	v_mfma_f32_16x16x32_bf16 v[142:145], v[150:153], v[190:193], v[142:145]
	v_mfma_f32_16x16x32_bf16 v[58:61], v[158:161], v[190:193], v[58:61]
	v_mfma_f32_16x16x32_bf16 v[114:117], v[150:153], v[220:223], v[114:117]
	v_mfma_f32_16x16x32_bf16 v[50:53], v[158:161], v[220:223], v[50:53]
	v_mfma_f32_16x16x32_bf16 v[102:105], v[150:153], v[228:231], v[102:105]
	v_mfma_f32_16x16x32_bf16 v[38:41], v[158:161], v[228:231], v[38:41]
	v_mfma_f32_16x16x32_bf16 v[118:121], v[154:157], v[184:187], v[118:121]
	v_mfma_f32_16x16x32_bf16 v[66:69], v[162:165], v[184:187], v[66:69]
	v_mfma_f32_16x16x32_bf16 v[142:145], v[154:157], v[216:219], v[142:145]
	v_mfma_f32_16x16x32_bf16 v[58:61], v[162:165], v[216:219], v[58:61]
	v_mfma_f32_16x16x32_bf16 v[114:117], v[154:157], v[224:227], v[114:117]
	v_mfma_f32_16x16x32_bf16 v[50:53], v[162:165], v[224:227], v[50:53]
	v_mfma_f32_16x16x32_bf16 v[102:105], v[154:157], v[232:235], v[102:105]
	v_mfma_f32_16x16x32_bf16 v[38:41], v[162:165], v[232:235], v[38:41]
	s_barrier
	s_add_i32 s20, s24, s92
	v_lshl_add_u64 v[236:237], s[10:11], 0, v[172:173]
	s_mov_b32 m0, s20
	ds_read_b128 v[166:169], v209 offset:16384
	ds_read_b128 v[184:187], v209 offset:17408
	ds_read_b128 v[190:193], v209 offset:18432
	ds_read_b128 v[216:219], v209 offset:19456
	ds_read_b128 v[220:223], v209 offset:20480
	ds_read_b128 v[224:227], v209 offset:21504
	ds_read_b128 v[228:231], v209 offset:22528
	ds_read_b128 v[232:235], v209 offset:23552
	global_load_lds_dwordx4 v[236:237], off
	s_add_i32 m0, s20, 0x2000
	s_add_u32 s20, s10, 0x100000
	v_lshl_add_u64 v[238:239], s[10:11], 0, v[176:177]
	s_addc_u32 s21, s11, 0
	s_add_i32 s22, s25, s92
	global_load_lds_dwordx4 v[238:239], off
	v_lshl_add_u64 v[240:241], s[20:21], 0, v[172:173]
	s_mov_b32 m0, s22
	v_lshl_add_u64 v[242:243], s[12:13], 0, v[174:175]
	global_load_lds_dwordx4 v[240:241], off
	v_lshl_add_u64 v[240:241], s[20:21], 0, v[176:177]
	s_add_i32 m0, s22, 0x2000
	s_nop 0
	global_load_lds_dwordx4 v[240:241], off
	v_lshl_add_u64 v[240:241], s[12:13], 0, v[170:171]
	s_mov_b32 m0, s93
	s_nop 0
	global_load_lds_dwordx4 v[240:241], off
	s_mov_b32 m0, s94
	s_nop 0
	global_load_lds_dwordx4 v[242:243], off
	s_waitcnt vmcnt(8)
	s_waitcnt lgkmcnt(0)
	s_barrier
; #define PG8_STAGE(bufoff, gbase, voff) do { _Pragma("unroll") for (int _i = 0; _i < 2; ++_i) \
;         __builtin_amdgcn_global_load_lds((const unsigned*)((const char*)(gbase) + (voff)[_i]), (PG8_LAS unsigned*)(lds + (bufoff) + ldsw + _i * 8192), 16, 0, 0); } while (0)
; #define PG8_LDA(dst, b, h) do { _Pragma("unroll") for (int m = 0; m < 4; ++m) _Pragma("unroll") for (int k = 0; k < 2; ++k) dst[m][k] = *(const PG8_LAS bf16x8*)(lds + PG8_SA(b, h) + aoff + m * 2048 + k * 1024); } while (0)
; #define PG8_LDB(dst, b, h) do { _Pragma("unroll") for (int n = 0; n < 2; ++n) _Pragma("unroll") for (int k = 0; k < 2; ++k) dst[n][k] = *(const PG8_LAS bf16x8*)(lds + PG8_SB(b, h) + boff + n * 2048 + k * 1024); } while (0)
; #define PG8_MMA(ai, bj, At, Bt) do { __builtin_amdgcn_s_setprio(1); _Pragma("unroll") for (int m = 0; m < 4; ++m) _Pragma("unroll") for (int n = 0; n < 2; ++n) _Pragma("unroll") for (int k = 0; k < 2; ++k) \
;         acc[ai][bj][m][n] = __builtin_amdgcn_mfma_f32_16x16x32_bf16(Bt[n][k], At[m][k], acc[ai][bj][m][n], 0, 0, 0); __builtin_amdgcn_s_setprio(0); } while (0)
; #define PG8_WAIT_V(n) asm volatile("s_waitcnt vmcnt(" #n ")" ::: "memory")
; #define PG8_WAIT_L(n) asm volatile("s_waitcnt lgkmcnt(" #n ")" ::: "memory")
; #define PG8_BAR __builtin_amdgcn_s_barrier()
; #define PG8_SCHED __builtin_amdgcn_sched_barrier(0)
; template <class Epi, class Sched, bool ALIGN_EPI = false, bool SP2 = false, bool A_TILED = false, bool B_TILED = false>
; __device__ __forceinline__ void gemm_phase(PG8_LAS unsigned char* lds, const Gemm g, const Sched& S, const Epi& E) {
;     ...
;             PG8_WAIT_V(8); PG8_WAIT_L(0); PG8_BAR; PG8_MMA(1, 0, At, B0); PG8_MMA(1, 1, At, B1); PG8_BAR; PG8_SCHED;
;             PG8_LDB(B0, 1, 0); PG8_LDB(B1, 1, 1); PG8_SCHED; PG8_LDA(At, 1, 0); PG8_STAGE(PG8_SA(0, 1), a2 + hstepA, voffA);
;             PG8_WAIT_V(8); PG8_WAIT_L(0); PG8_BAR; PG8_MMA(0, 0, At, B0); PG8_MMA(0, 1, At, B1); PG8_BAR; PG8_SCHED;
	v_mfma_f32_16x16x32_bf16 v[94:97], v[126:129], v[166:169], v[94:97]
	v_mfma_f32_16x16x32_bf16 v[30:33], v[134:137], v[166:169], v[30:33]
	v_mfma_f32_16x16x32_bf16 v[86:89], v[126:129], v[190:193], v[86:89]
	v_mfma_f32_16x16x32_bf16 v[22:25], v[134:137], v[190:193], v[22:25]
	v_mfma_f32_16x16x32_bf16 v[74:77], v[126:129], v[220:223], v[74:77]
	v_mfma_f32_16x16x32_bf16 v[10:13], v[134:137], v[220:223], v[10:13]
	v_mfma_f32_16x16x32_bf16 v[78:81], v[126:129], v[228:231], v[78:81]
	v_mfma_f32_16x16x32_bf16 v[14:17], v[134:137], v[228:231], v[14:17]
	v_mfma_f32_16x16x32_bf16 v[94:97], v[130:133], v[184:187], v[94:97]
	v_mfma_f32_16x16x32_bf16 v[30:33], v[138:141], v[184:187], v[30:33]
	v_mfma_f32_16x16x32_bf16 v[86:89], v[130:133], v[216:219], v[86:89]
	v_mfma_f32_16x16x32_bf16 v[22:25], v[138:141], v[216:219], v[22:25]
	v_mfma_f32_16x16x32_bf16 v[74:77], v[130:133], v[224:227], v[74:77]
	v_mfma_f32_16x16x32_bf16 v[10:13], v[138:141], v[224:227], v[10:13]
	v_mfma_f32_16x16x32_bf16 v[78:81], v[130:133], v[232:235], v[78:81]
	v_mfma_f32_16x16x32_bf16 v[14:17], v[138:141], v[232:235], v[14:17]
	v_mfma_f32_16x16x32_bf16 v[98:101], v[150:153], v[166:169], v[98:101]
	v_mfma_f32_16x16x32_bf16 v[34:37], v[158:161], v[166:169], v[34:37]
	v_mfma_f32_16x16x32_bf16 v[90:93], v[150:153], v[190:193], v[90:93]
	v_mfma_f32_16x16x32_bf16 v[26:29], v[158:161], v[190:193], v[26:29]
	v_mfma_f32_16x16x32_bf16 v[82:85], v[150:153], v[220:223], v[82:85]
	v_mfma_f32_16x16x32_bf16 v[18:21], v[158:161], v[220:223], v[18:21]
	v_mfma_f32_16x16x32_bf16 v[70:73], v[150:153], v[228:231], v[70:73]
	v_mfma_f32_16x16x32_bf16 v[6:9], v[158:161], v[228:231], v[6:9]
	v_mfma_f32_16x16x32_bf16 v[98:101], v[154:157], v[184:187], v[98:101]
	v_mfma_f32_16x16x32_bf16 v[34:37], v[162:165], v[184:187], v[34:37]
	v_mfma_f32_16x16x32_bf16 v[90:93], v[154:157], v[216:219], v[90:93]
	v_mfma_f32_16x16x32_bf16 v[26:29], v[162:165], v[216:219], v[26:29]
	v_mfma_f32_16x16x32_bf16 v[82:85], v[154:157], v[224:227], v[82:85]
	v_mfma_f32_16x16x32_bf16 v[18:21], v[162:165], v[224:227], v[18:21]
	v_mfma_f32_16x16x32_bf16 v[70:73], v[154:157], v[232:235], v[70:73]
	v_mfma_f32_16x16x32_bf16 v[6:9], v[162:165], v[232:235], v[6:9]
	s_barrier
	s_add_i32 s20, 0, 0x18000
	s_add_i32 s21, 0, 0x1c000
	v_add_u32_e32 v138, s20, v203
	v_add_u32_e32 v162, s21, v203
	ds_read_b128 v[126:129], v138
	ds_read_b128 v[130:133], v138 offset:1024
	ds_read_b128 v[134:137], v138 offset:2048
	ds_read_b128 v[138:141], v138 offset:3072
	ds_read_b128 v[150:153], v162
	ds_read_b128 v[154:157], v162 offset:1024
	ds_read_b128 v[158:161], v162 offset:2048
	ds_read_b128 v[162:165], v162 offset:3072
	s_add_u32 s12, s12, 0x100000
	s_addc_u32 s13, s13, 0
	s_mov_b32 m0, s95
	v_lshl_add_u64 v[244:245], s[12:13], 0, v[170:171]
	ds_read_b128 v[166:169], v209 offset:32768
	ds_read_b128 v[184:187], v209 offset:33792
	ds_read_b128 v[190:193], v209 offset:34816
	ds_read_b128 v[216:219], v209 offset:35840
	ds_read_b128 v[220:223], v209 offset:36864
	ds_read_b128 v[224:227], v209 offset:37888
	ds_read_b128 v[228:231], v209 offset:38912
	ds_read_b128 v[232:235], v209 offset:39936
	global_load_lds_dwordx4 v[244:245], off
	v_lshl_add_u64 v[244:245], s[12:13], 0, v[174:175]
	s_mov_b32 m0, s96
	s_nop 0
	global_load_lds_dwordx4 v[244:245], off
	s_waitcnt vmcnt(8)
	s_waitcnt lgkmcnt(0)
	s_barrier
	v_mfma_f32_16x16x32_bf16 v[146:149], v[126:129], v[166:169], v[146:149]
	v_mfma_f32_16x16x32_bf16 v[62:65], v[134:137], v[166:169], v[62:65]
	v_mfma_f32_16x16x32_bf16 v[122:125], v[126:129], v[190:193], v[122:125]
	v_mfma_f32_16x16x32_bf16 v[54:57], v[134:137], v[190:193], v[54:57]
	v_mfma_f32_16x16x32_bf16 v[106:109], v[126:129], v[220:223], v[106:109]
	v_mfma_f32_16x16x32_bf16 v[42:45], v[134:137], v[220:223], v[42:45]
	v_mfma_f32_16x16x32_bf16 v[110:113], v[126:129], v[228:231], v[110:113]
	v_mfma_f32_16x16x32_bf16 v[46:49], v[134:137], v[228:231], v[46:49]
	v_mfma_f32_16x16x32_bf16 v[146:149], v[130:133], v[184:187], v[146:149]
	v_mfma_f32_16x16x32_bf16 v[62:65], v[138:141], v[184:187], v[62:65]
	v_mfma_f32_16x16x32_bf16 v[122:125], v[130:133], v[216:219], v[122:125]
	v_mfma_f32_16x16x32_bf16 v[54:57], v[138:141], v[216:219], v[54:57]
	v_mfma_f32_16x16x32_bf16 v[106:109], v[130:133], v[224:227], v[106:109]
	v_mfma_f32_16x16x32_bf16 v[42:45], v[138:141], v[224:227], v[42:45]
	v_mfma_f32_16x16x32_bf16 v[110:113], v[130:133], v[232:235], v[110:113]
	v_mfma_f32_16x16x32_bf16 v[46:49], v[138:141], v[232:235], v[46:49]
	v_mfma_f32_16x16x32_bf16 v[118:121], v[150:153], v[166:169], v[118:121]
	v_mfma_f32_16x16x32_bf16 v[66:69], v[158:161], v[166:169], v[66:69]
	v_mfma_f32_16x16x32_bf16 v[142:145], v[150:153], v[190:193], v[142:145]
	v_mfma_f32_16x16x32_bf16 v[58:61], v[158:161], v[190:193], v[58:61]
	v_mfma_f32_16x16x32_bf16 v[114:117], v[150:153], v[220:223], v[114:117]
	v_mfma_f32_16x16x32_bf16 v[50:53], v[158:161], v[220:223], v[50:53]
	v_mfma_f32_16x16x32_bf16 v[102:105], v[150:153], v[228:231], v[102:105]
	v_mfma_f32_16x16x32_bf16 v[38:41], v[158:161], v[228:231], v[38:41]
	v_mfma_f32_16x16x32_bf16 v[118:121], v[154:157], v[184:187], v[118:121]
	v_mfma_f32_16x16x32_bf16 v[66:69], v[162:165], v[184:187], v[66:69]
	v_mfma_f32_16x16x32_bf16 v[142:145], v[154:157], v[216:219], v[142:145]
	v_mfma_f32_16x16x32_bf16 v[58:61], v[162:165], v[216:219], v[58:61]
	v_mfma_f32_16x16x32_bf16 v[114:117], v[154:157], v[224:227], v[114:117]
	v_mfma_f32_16x16x32_bf16 v[50:53], v[162:165], v[224:227], v[50:53]
	v_mfma_f32_16x16x32_bf16 v[102:105], v[154:157], v[232:235], v[102:105]
	v_mfma_f32_16x16x32_bf16 v[38:41], v[162:165], v[232:235], v[38:41]
	s_barrier
; #define PG8_STAGE(bufoff, gbase, voff) do { _Pragma("unroll") for (int _i = 0; _i < 2; ++_i) \
;         __builtin_amdgcn_global_load_lds((const unsigned*)((const char*)(gbase) + (voff)[_i]), (PG8_LAS unsigned*)(lds + (bufoff) + ldsw + _i * 8192), 16, 0, 0); } while (0)
; #define PG8_LDA(dst, b, h) do { _Pragma("unroll") for (int m = 0; m < 4; ++m) _Pragma("unroll") for (int k = 0; k < 2; ++k) dst[m][k] = *(const PG8_LAS bf16x8*)(lds + PG8_SA(b, h) + aoff + m * 2048 + k * 1024); } while (0)
; #define PG8_MMA(ai, bj, At, Bt) do { __builtin_amdgcn_s_setprio(1); _Pragma("unroll") for (int m = 0; m < 4; ++m) _Pragma("unroll") for (int n = 0; n < 2; ++n) _Pragma("unroll") for (int k = 0; k < 2; ++k) \
;         acc[ai][bj][m][n] = __builtin_amdgcn_mfma_f32_16x16x32_bf16(Bt[n][k], At[m][k], acc[ai][bj][m][n], 0, 0, 0); __builtin_amdgcn_s_setprio(0); } while (0)
; #define PG8_WAIT_V(n) asm volatile("s_waitcnt vmcnt(" #n ")" ::: "memory")
; #define PG8_WAIT_L(n) asm volatile("s_waitcnt lgkmcnt(" #n ")" ::: "memory")
; #define PG8_BAR __builtin_amdgcn_s_barrier()
; #define PG8_SCHED __builtin_amdgcn_sched_barrier(0)
; template <class Epi, class Sched, bool ALIGN_EPI = false, bool SP2 = false, bool A_TILED = false, bool B_TILED = false>
; __device__ __forceinline__ void gemm_phase(PG8_LAS unsigned char* lds, const Gemm g, const Sched& S, const Epi& E) {
;     ...
;         for (int t = 0; t < nt; t += 2) {
;     ...
;             PG8_LDA(At, 1, 1); PG8_STAGE(PG8_SB(1, 0), b3, voffB); PG8_STAGE(PG8_SB(1, 1), b3 + hstepB, voffB); PG8_STAGE(PG8_SA(1, 0), a3, voffA);
;             PG8_WAIT_V(8); PG8_WAIT_L(0); PG8_BAR; PG8_MMA(1, 0, At, B0); PG8_MMA(1, 1, At, B1); PG8_BAR; PG8_SCHED;
	s_add_i32 s12, s20, s92
	v_lshl_add_u64 v[236:237], v[236:237], 0, s[46:47]
	s_mov_b32 m0, s12
	ds_read_b128 v[166:169], v209 offset:49152
	ds_read_b128 v[184:187], v209 offset:50176
	ds_read_b128 v[190:193], v209 offset:51200
	ds_read_b128 v[216:219], v209 offset:52224
	ds_read_b128 v[220:223], v209 offset:53248
	ds_read_b128 v[224:227], v209 offset:54272
	ds_read_b128 v[228:231], v209 offset:55296
	ds_read_b128 v[232:235], v209 offset:56320
	global_load_lds_dwordx4 v[236:237], off
	s_add_i32 m0, s12, 0x2000
	s_add_u32 s10, s10, 0x100080
	v_lshl_add_u64 v[236:237], v[238:239], 0, s[46:47]
	s_addc_u32 s11, s11, 0
	s_add_i32 s12, s21, s92
	global_load_lds_dwordx4 v[236:237], off
	v_lshl_add_u64 v[236:237], s[10:11], 0, v[172:173]
	s_mov_b32 m0, s12
	s_nop 0
	global_load_lds_dwordx4 v[236:237], off
	v_lshl_add_u64 v[236:237], s[10:11], 0, v[176:177]
	s_add_i32 m0, s12, 0x2000
	s_nop 0
	global_load_lds_dwordx4 v[236:237], off
	v_lshl_add_u64 v[236:237], v[240:241], 0, s[46:47]
	s_mov_b32 m0, s54
	s_nop 0
	global_load_lds_dwordx4 v[236:237], off
	v_lshl_add_u64 v[236:237], v[242:243], 0, s[46:47]
	s_mov_b32 m0, s55
	s_nop 0
	global_load_lds_dwordx4 v[236:237], off
	s_waitcnt vmcnt(8)
	s_waitcnt lgkmcnt(0)
	s_barrier
	v_mfma_f32_16x16x32_bf16 v[94:97], v[126:129], v[166:169], v[94:97]
	v_mfma_f32_16x16x32_bf16 v[30:33], v[134:137], v[166:169], v[30:33]
	v_mfma_f32_16x16x32_bf16 v[86:89], v[126:129], v[190:193], v[86:89]
	v_mfma_f32_16x16x32_bf16 v[22:25], v[134:137], v[190:193], v[22:25]
	v_mfma_f32_16x16x32_bf16 v[74:77], v[126:129], v[220:223], v[74:77]
	v_mfma_f32_16x16x32_bf16 v[10:13], v[134:137], v[220:223], v[10:13]
	v_mfma_f32_16x16x32_bf16 v[78:81], v[126:129], v[228:231], v[78:81]
	v_mfma_f32_16x16x32_bf16 v[14:17], v[134:137], v[228:231], v[14:17]
	v_mfma_f32_16x16x32_bf16 v[94:97], v[130:133], v[184:187], v[94:97]
	v_mfma_f32_16x16x32_bf16 v[30:33], v[138:141], v[184:187], v[30:33]
	v_mfma_f32_16x16x32_bf16 v[86:89], v[130:133], v[216:219], v[86:89]
	v_mfma_f32_16x16x32_bf16 v[22:25], v[138:141], v[216:219], v[22:25]
	v_mfma_f32_16x16x32_bf16 v[74:77], v[130:133], v[224:227], v[74:77]
	v_mfma_f32_16x16x32_bf16 v[10:13], v[138:141], v[224:227], v[10:13]
	v_mfma_f32_16x16x32_bf16 v[78:81], v[130:133], v[232:235], v[78:81]
	v_mfma_f32_16x16x32_bf16 v[14:17], v[138:141], v[232:235], v[14:17]
	v_mfma_f32_16x16x32_bf16 v[98:101], v[150:153], v[166:169], v[98:101]
	v_mfma_f32_16x16x32_bf16 v[34:37], v[158:161], v[166:169], v[34:37]
	v_mfma_f32_16x16x32_bf16 v[90:93], v[150:153], v[190:193], v[90:93]
	v_mfma_f32_16x16x32_bf16 v[26:29], v[158:161], v[190:193], v[26:29]
	v_mfma_f32_16x16x32_bf16 v[82:85], v[150:153], v[220:223], v[82:85]
	v_mfma_f32_16x16x32_bf16 v[18:21], v[158:161], v[220:223], v[18:21]
	v_mfma_f32_16x16x32_bf16 v[70:73], v[150:153], v[228:231], v[70:73]
	v_mfma_f32_16x16x32_bf16 v[6:9], v[158:161], v[228:231], v[6:9]
	v_mfma_f32_16x16x32_bf16 v[98:101], v[154:157], v[184:187], v[98:101]
	v_mfma_f32_16x16x32_bf16 v[34:37], v[162:165], v[184:187], v[34:37]
	v_mfma_f32_16x16x32_bf16 v[90:93], v[154:157], v[216:219], v[90:93]
	v_mfma_f32_16x16x32_bf16 v[26:29], v[162:165], v[216:219], v[26:29]
	v_mfma_f32_16x16x32_bf16 v[82:85], v[154:157], v[224:227], v[82:85]
	v_mfma_f32_16x16x32_bf16 v[18:21], v[162:165], v[224:227], v[18:21]
	v_mfma_f32_16x16x32_bf16 v[70:73], v[154:157], v[232:235], v[70:73]
	v_mfma_f32_16x16x32_bf16 v[6:9], v[162:165], v[232:235], v[6:9]
	s_add_i32 s19, s19, 2
	s_add_u32 s8, s8, 0x100
	s_addc_u32 s9, s9, 0
	s_add_u32 s17, s17, 0x100
	s_addc_u32 s18, s18, 0
	s_cmp_gt_u32 s19, 61
	s_barrier
	s_cbranch_scc0 .LBB0_726
	s_and_b64 vcc, exec, s[56:57]
	s_cbranch_vccz .LBB0_729
	s_barrier

; #define PG8_STAGE(bufoff, gbase, voff) do { _Pragma("unroll") for (int _i = 0; _i < 2; ++_i) \
;         __builtin_amdgcn_global_load_lds((const unsigned*)((const char*)(gbase) + (voff)[_i]), (PG8_LAS unsigned*)(lds + (bufoff) + ldsw + _i * 8192), 16, 0, 0); } while (0)
; #define PG8_LDA(dst, b, h) do { _Pragma("unroll") for (int m = 0; m < 4; ++m) _Pragma("unroll") for (int k = 0; k < 2; ++k) dst[m][k] = *(const PG8_LAS bf16x8*)(lds + PG8_SA(b, h) + aoff + m * 2048 + k * 1024); } while (0)
; #define PG8_LDB(dst, b, h) do { _Pragma("unroll") for (int n = 0; n < 2; ++n) _Pragma("unroll") for (int k = 0; k < 2; ++k) dst[n][k] = *(const PG8_LAS bf16x8*)(lds + PG8_SB(b, h) + boff + n * 2048 + k * 1024); } while (0)
; #define PG8_MMA(ai, bj, At, Bt) do { __builtin_amdgcn_s_setprio(1); _Pragma("unroll") for (int m = 0; m < 4; ++m) _Pragma("unroll") for (int n = 0; n < 2; ++n) _Pragma("unroll") for (int k = 0; k < 2; ++k) \
;         acc[ai][bj][m][n] = __builtin_amdgcn_mfma_f32_16x16x32_bf16(Bt[n][k], At[m][k], acc[ai][bj][m][n], 0, 0, 0); __builtin_amdgcn_s_setprio(0); } while (0)
; #define PG8_WAIT_V(n) asm volatile("s_waitcnt vmcnt(" #n ")" ::: "memory")
; #define PG8_WAIT_L(n) asm volatile("s_waitcnt lgkmcnt(" #n ")" ::: "memory")
; #define PG8_BAR __builtin_amdgcn_s_barrier()
; #define PG8_SCHED __builtin_amdgcn_sched_barrier(0)
; template <class Epi, class Sched, bool ALIGN_EPI = false, bool SP2 = false, bool A_TILED = false, bool B_TILED = false>
; __device__ __forceinline__ void gemm_phase(PG8_LAS unsigned char* lds, const Gemm g, const Sched& S, const Epi& E) {
;     ...
;             const char* a1 = cA + (size_t)(t + 1) * kstepA;
;             const char* a2 = last ? nA : cA + (size_t)(t + 2) * kstepA; const char* b2 = last ? nB : cB + (size_t)(t + 2) * kstepB;
;             const char* a3 = a2 + kstepA; const char* b3 = b2 + kstepB;
;             if (last && has_next) S.a_ready(nxt);
;             if constexpr (SP2) {
;             PG8_LDB(B0, 0, 0); PG8_LDB(B1, 0, 1); PG8_SCHED; PG8_LDA(At, 0, 0); PG8_STAGE(PG8_SA(1, 1), a1 + hstepA, voffA);
;             PG8_WAIT_V(8); PG8_WAIT_L(0); PG8_BAR; PG8_MMA(0, 0, At, B0); PG8_MMA(0, 1, At, B1); PG8_BAR; PG8_SCHED;
;             PG8_LDA(At, 0, 1); PG8_STAGE(PG8_SB(0, 0), b2, voffB); PG8_STAGE(PG8_SB(0, 1), b2 + hstepB, voffB); PG8_STAGE(PG8_SA(0, 0), a2, voffA);
.LBB0_905:
	ds_read_b128 v[140:143], v1
	ds_read_b128 v[144:147], v1 offset:1024
	ds_read_b128 v[148:151], v1 offset:2048
	ds_read_b128 v[152:155], v1 offset:3072
	ds_read_b128 v[156:159], v137
	ds_read_b128 v[160:163], v137 offset:1024
	ds_read_b128 v[164:167], v137 offset:2048
	ds_read_b128 v[178:181], v137 offset:3072
	s_add_u32 s30, s26, 0xfff00080
	s_addc_u32 s31, s27, -1
	s_cmp_eq_u32 s44, 4
	s_cselect_b32 s35, s13, s31
	s_cselect_b32 s34, s17, s30
	s_cselect_b32 s31, s15, s43
	s_cselect_b32 s30, s25, s42
	v_lshl_add_u64 v[168:169], s[26:27], 0, v[132:133]
	s_add_i32 m0, s29, 0xc000
	ds_read_b128 v[182:185], v138
	ds_read_b128 v[190:193], v138 offset:1024
	ds_read_b128 v[196:199], v138 offset:2048
	ds_read_b128 v[200:203], v138 offset:3072
	ds_read_b128 v[204:207], v138 offset:4096
	ds_read_b128 v[208:211], v138 offset:5120
	ds_read_b128 v[212:215], v138 offset:6144
	ds_read_b128 v[216:219], v138 offset:7168
	global_load_lds_dwordx4 v[168:169], off
	v_lshl_add_u64 v[168:169], s[26:27], 0, v[134:135]
	s_add_i32 m0, s29, 0xe000
	s_nop 0
	global_load_lds_dwordx4 v[168:169], off
	s_waitcnt vmcnt(8)
	s_waitcnt lgkmcnt(0)
	s_barrier
	v_mfma_f32_16x16x32_bf16 v[126:129], v[140:143], v[182:185], v[126:129]
	v_mfma_f32_16x16x32_bf16 v[122:125], v[148:151], v[182:185], v[122:125]
	v_mfma_f32_16x16x32_bf16 v[118:121], v[140:143], v[196:199], v[118:121]
	v_mfma_f32_16x16x32_bf16 v[114:117], v[148:151], v[196:199], v[114:117]
	v_mfma_f32_16x16x32_bf16 v[110:113], v[140:143], v[204:207], v[110:113]
	v_mfma_f32_16x16x32_bf16 v[102:105], v[148:151], v[204:207], v[102:105]
	v_mfma_f32_16x16x32_bf16 v[94:97], v[140:143], v[212:215], v[94:97]
	v_mfma_f32_16x16x32_bf16 v[86:89], v[148:151], v[212:215], v[86:89]
	v_mfma_f32_16x16x32_bf16 v[126:129], v[144:147], v[190:193], v[126:129]
	v_mfma_f32_16x16x32_bf16 v[122:125], v[152:155], v[190:193], v[122:125]
	v_mfma_f32_16x16x32_bf16 v[118:121], v[144:147], v[200:203], v[118:121]
	v_mfma_f32_16x16x32_bf16 v[114:117], v[152:155], v[200:203], v[114:117]
	v_mfma_f32_16x16x32_bf16 v[110:113], v[144:147], v[208:211], v[110:113]
	v_mfma_f32_16x16x32_bf16 v[102:105], v[152:155], v[208:211], v[102:105]
	v_mfma_f32_16x16x32_bf16 v[94:97], v[144:147], v[216:219], v[94:97]
	v_mfma_f32_16x16x32_bf16 v[86:89], v[152:155], v[216:219], v[86:89]
	v_mfma_f32_16x16x32_bf16 v[106:109], v[156:159], v[182:185], v[106:109]
	v_mfma_f32_16x16x32_bf16 v[98:101], v[164:167], v[182:185], v[98:101]
	v_mfma_f32_16x16x32_bf16 v[90:93], v[156:159], v[196:199], v[90:93]
	v_mfma_f32_16x16x32_bf16 v[82:85], v[164:167], v[196:199], v[82:85]
	v_mfma_f32_16x16x32_bf16 v[78:81], v[156:159], v[204:207], v[78:81]
	v_mfma_f32_16x16x32_bf16 v[74:77], v[164:167], v[204:207], v[74:77]
	v_mfma_f32_16x16x32_bf16 v[70:73], v[156:159], v[212:215], v[70:73]
	v_mfma_f32_16x16x32_bf16 v[66:69], v[164:167], v[212:215], v[66:69]
	v_mfma_f32_16x16x32_bf16 v[106:109], v[160:163], v[190:193], v[106:109]
	v_mfma_f32_16x16x32_bf16 v[98:101], v[178:181], v[190:193], v[98:101]
	v_mfma_f32_16x16x32_bf16 v[90:93], v[160:163], v[200:203], v[90:93]
	v_mfma_f32_16x16x32_bf16 v[82:85], v[178:181], v[200:203], v[82:85]
	v_mfma_f32_16x16x32_bf16 v[78:81], v[160:163], v[208:211], v[78:81]
	v_mfma_f32_16x16x32_bf16 v[74:77], v[178:181], v[208:211], v[74:77]
	v_mfma_f32_16x16x32_bf16 v[70:73], v[160:163], v[216:219], v[70:73]
	v_mfma_f32_16x16x32_bf16 v[66:69], v[178:181], v[216:219], v[66:69]
	s_barrier
	s_add_i32 s45, s4, s28
	v_lshl_add_u64 v[168:169], s[30:31], 0, v[172:173]
	s_mov_b32 m0, s45
	ds_read_b128 v[182:185], v138 offset:16384
	ds_read_b128 v[190:193], v138 offset:17408
	ds_read_b128 v[196:199], v138 offset:18432
	ds_read_b128 v[200:203], v138 offset:19456
	ds_read_b128 v[204:207], v138 offset:20480
	ds_read_b128 v[208:211], v138 offset:21504
	ds_read_b128 v[212:215], v138 offset:22528
	ds_read_b128 v[216:219], v138 offset:23552
	global_load_lds_dwordx4 v[168:169], off
	s_add_i32 m0, s45, 0x2000
	s_add_u32 s46, s30, 0x100000
	v_lshl_add_u64 v[186:187], s[30:31], 0, v[176:177]
	s_addc_u32 s47, s31, 0
	s_add_i32 s45, s40, s28
	global_load_lds_dwordx4 v[186:187], off
	v_lshl_add_u64 v[220:221], s[46:47], 0, v[172:173]
	s_mov_b32 m0, s45
	v_lshl_add_u64 v[222:223], s[34:35], 0, v[174:175]
	global_load_lds_dwordx4 v[220:221], off
	v_lshl_add_u64 v[220:221], s[46:47], 0, v[176:177]
	s_add_i32 m0, s45, 0x2000
	s_nop 0
	global_load_lds_dwordx4 v[220:221], off
	v_lshl_add_u64 v[220:221], s[34:35], 0, v[170:171]
	s_mov_b32 m0, s29
	s_nop 0
	global_load_lds_dwordx4 v[220:221], off
	s_mov_b32 m0, s33
	s_nop 0
	global_load_lds_dwordx4 v[222:223], off
	s_waitcnt vmcnt(8)
	s_waitcnt lgkmcnt(0)
	s_barrier
; #define PG8_STAGE(bufoff, gbase, voff) do { _Pragma("unroll") for (int _i = 0; _i < 2; ++_i) \
;         __builtin_amdgcn_global_load_lds((const unsigned*)((const char*)(gbase) + (voff)[_i]), (PG8_LAS unsigned*)(lds + (bufoff) + ldsw + _i * 8192), 16, 0, 0); } while (0)
; #define PG8_LDA(dst, b, h) do { _Pragma("unroll") for (int m = 0; m < 4; ++m) _Pragma("unroll") for (int k = 0; k < 2; ++k) dst[m][k] = *(const PG8_LAS bf16x8*)(lds + PG8_SA(b, h) + aoff + m * 2048 + k * 1024); } while (0)
; #define PG8_LDB(dst, b, h) do { _Pragma("unroll") for (int n = 0; n < 2; ++n) _Pragma("unroll") for (int k = 0; k < 2; ++k) dst[n][k] = *(const PG8_LAS bf16x8*)(lds + PG8_SB(b, h) + boff + n * 2048 + k * 1024); } while (0)
; #define PG8_MMA(ai, bj, At, Bt) do { __builtin_amdgcn_s_setprio(1); _Pragma("unroll") for (int m = 0; m < 4; ++m) _Pragma("unroll") for (int n = 0; n < 2; ++n) _Pragma("unroll") for (int k = 0; k < 2; ++k) \
;         acc[ai][bj][m][n] = __builtin_amdgcn_mfma_f32_16x16x32_bf16(Bt[n][k], At[m][k], acc[ai][bj][m][n], 0, 0, 0); __builtin_amdgcn_s_setprio(0); } while (0)
; #define PG8_WAIT_V(n) asm volatile("s_waitcnt vmcnt(" #n ")" ::: "memory")
; #define PG8_WAIT_L(n) asm volatile("s_waitcnt lgkmcnt(" #n ")" ::: "memory")
; #define PG8_BAR __builtin_amdgcn_s_barrier()
; #define PG8_SCHED __builtin_amdgcn_sched_barrier(0)
; template <class Epi, class Sched, bool ALIGN_EPI = false, bool SP2 = false, bool A_TILED = false, bool B_TILED = false>
; __device__ __forceinline__ void gemm_phase(PG8_LAS unsigned char* lds, const Gemm g, const Sched& S, const Epi& E) {
;     ...
;             PG8_WAIT_V(8); PG8_WAIT_L(0); PG8_BAR; PG8_MMA(1, 0, At, B0); PG8_MMA(1, 1, At, B1); PG8_BAR; PG8_SCHED;
;             PG8_LDB(B0, 1, 0); PG8_LDB(B1, 1, 1); PG8_SCHED; PG8_LDA(At, 1, 0); PG8_STAGE(PG8_SA(0, 1), a2 + hstepA, voffA);
;             PG8_WAIT_V(8); PG8_WAIT_L(0); PG8_BAR; PG8_MMA(0, 0, At, B0); PG8_MMA(0, 1, At, B1); PG8_BAR; PG8_SCHED;
	v_mfma_f32_16x16x32_bf16 v[62:65], v[140:143], v[182:185], v[62:65]
	v_mfma_f32_16x16x32_bf16 v[58:61], v[148:151], v[182:185], v[58:61]
	v_mfma_f32_16x16x32_bf16 v[54:57], v[140:143], v[196:199], v[54:57]
	v_mfma_f32_16x16x32_bf16 v[50:53], v[148:151], v[196:199], v[50:53]
	v_mfma_f32_16x16x32_bf16 v[46:49], v[140:143], v[204:207], v[46:49]
	v_mfma_f32_16x16x32_bf16 v[38:41], v[148:151], v[204:207], v[38:41]
	v_mfma_f32_16x16x32_bf16 v[30:33], v[140:143], v[212:215], v[30:33]
	v_mfma_f32_16x16x32_bf16 v[22:25], v[148:151], v[212:215], v[22:25]
	v_mfma_f32_16x16x32_bf16 v[62:65], v[144:147], v[190:193], v[62:65]
	v_mfma_f32_16x16x32_bf16 v[58:61], v[152:155], v[190:193], v[58:61]
	v_mfma_f32_16x16x32_bf16 v[54:57], v[144:147], v[200:203], v[54:57]
	v_mfma_f32_16x16x32_bf16 v[50:53], v[152:155], v[200:203], v[50:53]
	v_mfma_f32_16x16x32_bf16 v[46:49], v[144:147], v[208:211], v[46:49]
	v_mfma_f32_16x16x32_bf16 v[38:41], v[152:155], v[208:211], v[38:41]
	v_mfma_f32_16x16x32_bf16 v[30:33], v[144:147], v[216:219], v[30:33]
	v_mfma_f32_16x16x32_bf16 v[22:25], v[152:155], v[216:219], v[22:25]
	v_mfma_f32_16x16x32_bf16 v[42:45], v[156:159], v[182:185], v[42:45]
	v_mfma_f32_16x16x32_bf16 v[34:37], v[164:167], v[182:185], v[34:37]
	v_mfma_f32_16x16x32_bf16 v[26:29], v[156:159], v[196:199], v[26:29]
	v_mfma_f32_16x16x32_bf16 v[18:21], v[164:167], v[196:199], v[18:21]
	v_mfma_f32_16x16x32_bf16 v[14:17], v[156:159], v[204:207], v[14:17]
	v_mfma_f32_16x16x32_bf16 v[10:13], v[164:167], v[204:207], v[10:13]
	v_mfma_f32_16x16x32_bf16 v[6:9], v[156:159], v[212:215], v[6:9]
	v_mfma_f32_16x16x32_bf16 v[2:5], v[164:167], v[212:215], v[2:5]
	v_mfma_f32_16x16x32_bf16 v[42:45], v[160:163], v[190:193], v[42:45]
	v_mfma_f32_16x16x32_bf16 v[34:37], v[178:181], v[190:193], v[34:37]
	v_mfma_f32_16x16x32_bf16 v[26:29], v[160:163], v[200:203], v[26:29]
	v_mfma_f32_16x16x32_bf16 v[18:21], v[178:181], v[200:203], v[18:21]
	v_mfma_f32_16x16x32_bf16 v[14:17], v[160:163], v[208:211], v[14:17]
	v_mfma_f32_16x16x32_bf16 v[10:13], v[178:181], v[208:211], v[10:13]
	v_mfma_f32_16x16x32_bf16 v[6:9], v[160:163], v[216:219], v[6:9]
	v_mfma_f32_16x16x32_bf16 v[2:5], v[178:181], v[216:219], v[2:5]
	s_barrier
	s_add_i32 s45, 0, 0x18000
	v_add_u32_e32 v139, s45, v136
	s_add_i32 s46, 0, 0x1c000
	ds_read_b128 v[140:143], v139
	ds_read_b128 v[144:147], v139 offset:1024
	ds_read_b128 v[148:151], v139 offset:2048
	ds_read_b128 v[152:155], v139 offset:3072
	v_add_u32_e32 v139, s46, v136
	ds_read_b128 v[156:159], v139
	ds_read_b128 v[160:163], v139 offset:1024
	ds_read_b128 v[164:167], v139 offset:2048
	ds_read_b128 v[178:181], v139 offset:3072
	s_add_u32 s34, s34, 0x100000
	s_addc_u32 s35, s35, 0
	s_mov_b32 m0, s36
	v_lshl_add_u64 v[224:225], s[34:35], 0, v[170:171]
	ds_read_b128 v[182:185], v138 offset:32768
	ds_read_b128 v[190:193], v138 offset:33792
	ds_read_b128 v[196:199], v138 offset:34816
	ds_read_b128 v[200:203], v138 offset:35840
	ds_read_b128 v[204:207], v138 offset:36864
	ds_read_b128 v[208:211], v138 offset:37888
	ds_read_b128 v[212:215], v138 offset:38912
	ds_read_b128 v[216:219], v138 offset:39936
	global_load_lds_dwordx4 v[224:225], off
	v_lshl_add_u64 v[224:225], s[34:35], 0, v[174:175]
	s_mov_b32 m0, s37
	s_nop 0
	global_load_lds_dwordx4 v[224:225], off
	s_waitcnt vmcnt(8)
	s_waitcnt lgkmcnt(0)
	s_barrier
	v_mfma_f32_16x16x32_bf16 v[126:129], v[140:143], v[182:185], v[126:129]
	v_mfma_f32_16x16x32_bf16 v[122:125], v[148:151], v[182:185], v[122:125]
	v_mfma_f32_16x16x32_bf16 v[118:121], v[140:143], v[196:199], v[118:121]
	v_mfma_f32_16x16x32_bf16 v[114:117], v[148:151], v[196:199], v[114:117]
	v_mfma_f32_16x16x32_bf16 v[110:113], v[140:143], v[204:207], v[110:113]
	v_mfma_f32_16x16x32_bf16 v[102:105], v[148:151], v[204:207], v[102:105]
	v_mfma_f32_16x16x32_bf16 v[94:97], v[140:143], v[212:215], v[94:97]
	v_mfma_f32_16x16x32_bf16 v[86:89], v[148:151], v[212:215], v[86:89]
	v_mfma_f32_16x16x32_bf16 v[126:129], v[144:147], v[190:193], v[126:129]
	v_mfma_f32_16x16x32_bf16 v[122:125], v[152:155], v[190:193], v[122:125]
	v_mfma_f32_16x16x32_bf16 v[118:121], v[144:147], v[200:203], v[118:121]
	v_mfma_f32_16x16x32_bf16 v[114:117], v[152:155], v[200:203], v[114:117]
	v_mfma_f32_16x16x32_bf16 v[110:113], v[144:147], v[208:211], v[110:113]
	v_mfma_f32_16x16x32_bf16 v[102:105], v[152:155], v[208:211], v[102:105]
	v_mfma_f32_16x16x32_bf16 v[94:97], v[144:147], v[216:219], v[94:97]
	v_mfma_f32_16x16x32_bf16 v[86:89], v[152:155], v[216:219], v[86:89]
	v_mfma_f32_16x16x32_bf16 v[106:109], v[156:159], v[182:185], v[106:109]
	v_mfma_f32_16x16x32_bf16 v[98:101], v[164:167], v[182:185], v[98:101]
	v_mfma_f32_16x16x32_bf16 v[90:93], v[156:159], v[196:199], v[90:93]
	v_mfma_f32_16x16x32_bf16 v[82:85], v[164:167], v[196:199], v[82:85]
	v_mfma_f32_16x16x32_bf16 v[78:81], v[156:159], v[204:207], v[78:81]
	v_mfma_f32_16x16x32_bf16 v[74:77], v[164:167], v[204:207], v[74:77]
	v_mfma_f32_16x16x32_bf16 v[70:73], v[156:159], v[212:215], v[70:73]
	v_mfma_f32_16x16x32_bf16 v[66:69], v[164:167], v[212:215], v[66:69]
	v_mfma_f32_16x16x32_bf16 v[106:109], v[160:163], v[190:193], v[106:109]
	v_mfma_f32_16x16x32_bf16 v[98:101], v[178:181], v[190:193], v[98:101]
	v_mfma_f32_16x16x32_bf16 v[90:93], v[160:163], v[200:203], v[90:93]
	v_mfma_f32_16x16x32_bf16 v[82:85], v[178:181], v[200:203], v[82:85]
	v_mfma_f32_16x16x32_bf16 v[78:81], v[160:163], v[208:211], v[78:81]
	v_mfma_f32_16x16x32_bf16 v[74:77], v[178:181], v[208:211], v[74:77]
	v_mfma_f32_16x16x32_bf16 v[70:73], v[160:163], v[216:219], v[70:73]
	v_mfma_f32_16x16x32_bf16 v[66:69], v[178:181], v[216:219], v[66:69]
	s_barrier
; #define PG8_STAGE(bufoff, gbase, voff) do { _Pragma("unroll") for (int _i = 0; _i < 2; ++_i) \
;         __builtin_amdgcn_global_load_lds((const unsigned*)((const char*)(gbase) + (voff)[_i]), (PG8_LAS unsigned*)(lds + (bufoff) + ldsw + _i * 8192), 16, 0, 0); } while (0)
; #define PG8_LDA(dst, b, h) do { _Pragma("unroll") for (int m = 0; m < 4; ++m) _Pragma("unroll") for (int k = 0; k < 2; ++k) dst[m][k] = *(const PG8_LAS bf16x8*)(lds + PG8_SA(b, h) + aoff + m * 2048 + k * 1024); } while (0)
; #define PG8_MMA(ai, bj, At, Bt) do { __builtin_amdgcn_s_setprio(1); _Pragma("unroll") for (int m = 0; m < 4; ++m) _Pragma("unroll") for (int n = 0; n < 2; ++n) _Pragma("unroll") for (int k = 0; k < 2; ++k) \
;         acc[ai][bj][m][n] = __builtin_amdgcn_mfma_f32_16x16x32_bf16(Bt[n][k], At[m][k], acc[ai][bj][m][n], 0, 0, 0); __builtin_amdgcn_s_setprio(0); } while (0)
; #define PG8_WAIT_V(n) asm volatile("s_waitcnt vmcnt(" #n ")" ::: "memory")
; #define PG8_WAIT_L(n) asm volatile("s_waitcnt lgkmcnt(" #n ")" ::: "memory")
; #define PG8_BAR __builtin_amdgcn_s_barrier()
; #define PG8_SCHED __builtin_amdgcn_sched_barrier(0)
; template <class Epi, class Sched, bool ALIGN_EPI = false, bool SP2 = false, bool A_TILED = false, bool B_TILED = false>
; __device__ __forceinline__ void gemm_phase(PG8_LAS unsigned char* lds, const Gemm g, const Sched& S, const Epi& E) {
;     ...
;         for (int t = 0; t < nt; t += 2) {
;     ...
;             PG8_LDA(At, 1, 1); PG8_STAGE(PG8_SB(1, 0), b3, voffB); PG8_STAGE(PG8_SB(1, 1), b3 + hstepB, voffB); PG8_STAGE(PG8_SA(1, 0), a3, voffA);
;             PG8_WAIT_V(8); PG8_WAIT_L(0); PG8_BAR; PG8_MMA(1, 0, At, B0); PG8_MMA(1, 1, At, B1); PG8_BAR; PG8_SCHED;
	s_add_i32 s34, s45, s28
	v_lshl_add_u64 v[168:169], v[168:169], 0, s[8:9]
	s_mov_b32 m0, s34
	ds_read_b128 v[182:185], v138 offset:49152
	ds_read_b128 v[190:193], v138 offset:50176
	ds_read_b128 v[196:199], v138 offset:51200
	ds_read_b128 v[200:203], v138 offset:52224
	ds_read_b128 v[204:207], v138 offset:53248
	ds_read_b128 v[208:211], v138 offset:54272
	ds_read_b128 v[212:215], v138 offset:55296
	ds_read_b128 v[216:219], v138 offset:56320
	global_load_lds_dwordx4 v[168:169], off
	s_add_i32 m0, s34, 0x2000
	s_add_u32 s30, s30, 0x100080
	v_lshl_add_u64 v[168:169], v[186:187], 0, s[8:9]
	s_addc_u32 s31, s31, 0
	s_add_i32 s34, s46, s28
	global_load_lds_dwordx4 v[168:169], off
	v_lshl_add_u64 v[168:169], s[30:31], 0, v[172:173]
	s_mov_b32 m0, s34
	s_nop 0
	global_load_lds_dwordx4 v[168:169], off
	v_lshl_add_u64 v[168:169], s[30:31], 0, v[176:177]
	s_add_i32 m0, s34, 0x2000
	s_nop 0
	global_load_lds_dwordx4 v[168:169], off
	v_lshl_add_u64 v[168:169], v[220:221], 0, s[8:9]
	s_mov_b32 m0, s38
	s_nop 0
	global_load_lds_dwordx4 v[168:169], off
	v_lshl_add_u64 v[168:169], v[222:223], 0, s[8:9]
	s_mov_b32 m0, s39
	s_nop 0
	global_load_lds_dwordx4 v[168:169], off
	s_waitcnt vmcnt(8)
	s_waitcnt lgkmcnt(0)
	s_barrier
	v_mfma_f32_16x16x32_bf16 v[62:65], v[140:143], v[182:185], v[62:65]
	v_mfma_f32_16x16x32_bf16 v[58:61], v[148:151], v[182:185], v[58:61]
	v_mfma_f32_16x16x32_bf16 v[54:57], v[140:143], v[196:199], v[54:57]
	v_mfma_f32_16x16x32_bf16 v[50:53], v[148:151], v[196:199], v[50:53]
	v_mfma_f32_16x16x32_bf16 v[46:49], v[140:143], v[204:207], v[46:49]
	v_mfma_f32_16x16x32_bf16 v[38:41], v[148:151], v[204:207], v[38:41]
	v_mfma_f32_16x16x32_bf16 v[30:33], v[140:143], v[212:215], v[30:33]
	v_mfma_f32_16x16x32_bf16 v[22:25], v[148:151], v[212:215], v[22:25]
	v_mfma_f32_16x16x32_bf16 v[62:65], v[144:147], v[190:193], v[62:65]
	v_mfma_f32_16x16x32_bf16 v[58:61], v[152:155], v[190:193], v[58:61]
	v_mfma_f32_16x16x32_bf16 v[54:57], v[144:147], v[200:203], v[54:57]
	v_mfma_f32_16x16x32_bf16 v[50:53], v[152:155], v[200:203], v[50:53]
	v_mfma_f32_16x16x32_bf16 v[46:49], v[144:147], v[208:211], v[46:49]
	v_mfma_f32_16x16x32_bf16 v[38:41], v[152:155], v[208:211], v[38:41]
	v_mfma_f32_16x16x32_bf16 v[30:33], v[144:147], v[216:219], v[30:33]
	v_mfma_f32_16x16x32_bf16 v[22:25], v[152:155], v[216:219], v[22:25]
	v_mfma_f32_16x16x32_bf16 v[42:45], v[156:159], v[182:185], v[42:45]
	v_mfma_f32_16x16x32_bf16 v[34:37], v[164:167], v[182:185], v[34:37]
	v_mfma_f32_16x16x32_bf16 v[26:29], v[156:159], v[196:199], v[26:29]
	v_mfma_f32_16x16x32_bf16 v[18:21], v[164:167], v[196:199], v[18:21]
	v_mfma_f32_16x16x32_bf16 v[14:17], v[156:159], v[204:207], v[14:17]
	v_mfma_f32_16x16x32_bf16 v[10:13], v[164:167], v[204:207], v[10:13]
	v_mfma_f32_16x16x32_bf16 v[6:9], v[156:159], v[212:215], v[6:9]
	v_mfma_f32_16x16x32_bf16 v[2:5], v[164:167], v[212:215], v[2:5]
	v_mfma_f32_16x16x32_bf16 v[42:45], v[160:163], v[190:193], v[42:45]
	v_mfma_f32_16x16x32_bf16 v[34:37], v[178:181], v[190:193], v[34:37]
	v_mfma_f32_16x16x32_bf16 v[26:29], v[160:163], v[200:203], v[26:29]
	v_mfma_f32_16x16x32_bf16 v[18:21], v[178:181], v[200:203], v[18:21]
	v_mfma_f32_16x16x32_bf16 v[14:17], v[160:163], v[208:211], v[14:17]
	v_mfma_f32_16x16x32_bf16 v[10:13], v[178:181], v[208:211], v[10:13]
	v_mfma_f32_16x16x32_bf16 v[6:9], v[160:163], v[216:219], v[6:9]
	v_mfma_f32_16x16x32_bf16 v[2:5], v[178:181], v[216:219], v[2:5]
	s_add_i32 s44, s44, 2
	s_add_u32 s26, s26, 0x100
	s_addc_u32 s27, s27, 0
	s_add_u32 s42, s42, 0x100
	s_addc_u32 s43, s43, 0
	s_cmp_gt_u32 s44, 5
	s_barrier
	s_cbranch_scc0 .LBB0_905
	s_and_b64 vcc, exec, s[10:11]
	s_cbranch_vccz .LBB0_908
	s_barrier

; #define PG8_STAGE(bufoff, gbase, voff) do { _Pragma("unroll") for (int _i = 0; _i < 2; ++_i) \
;         __builtin_amdgcn_global_load_lds((const unsigned*)((const char*)(gbase) + (voff)[_i]), (PG8_LAS unsigned*)(lds + (bufoff) + ldsw + _i * 8192), 16, 0, 0); } while (0)
; #define PG8_LDA(dst, b, h) do { _Pragma("unroll") for (int m = 0; m < 4; ++m) _Pragma("unroll") for (int k = 0; k < 2; ++k) dst[m][k] = *(const PG8_LAS bf16x8*)(lds + PG8_SA(b, h) + aoff + m * 2048 + k * 1024); } while (0)
; #define PG8_LDB(dst, b, h) do { _Pragma("unroll") for (int n = 0; n < 2; ++n) _Pragma("unroll") for (int k = 0; k < 2; ++k) dst[n][k] = *(const PG8_LAS bf16x8*)(lds + PG8_SB(b, h) + boff + n * 2048 + k * 1024); } while (0)
; #define PG8_MMA(ai, bj, At, Bt) do { __builtin_amdgcn_s_setprio(1); _Pragma("unroll") for (int m = 0; m < 4; ++m) _Pragma("unroll") for (int n = 0; n < 2; ++n) _Pragma("unroll") for (int k = 0; k < 2; ++k) \
;         acc[ai][bj][m][n] = __builtin_amdgcn_mfma_f32_16x16x32_bf16(Bt[n][k], At[m][k], acc[ai][bj][m][n], 0, 0, 0); __builtin_amdgcn_s_setprio(0); } while (0)
; #define PG8_WAIT_V(n) asm volatile("s_waitcnt vmcnt(" #n ")" ::: "memory")
; #define PG8_WAIT_L(n) asm volatile("s_waitcnt lgkmcnt(" #n ")" ::: "memory")
; #define PG8_BAR __builtin_amdgcn_s_barrier()
; #define PG8_SCHED __builtin_amdgcn_sched_barrier(0)
; template <class Epi, class Sched, bool ALIGN_EPI = false, bool SP2 = false, bool A_TILED = false, bool B_TILED = false>
; __device__ __forceinline__ void gemm_phase(PG8_LAS unsigned char* lds, const Gemm g, const Sched& S, const Epi& E) {
;     ...
;             const char* a1 = cA + (size_t)(t + 1) * kstepA;
;             const char* a2 = last ? nA : cA + (size_t)(t + 2) * kstepA; const char* b2 = last ? nB : cB + (size_t)(t + 2) * kstepB;
;             const char* a3 = a2 + kstepA; const char* b3 = b2 + kstepB;
;             if (last && has_next) S.a_ready(nxt);
;             if constexpr (SP2) {
;             PG8_LDB(B0, 0, 0); PG8_LDB(B1, 0, 1); PG8_SCHED; PG8_LDA(At, 0, 0); PG8_STAGE(PG8_SA(1, 1), a1 + hstepA, voffA);
;             PG8_WAIT_V(8); PG8_WAIT_L(0); PG8_BAR; PG8_MMA(0, 0, At, B0); PG8_MMA(0, 1, At, B1); PG8_BAR; PG8_SCHED;
;             PG8_LDA(At, 0, 1); PG8_STAGE(PG8_SB(0, 0), b2, voffB); PG8_STAGE(PG8_SB(0, 1), b2 + hstepB, voffB); PG8_STAGE(PG8_SA(0, 0), a2, voffA);
.LBB0_1069:
	ds_read_b128 v[142:145], v161
	ds_read_b128 v[164:167], v161 offset:1024
	ds_read_b128 v[168:171], v161 offset:2048
	ds_read_b128 v[172:175], v161 offset:3072
	ds_read_b128 v[176:179], v162
	ds_read_b128 v[180:183], v162 offset:1024
	ds_read_b128 v[184:187], v162 offset:2048
	ds_read_b128 v[190:193], v162 offset:3072
	s_add_u32 s36, s34, 0x4000
	s_addc_u32 s37, s35, 0
	s_cmpk_eq_i32 s67, 0xa8
	s_cselect_b32 s40, s28, s36
	s_cselect_b32 s41, s29, s37
	s_cselect_b32 s38, s30, s65
	s_cselect_b32 s39, s31, s66
	s_add_u32 s36, s40, 0x8000
	s_addc_u32 s37, s41, 0
	v_lshl_add_u64 v[146:147], s[34:35], 0, v[138:139]
	s_add_i32 m0, s46, 0xc000
	ds_read_b128 v[194:197], v163
	ds_read_b128 v[198:201], v163 offset:1024
	ds_read_b128 v[202:205], v163 offset:2048
	ds_read_b128 v[206:209], v163 offset:3072
	ds_read_b128 v[210:213], v163 offset:4096
	ds_read_b128 v[214:217], v163 offset:5120
	ds_read_b128 v[218:221], v163 offset:6144
	ds_read_b128 v[222:225], v163 offset:7168
	global_load_lds_dwordx4 v[146:147], off
	v_lshl_add_u64 v[146:147], s[34:35], 0, v[140:141]
	s_add_i32 m0, s46, 0xe000
	s_nop 0
	global_load_lds_dwordx4 v[146:147], off
	s_waitcnt vmcnt(8)
	s_waitcnt lgkmcnt(0)
	s_barrier
	v_mfma_f32_16x16x32_bf16 v[126:129], v[142:145], v[194:197], v[126:129]
	v_mfma_f32_16x16x32_bf16 v[122:125], v[168:171], v[194:197], v[122:125]
	v_mfma_f32_16x16x32_bf16 v[110:113], v[142:145], v[202:205], v[110:113]
	v_mfma_f32_16x16x32_bf16 v[106:109], v[168:171], v[202:205], v[106:109]
	v_mfma_f32_16x16x32_bf16 v[94:97], v[142:145], v[210:213], v[94:97]
	v_mfma_f32_16x16x32_bf16 v[90:93], v[168:171], v[210:213], v[90:93]
	v_mfma_f32_16x16x32_bf16 v[78:81], v[142:145], v[218:221], v[78:81]
	v_mfma_f32_16x16x32_bf16 v[74:77], v[168:171], v[218:221], v[74:77]
	v_mfma_f32_16x16x32_bf16 v[126:129], v[164:167], v[198:201], v[126:129]
	v_mfma_f32_16x16x32_bf16 v[122:125], v[172:175], v[198:201], v[122:125]
	v_mfma_f32_16x16x32_bf16 v[110:113], v[164:167], v[206:209], v[110:113]
	v_mfma_f32_16x16x32_bf16 v[106:109], v[172:175], v[206:209], v[106:109]
	v_mfma_f32_16x16x32_bf16 v[94:97], v[164:167], v[214:217], v[94:97]
	v_mfma_f32_16x16x32_bf16 v[90:93], v[172:175], v[214:217], v[90:93]
	v_mfma_f32_16x16x32_bf16 v[78:81], v[164:167], v[222:225], v[78:81]
	v_mfma_f32_16x16x32_bf16 v[74:77], v[172:175], v[222:225], v[74:77]
	v_mfma_f32_16x16x32_bf16 v[118:121], v[176:179], v[194:197], v[118:121]
	v_mfma_f32_16x16x32_bf16 v[114:117], v[184:187], v[194:197], v[114:117]
	v_mfma_f32_16x16x32_bf16 v[102:105], v[176:179], v[202:205], v[102:105]
	v_mfma_f32_16x16x32_bf16 v[98:101], v[184:187], v[202:205], v[98:101]
	v_mfma_f32_16x16x32_bf16 v[86:89], v[176:179], v[210:213], v[86:89]
	v_mfma_f32_16x16x32_bf16 v[82:85], v[184:187], v[210:213], v[82:85]
	v_mfma_f32_16x16x32_bf16 v[70:73], v[176:179], v[218:221], v[70:73]
	v_mfma_f32_16x16x32_bf16 v[66:69], v[184:187], v[218:221], v[66:69]
	v_mfma_f32_16x16x32_bf16 v[118:121], v[180:183], v[198:201], v[118:121]
	v_mfma_f32_16x16x32_bf16 v[114:117], v[190:193], v[198:201], v[114:117]
	v_mfma_f32_16x16x32_bf16 v[102:105], v[180:183], v[206:209], v[102:105]
	v_mfma_f32_16x16x32_bf16 v[98:101], v[190:193], v[206:209], v[98:101]
	v_mfma_f32_16x16x32_bf16 v[86:89], v[180:183], v[214:217], v[86:89]
	v_mfma_f32_16x16x32_bf16 v[82:85], v[190:193], v[214:217], v[82:85]
	v_mfma_f32_16x16x32_bf16 v[70:73], v[180:183], v[222:225], v[70:73]
	v_mfma_f32_16x16x32_bf16 v[66:69], v[190:193], v[222:225], v[66:69]
	s_barrier
	s_add_i32 s68, s58, s45
	v_lshl_add_u64 v[146:147], s[38:39], 0, v[134:135]
	s_mov_b32 m0, s68
	ds_read_b128 v[194:197], v163 offset:16384
	ds_read_b128 v[198:201], v163 offset:17408
	ds_read_b128 v[202:205], v163 offset:18432
	ds_read_b128 v[206:209], v163 offset:19456
	ds_read_b128 v[210:213], v163 offset:20480
	ds_read_b128 v[214:217], v163 offset:21504
	ds_read_b128 v[218:221], v163 offset:22528
	ds_read_b128 v[222:225], v163 offset:23552
	global_load_lds_dwordx4 v[146:147], off
	s_add_i32 m0, s68, 0x2000
	s_add_u32 s68, s38, 0x2b0000
	v_lshl_add_u64 v[226:227], s[38:39], 0, v[136:137]
	s_addc_u32 s69, s39, 0
	s_add_i32 s70, s59, s45
	global_load_lds_dwordx4 v[226:227], off
	v_lshl_add_u64 v[228:229], s[68:69], 0, v[134:135]
	s_mov_b32 m0, s70
	s_nop 0
	global_load_lds_dwordx4 v[228:229], off
	v_lshl_add_u64 v[228:229], s[68:69], 0, v[136:137]
	s_add_i32 m0, s70, 0x2000
	s_nop 0
	global_load_lds_dwordx4 v[228:229], off
	v_lshl_add_u64 v[228:229], s[40:41], 0, v[130:131]
	s_mov_b32 m0, s46
	s_nop 0
	global_load_lds_dwordx4 v[228:229], off
	v_lshl_add_u64 v[228:229], s[40:41], 0, v[132:133]
	s_mov_b32 m0, s47
	s_nop 0
	global_load_lds_dwordx4 v[228:229], off
	s_waitcnt vmcnt(8)
	s_waitcnt lgkmcnt(0)
	s_barrier
; #define PG8_STAGE(bufoff, gbase, voff) do { _Pragma("unroll") for (int _i = 0; _i < 2; ++_i) \
;         __builtin_amdgcn_global_load_lds((const unsigned*)((const char*)(gbase) + (voff)[_i]), (PG8_LAS unsigned*)(lds + (bufoff) + ldsw + _i * 8192), 16, 0, 0); } while (0)
; #define PG8_LDA(dst, b, h) do { _Pragma("unroll") for (int m = 0; m < 4; ++m) _Pragma("unroll") for (int k = 0; k < 2; ++k) dst[m][k] = *(const PG8_LAS bf16x8*)(lds + PG8_SA(b, h) + aoff + m * 2048 + k * 1024); } while (0)
; #define PG8_LDB(dst, b, h) do { _Pragma("unroll") for (int n = 0; n < 2; ++n) _Pragma("unroll") for (int k = 0; k < 2; ++k) dst[n][k] = *(const PG8_LAS bf16x8*)(lds + PG8_SB(b, h) + boff + n * 2048 + k * 1024); } while (0)
; #define PG8_MMA(ai, bj, At, Bt) do { __builtin_amdgcn_s_setprio(1); _Pragma("unroll") for (int m = 0; m < 4; ++m) _Pragma("unroll") for (int n = 0; n < 2; ++n) _Pragma("unroll") for (int k = 0; k < 2; ++k) \
;         acc[ai][bj][m][n] = __builtin_amdgcn_mfma_f32_16x16x32_bf16(Bt[n][k], At[m][k], acc[ai][bj][m][n], 0, 0, 0); __builtin_amdgcn_s_setprio(0); } while (0)
; #define PG8_WAIT_V(n) asm volatile("s_waitcnt vmcnt(" #n ")" ::: "memory")
; #define PG8_WAIT_L(n) asm volatile("s_waitcnt lgkmcnt(" #n ")" ::: "memory")
; #define PG8_BAR __builtin_amdgcn_s_barrier()
; #define PG8_SCHED __builtin_amdgcn_sched_barrier(0)
; template <class Epi, class Sched, bool ALIGN_EPI = false, bool SP2 = false, bool A_TILED = false, bool B_TILED = false>
; __device__ __forceinline__ void gemm_phase(PG8_LAS unsigned char* lds, const Gemm g, const Sched& S, const Epi& E) {
;     ...
;             PG8_WAIT_V(8); PG8_WAIT_L(0); PG8_BAR; PG8_MMA(1, 0, At, B0); PG8_MMA(1, 1, At, B1); PG8_BAR; PG8_SCHED;
;             PG8_LDB(B0, 1, 0); PG8_LDB(B1, 1, 1); PG8_SCHED; PG8_LDA(At, 1, 0); PG8_STAGE(PG8_SA(0, 1), a2 + hstepA, voffA);
;             PG8_WAIT_V(8); PG8_WAIT_L(0); PG8_BAR; PG8_MMA(0, 0, At, B0); PG8_MMA(0, 1, At, B1); PG8_BAR; PG8_SCHED;
	v_mfma_f32_16x16x32_bf16 v[62:65], v[142:145], v[194:197], v[62:65]
	v_mfma_f32_16x16x32_bf16 v[58:61], v[168:171], v[194:197], v[58:61]
	v_mfma_f32_16x16x32_bf16 v[46:49], v[142:145], v[202:205], v[46:49]
	v_mfma_f32_16x16x32_bf16 v[42:45], v[168:171], v[202:205], v[42:45]
	v_mfma_f32_16x16x32_bf16 v[30:33], v[142:145], v[210:213], v[30:33]
	v_mfma_f32_16x16x32_bf16 v[26:29], v[168:171], v[210:213], v[26:29]
	v_mfma_f32_16x16x32_bf16 v[14:17], v[142:145], v[218:221], v[14:17]
	v_mfma_f32_16x16x32_bf16 v[10:13], v[168:171], v[218:221], v[10:13]
	v_mfma_f32_16x16x32_bf16 v[62:65], v[164:167], v[198:201], v[62:65]
	v_mfma_f32_16x16x32_bf16 v[58:61], v[172:175], v[198:201], v[58:61]
	v_mfma_f32_16x16x32_bf16 v[46:49], v[164:167], v[206:209], v[46:49]
	v_mfma_f32_16x16x32_bf16 v[42:45], v[172:175], v[206:209], v[42:45]
	v_mfma_f32_16x16x32_bf16 v[30:33], v[164:167], v[214:217], v[30:33]
	v_mfma_f32_16x16x32_bf16 v[26:29], v[172:175], v[214:217], v[26:29]
	v_mfma_f32_16x16x32_bf16 v[14:17], v[164:167], v[222:225], v[14:17]
	v_mfma_f32_16x16x32_bf16 v[10:13], v[172:175], v[222:225], v[10:13]
	v_mfma_f32_16x16x32_bf16 v[54:57], v[176:179], v[194:197], v[54:57]
	v_mfma_f32_16x16x32_bf16 v[50:53], v[184:187], v[194:197], v[50:53]
	v_mfma_f32_16x16x32_bf16 v[38:41], v[176:179], v[202:205], v[38:41]
	v_mfma_f32_16x16x32_bf16 v[34:37], v[184:187], v[202:205], v[34:37]
	v_mfma_f32_16x16x32_bf16 v[22:25], v[176:179], v[210:213], v[22:25]
	v_mfma_f32_16x16x32_bf16 v[18:21], v[184:187], v[210:213], v[18:21]
	v_mfma_f32_16x16x32_bf16 v[6:9], v[176:179], v[218:221], v[6:9]
	v_mfma_f32_16x16x32_bf16 v[2:5], v[184:187], v[218:221], v[2:5]
	v_mfma_f32_16x16x32_bf16 v[54:57], v[180:183], v[198:201], v[54:57]
	v_mfma_f32_16x16x32_bf16 v[50:53], v[190:193], v[198:201], v[50:53]
	v_mfma_f32_16x16x32_bf16 v[38:41], v[180:183], v[206:209], v[38:41]
	v_mfma_f32_16x16x32_bf16 v[34:37], v[190:193], v[206:209], v[34:37]
	v_mfma_f32_16x16x32_bf16 v[22:25], v[180:183], v[214:217], v[22:25]
	v_mfma_f32_16x16x32_bf16 v[18:21], v[190:193], v[214:217], v[18:21]
	v_mfma_f32_16x16x32_bf16 v[6:9], v[180:183], v[222:225], v[6:9]
	v_mfma_f32_16x16x32_bf16 v[2:5], v[190:193], v[222:225], v[2:5]
	s_barrier
	s_add_i32 s68, 0, 0x18000
	s_add_i32 s69, 0, 0x1c000
	v_add_u32_e32 v172, s68, v159
	v_add_u32_e32 v188, s69, v159
	ds_read_b128 v[142:145], v172
	ds_read_b128 v[164:167], v172 offset:1024
	ds_read_b128 v[168:171], v172 offset:2048
	ds_read_b128 v[172:175], v172 offset:3072
	ds_read_b128 v[176:179], v188
	ds_read_b128 v[180:183], v188 offset:1024
	ds_read_b128 v[184:187], v188 offset:2048
	ds_read_b128 v[190:193], v188 offset:3072
	s_add_u32 s40, s40, 0x4000
	s_addc_u32 s41, s41, 0
	s_mov_b32 m0, s52
	v_lshl_add_u64 v[228:229], s[40:41], 0, v[130:131]
	ds_read_b128 v[194:197], v163 offset:32768
	ds_read_b128 v[198:201], v163 offset:33792
	ds_read_b128 v[202:205], v163 offset:34816
	ds_read_b128 v[206:209], v163 offset:35840
	ds_read_b128 v[210:213], v163 offset:36864
	ds_read_b128 v[214:217], v163 offset:37888
	ds_read_b128 v[218:221], v163 offset:38912
	ds_read_b128 v[222:225], v163 offset:39936
	global_load_lds_dwordx4 v[228:229], off
	v_lshl_add_u64 v[228:229], s[40:41], 0, v[132:133]
	s_mov_b32 m0, s53
	s_nop 0
	global_load_lds_dwordx4 v[228:229], off
	s_waitcnt vmcnt(8)
	s_waitcnt lgkmcnt(0)
	s_barrier
	v_mfma_f32_16x16x32_bf16 v[126:129], v[142:145], v[194:197], v[126:129]
	v_mfma_f32_16x16x32_bf16 v[122:125], v[168:171], v[194:197], v[122:125]
	v_mfma_f32_16x16x32_bf16 v[110:113], v[142:145], v[202:205], v[110:113]
	v_mfma_f32_16x16x32_bf16 v[106:109], v[168:171], v[202:205], v[106:109]
	v_mfma_f32_16x16x32_bf16 v[94:97], v[142:145], v[210:213], v[94:97]
	v_mfma_f32_16x16x32_bf16 v[90:93], v[168:171], v[210:213], v[90:93]
	v_mfma_f32_16x16x32_bf16 v[78:81], v[142:145], v[218:221], v[78:81]
	v_mfma_f32_16x16x32_bf16 v[74:77], v[168:171], v[218:221], v[74:77]
	v_mfma_f32_16x16x32_bf16 v[126:129], v[164:167], v[198:201], v[126:129]
	v_mfma_f32_16x16x32_bf16 v[122:125], v[172:175], v[198:201], v[122:125]
	v_mfma_f32_16x16x32_bf16 v[110:113], v[164:167], v[206:209], v[110:113]
	v_mfma_f32_16x16x32_bf16 v[106:109], v[172:175], v[206:209], v[106:109]
	v_mfma_f32_16x16x32_bf16 v[94:97], v[164:167], v[214:217], v[94:97]
	v_mfma_f32_16x16x32_bf16 v[90:93], v[172:175], v[214:217], v[90:93]
	v_mfma_f32_16x16x32_bf16 v[78:81], v[164:167], v[222:225], v[78:81]
	v_mfma_f32_16x16x32_bf16 v[74:77], v[172:175], v[222:225], v[74:77]
	v_mfma_f32_16x16x32_bf16 v[118:121], v[176:179], v[194:197], v[118:121]
	v_mfma_f32_16x16x32_bf16 v[114:117], v[184:187], v[194:197], v[114:117]
	v_mfma_f32_16x16x32_bf16 v[102:105], v[176:179], v[202:205], v[102:105]
	v_mfma_f32_16x16x32_bf16 v[98:101], v[184:187], v[202:205], v[98:101]
	v_mfma_f32_16x16x32_bf16 v[86:89], v[176:179], v[210:213], v[86:89]
	v_mfma_f32_16x16x32_bf16 v[82:85], v[184:187], v[210:213], v[82:85]
	v_mfma_f32_16x16x32_bf16 v[70:73], v[176:179], v[218:221], v[70:73]
	v_mfma_f32_16x16x32_bf16 v[66:69], v[184:187], v[218:221], v[66:69]
	v_mfma_f32_16x16x32_bf16 v[118:121], v[180:183], v[198:201], v[118:121]
	v_mfma_f32_16x16x32_bf16 v[114:117], v[190:193], v[198:201], v[114:117]
	v_mfma_f32_16x16x32_bf16 v[102:105], v[180:183], v[206:209], v[102:105]
	v_mfma_f32_16x16x32_bf16 v[98:101], v[190:193], v[206:209], v[98:101]
	v_mfma_f32_16x16x32_bf16 v[86:89], v[180:183], v[214:217], v[86:89]
	v_mfma_f32_16x16x32_bf16 v[82:85], v[190:193], v[214:217], v[82:85]
	v_mfma_f32_16x16x32_bf16 v[70:73], v[180:183], v[222:225], v[70:73]
	v_mfma_f32_16x16x32_bf16 v[66:69], v[190:193], v[222:225], v[66:69]
	s_barrier
; #define PG8_STAGE(bufoff, gbase, voff) do { _Pragma("unroll") for (int _i = 0; _i < 2; ++_i) \
;         __builtin_amdgcn_global_load_lds((const unsigned*)((const char*)(gbase) + (voff)[_i]), (PG8_LAS unsigned*)(lds + (bufoff) + ldsw + _i * 8192), 16, 0, 0); } while (0)
; #define PG8_LDA(dst, b, h) do { _Pragma("unroll") for (int m = 0; m < 4; ++m) _Pragma("unroll") for (int k = 0; k < 2; ++k) dst[m][k] = *(const PG8_LAS bf16x8*)(lds + PG8_SA(b, h) + aoff + m * 2048 + k * 1024); } while (0)
; #define PG8_MMA(ai, bj, At, Bt) do { __builtin_amdgcn_s_setprio(1); _Pragma("unroll") for (int m = 0; m < 4; ++m) _Pragma("unroll") for (int n = 0; n < 2; ++n) _Pragma("unroll") for (int k = 0; k < 2; ++k) \
;         acc[ai][bj][m][n] = __builtin_amdgcn_mfma_f32_16x16x32_bf16(Bt[n][k], At[m][k], acc[ai][bj][m][n], 0, 0, 0); __builtin_amdgcn_s_setprio(0); } while (0)
; #define PG8_WAIT_V(n) asm volatile("s_waitcnt vmcnt(" #n ")" ::: "memory")
; #define PG8_WAIT_L(n) asm volatile("s_waitcnt lgkmcnt(" #n ")" ::: "memory")
; #define PG8_BAR __builtin_amdgcn_s_barrier()
; #define PG8_SCHED __builtin_amdgcn_sched_barrier(0)
; template <class Epi, class Sched, bool ALIGN_EPI = false, bool SP2 = false, bool A_TILED = false, bool B_TILED = false>
; __device__ __forceinline__ void gemm_phase(PG8_LAS unsigned char* lds, const Gemm g, const Sched& S, const Epi& E) {
;     ...
;         for (int t = 0; t < nt; t += 2) {
;     ...
;             PG8_LDA(At, 1, 1); PG8_STAGE(PG8_SB(1, 0), b3, voffB); PG8_STAGE(PG8_SB(1, 1), b3 + hstepB, voffB); PG8_STAGE(PG8_SA(1, 0), a3, voffA);
;             PG8_WAIT_V(8); PG8_WAIT_L(0); PG8_BAR; PG8_MMA(1, 0, At, B0); PG8_MMA(1, 1, At, B1); PG8_BAR; PG8_SCHED;
	s_add_i32 s40, s68, s45
	v_lshl_add_u64 v[146:147], v[146:147], 0, s[16:17]
	s_mov_b32 m0, s40
	ds_read_b128 v[194:197], v163 offset:49152
	ds_read_b128 v[198:201], v163 offset:50176
	ds_read_b128 v[202:205], v163 offset:51200
	ds_read_b128 v[206:209], v163 offset:52224
	ds_read_b128 v[210:213], v163 offset:53248
	ds_read_b128 v[214:217], v163 offset:54272
	ds_read_b128 v[218:221], v163 offset:55296
	ds_read_b128 v[222:225], v163 offset:56320
	global_load_lds_dwordx4 v[146:147], off
	s_add_i32 m0, s40, 0x2000
	s_add_u32 s38, s38, 0x2b0080
	v_lshl_add_u64 v[146:147], v[226:227], 0, s[16:17]
	s_addc_u32 s39, s39, 0
	s_add_i32 s40, s69, s45
	global_load_lds_dwordx4 v[146:147], off
	v_lshl_add_u64 v[146:147], s[38:39], 0, v[134:135]
	s_mov_b32 m0, s40
	s_nop 0
	global_load_lds_dwordx4 v[146:147], off
	v_lshl_add_u64 v[146:147], s[38:39], 0, v[136:137]
	s_add_i32 m0, s40, 0x2000
	s_nop 0
	global_load_lds_dwordx4 v[146:147], off
	v_lshl_add_u64 v[146:147], s[36:37], 0, v[130:131]
	s_mov_b32 m0, s54
	s_nop 0
	global_load_lds_dwordx4 v[146:147], off
	v_lshl_add_u64 v[146:147], s[36:37], 0, v[132:133]
	s_mov_b32 m0, s55
	s_nop 0
	global_load_lds_dwordx4 v[146:147], off
	s_waitcnt vmcnt(8)
	s_waitcnt lgkmcnt(0)
	s_barrier
	v_mfma_f32_16x16x32_bf16 v[62:65], v[142:145], v[194:197], v[62:65]
	v_mfma_f32_16x16x32_bf16 v[58:61], v[168:171], v[194:197], v[58:61]
	v_mfma_f32_16x16x32_bf16 v[46:49], v[142:145], v[202:205], v[46:49]
	v_mfma_f32_16x16x32_bf16 v[42:45], v[168:171], v[202:205], v[42:45]
	v_mfma_f32_16x16x32_bf16 v[30:33], v[142:145], v[210:213], v[30:33]
	v_mfma_f32_16x16x32_bf16 v[26:29], v[168:171], v[210:213], v[26:29]
	v_mfma_f32_16x16x32_bf16 v[14:17], v[142:145], v[218:221], v[14:17]
	v_mfma_f32_16x16x32_bf16 v[10:13], v[168:171], v[218:221], v[10:13]
	v_mfma_f32_16x16x32_bf16 v[62:65], v[164:167], v[198:201], v[62:65]
	v_mfma_f32_16x16x32_bf16 v[58:61], v[172:175], v[198:201], v[58:61]
	v_mfma_f32_16x16x32_bf16 v[46:49], v[164:167], v[206:209], v[46:49]
	v_mfma_f32_16x16x32_bf16 v[42:45], v[172:175], v[206:209], v[42:45]
	v_mfma_f32_16x16x32_bf16 v[30:33], v[164:167], v[214:217], v[30:33]
	v_mfma_f32_16x16x32_bf16 v[26:29], v[172:175], v[214:217], v[26:29]
	v_mfma_f32_16x16x32_bf16 v[14:17], v[164:167], v[222:225], v[14:17]
	v_mfma_f32_16x16x32_bf16 v[10:13], v[172:175], v[222:225], v[10:13]
	v_mfma_f32_16x16x32_bf16 v[54:57], v[176:179], v[194:197], v[54:57]
	v_mfma_f32_16x16x32_bf16 v[50:53], v[184:187], v[194:197], v[50:53]
	v_mfma_f32_16x16x32_bf16 v[38:41], v[176:179], v[202:205], v[38:41]
	v_mfma_f32_16x16x32_bf16 v[34:37], v[184:187], v[202:205], v[34:37]
	v_mfma_f32_16x16x32_bf16 v[22:25], v[176:179], v[210:213], v[22:25]
	v_mfma_f32_16x16x32_bf16 v[18:21], v[184:187], v[210:213], v[18:21]
	v_mfma_f32_16x16x32_bf16 v[6:9], v[176:179], v[218:221], v[6:9]
	v_mfma_f32_16x16x32_bf16 v[2:5], v[184:187], v[218:221], v[2:5]
	v_mfma_f32_16x16x32_bf16 v[54:57], v[180:183], v[198:201], v[54:57]
	v_mfma_f32_16x16x32_bf16 v[50:53], v[190:193], v[198:201], v[50:53]
	v_mfma_f32_16x16x32_bf16 v[38:41], v[180:183], v[206:209], v[38:41]
	v_mfma_f32_16x16x32_bf16 v[34:37], v[190:193], v[206:209], v[34:37]
	v_mfma_f32_16x16x32_bf16 v[22:25], v[180:183], v[214:217], v[22:25]
	v_mfma_f32_16x16x32_bf16 v[18:21], v[190:193], v[214:217], v[18:21]
	v_mfma_f32_16x16x32_bf16 v[6:9], v[180:183], v[222:225], v[6:9]
	v_mfma_f32_16x16x32_bf16 v[2:5], v[190:193], v[222:225], v[2:5]
	s_add_i32 s67, s67, 2
	s_add_u32 s65, s65, 0x100
	s_addc_u32 s66, s66, 0
	s_add_u32 s34, s34, 0x10000
	s_addc_u32 s35, s35, 0
	s_cmpk_gt_u32 s67, 0xa9
	s_barrier
	s_cbranch_scc0 .LBB0_1069
	s_and_b64 vcc, exec, s[18:19]
	s_cbranch_vccz .LBB0_1072
	s_barrier

; #define PG8_STAGE(bufoff, gbase, voff) do { _Pragma("unroll") for (int _i = 0; _i < 2; ++_i) \
;         __builtin_amdgcn_global_load_lds((const unsigned*)((const char*)(gbase) + (voff)[_i]), (PG8_LAS unsigned*)(lds + (bufoff) + ldsw + _i * 8192), 16, 0, 0); } while (0)
; #define PG8_LDA(dst, b, h) do { _Pragma("unroll") for (int m = 0; m < 4; ++m) _Pragma("unroll") for (int k = 0; k < 2; ++k) dst[m][k] = *(const PG8_LAS bf16x8*)(lds + PG8_SA(b, h) + aoff + m * 2048 + k * 1024); } while (0)
; #define PG8_LDB(dst, b, h) do { _Pragma("unroll") for (int n = 0; n < 2; ++n) _Pragma("unroll") for (int k = 0; k < 2; ++k) dst[n][k] = *(const PG8_LAS bf16x8*)(lds + PG8_SB(b, h) + boff + n * 2048 + k * 1024); } while (0)
; #define PG8_MMA(ai, bj, At, Bt) do { __builtin_amdgcn_s_setprio(1); _Pragma("unroll") for (int m = 0; m < 4; ++m) _Pragma("unroll") for (int n = 0; n < 2; ++n) _Pragma("unroll") for (int k = 0; k < 2; ++k) \
;         acc[ai][bj][m][n] = __builtin_amdgcn_mfma_f32_16x16x32_bf16(Bt[n][k], At[m][k], acc[ai][bj][m][n], 0, 0, 0); __builtin_amdgcn_s_setprio(0); } while (0)
; #define PG8_WAIT_V(n) asm volatile("s_waitcnt vmcnt(" #n ")" ::: "memory")
; #define PG8_WAIT_L(n) asm volatile("s_waitcnt lgkmcnt(" #n ")" ::: "memory")
; #define PG8_BAR __builtin_amdgcn_s_barrier()
; #define PG8_SCHED __builtin_amdgcn_sched_barrier(0)
; template <class Epi, class Sched, bool ALIGN_EPI = false, bool SP2 = false, bool A_TILED = false, bool B_TILED = false>
; __device__ __forceinline__ void gemm_phase(PG8_LAS unsigned char* lds, const Gemm g, const Sched& S, const Epi& E) {
;     ...
;             const char* a1 = cA + (size_t)(t + 1) * kstepA;
;             const char* a2 = last ? nA : cA + (size_t)(t + 2) * kstepA; const char* b2 = last ? nB : cB + (size_t)(t + 2) * kstepB;
;             const char* a3 = a2 + kstepA; const char* b3 = b2 + kstepB;
;             if (last && has_next) S.a_ready(nxt);
;             if constexpr (SP2) {
;             PG8_LDB(B0, 0, 0); PG8_LDB(B1, 0, 1); PG8_SCHED; PG8_LDA(At, 0, 0); PG8_STAGE(PG8_SA(1, 1), a1 + hstepA, voffA);
;             PG8_WAIT_V(8); PG8_WAIT_L(0); PG8_BAR; PG8_MMA(0, 0, At, B0); PG8_MMA(0, 1, At, B1); PG8_BAR; PG8_SCHED;
;             PG8_LDA(At, 0, 1); PG8_STAGE(PG8_SB(0, 0), b2, voffB); PG8_STAGE(PG8_SB(0, 1), b2 + hstepB, voffB); PG8_STAGE(PG8_SA(0, 0), a2, voffA);
.LBB0_1097:
	ds_read_b128 v[146:149], v143
	ds_read_b128 v[150:153], v143 offset:1024
	ds_read_b128 v[154:157], v143 offset:2048
	ds_read_b128 v[158:161], v143 offset:3072
	ds_read_b128 v[162:165], v144
	ds_read_b128 v[166:169], v144 offset:1024
	ds_read_b128 v[170:173], v144 offset:2048
	ds_read_b128 v[174:177], v144 offset:3072
	s_add_i32 s55, s26, 2
	s_add_u32 s27, s24, 0x4000
	s_addc_u32 s28, s25, 0
	s_cmp_eq_u32 s17, s26
	s_cselect_b32 s30, s20, s27
	s_cselect_b32 s31, s21, s28
	s_cselect_b32 s28, s22, s53
	s_cselect_b32 s29, s23, s54
	s_add_u32 s26, s30, 0x8000
	s_addc_u32 s27, s31, 0
	v_lshl_add_u64 v[186:187], s[24:25], 0, v[138:139]
	s_add_i32 m0, s35, 0xc000
	ds_read_b128 v[178:181], v145
	ds_read_b128 v[182:185], v145 offset:1024
	ds_read_b128 v[190:193], v145 offset:2048
	ds_read_b128 v[194:197], v145 offset:3072
	ds_read_b128 v[198:201], v145 offset:4096
	ds_read_b128 v[202:205], v145 offset:5120
	ds_read_b128 v[206:209], v145 offset:6144
	ds_read_b128 v[210:213], v145 offset:7168
	global_load_lds_dwordx4 v[186:187], off
	v_lshl_add_u64 v[186:187], s[24:25], 0, v[140:141]
	s_add_i32 m0, s35, 0xe000
	s_nop 0
	global_load_lds_dwordx4 v[186:187], off
	s_waitcnt vmcnt(8)
	s_waitcnt lgkmcnt(0)
	s_barrier
	v_mfma_f32_16x16x32_bf16 v[124:127], v[146:149], v[178:181], v[124:127]
	v_mfma_f32_16x16x32_bf16 v[120:123], v[154:157], v[178:181], v[120:123]
	v_mfma_f32_16x16x32_bf16 v[116:119], v[146:149], v[190:193], v[116:119]
	v_mfma_f32_16x16x32_bf16 v[112:115], v[154:157], v[190:193], v[112:115]
	v_mfma_f32_16x16x32_bf16 v[108:111], v[146:149], v[198:201], v[108:111]
	v_mfma_f32_16x16x32_bf16 v[100:103], v[154:157], v[198:201], v[100:103]
	v_mfma_f32_16x16x32_bf16 v[92:95], v[146:149], v[206:209], v[92:95]
	v_mfma_f32_16x16x32_bf16 v[84:87], v[154:157], v[206:209], v[84:87]
	v_mfma_f32_16x16x32_bf16 v[124:127], v[150:153], v[182:185], v[124:127]
	v_mfma_f32_16x16x32_bf16 v[120:123], v[158:161], v[182:185], v[120:123]
	v_mfma_f32_16x16x32_bf16 v[116:119], v[150:153], v[194:197], v[116:119]
	v_mfma_f32_16x16x32_bf16 v[112:115], v[158:161], v[194:197], v[112:115]
	v_mfma_f32_16x16x32_bf16 v[108:111], v[150:153], v[202:205], v[108:111]
	v_mfma_f32_16x16x32_bf16 v[100:103], v[158:161], v[202:205], v[100:103]
	v_mfma_f32_16x16x32_bf16 v[92:95], v[150:153], v[210:213], v[92:95]
	v_mfma_f32_16x16x32_bf16 v[84:87], v[158:161], v[210:213], v[84:87]
	v_mfma_f32_16x16x32_bf16 v[104:107], v[162:165], v[178:181], v[104:107]
	v_mfma_f32_16x16x32_bf16 v[96:99], v[170:173], v[178:181], v[96:99]
	v_mfma_f32_16x16x32_bf16 v[88:91], v[162:165], v[190:193], v[88:91]
	v_mfma_f32_16x16x32_bf16 v[80:83], v[170:173], v[190:193], v[80:83]
	v_mfma_f32_16x16x32_bf16 v[76:79], v[162:165], v[198:201], v[76:79]
	v_mfma_f32_16x16x32_bf16 v[72:75], v[170:173], v[198:201], v[72:75]
	v_mfma_f32_16x16x32_bf16 v[68:71], v[162:165], v[206:209], v[68:71]
	v_mfma_f32_16x16x32_bf16 v[64:67], v[170:173], v[206:209], v[64:67]
	v_mfma_f32_16x16x32_bf16 v[104:107], v[166:169], v[182:185], v[104:107]
	v_mfma_f32_16x16x32_bf16 v[96:99], v[174:177], v[182:185], v[96:99]
	v_mfma_f32_16x16x32_bf16 v[88:91], v[166:169], v[194:197], v[88:91]
	v_mfma_f32_16x16x32_bf16 v[80:83], v[174:177], v[194:197], v[80:83]
	v_mfma_f32_16x16x32_bf16 v[76:79], v[166:169], v[202:205], v[76:79]
	v_mfma_f32_16x16x32_bf16 v[72:75], v[174:177], v[202:205], v[72:75]
	v_mfma_f32_16x16x32_bf16 v[68:71], v[166:169], v[210:213], v[68:71]
	v_mfma_f32_16x16x32_bf16 v[64:67], v[174:177], v[210:213], v[64:67]
	s_barrier
	s_add_i32 s56, s6, s34
	v_lshl_add_u64 v[186:187], s[28:29], 0, v[128:129]
	s_mov_b32 m0, s56
	ds_read_b128 v[178:181], v145 offset:16384
	ds_read_b128 v[182:185], v145 offset:17408
	ds_read_b128 v[190:193], v145 offset:18432
	ds_read_b128 v[194:197], v145 offset:19456
	ds_read_b128 v[198:201], v145 offset:20480
	ds_read_b128 v[202:205], v145 offset:21504
	ds_read_b128 v[206:209], v145 offset:22528
	ds_read_b128 v[210:213], v145 offset:23552
	global_load_lds_dwordx4 v[186:187], off
	s_add_i32 m0, s56, 0x2000
	s_add_u32 s56, s28, 0x2b0000
	v_lshl_add_u64 v[214:215], s[28:29], 0, v[134:135]
	s_addc_u32 s57, s29, 0
	s_add_i32 s58, s41, s34
	global_load_lds_dwordx4 v[214:215], off
	v_lshl_add_u64 v[216:217], s[56:57], 0, v[128:129]
	s_mov_b32 m0, s58
	s_nop 0
	global_load_lds_dwordx4 v[216:217], off
	v_lshl_add_u64 v[216:217], s[56:57], 0, v[134:135]
	s_add_i32 m0, s58, 0x2000
	s_nop 0
	global_load_lds_dwordx4 v[216:217], off
	v_lshl_add_u64 v[216:217], s[30:31], 0, v[130:131]
	s_mov_b32 m0, s35
	s_nop 0
	global_load_lds_dwordx4 v[216:217], off
	v_lshl_add_u64 v[216:217], s[30:31], 0, v[132:133]
	s_mov_b32 m0, s36
	s_nop 0
	global_load_lds_dwordx4 v[216:217], off
	s_waitcnt vmcnt(8)
	s_waitcnt lgkmcnt(0)
	s_barrier
; #define PG8_STAGE(bufoff, gbase, voff) do { _Pragma("unroll") for (int _i = 0; _i < 2; ++_i) \
;         __builtin_amdgcn_global_load_lds((const unsigned*)((const char*)(gbase) + (voff)[_i]), (PG8_LAS unsigned*)(lds + (bufoff) + ldsw + _i * 8192), 16, 0, 0); } while (0)
; #define PG8_LDA(dst, b, h) do { _Pragma("unroll") for (int m = 0; m < 4; ++m) _Pragma("unroll") for (int k = 0; k < 2; ++k) dst[m][k] = *(const PG8_LAS bf16x8*)(lds + PG8_SA(b, h) + aoff + m * 2048 + k * 1024); } while (0)
; #define PG8_LDB(dst, b, h) do { _Pragma("unroll") for (int n = 0; n < 2; ++n) _Pragma("unroll") for (int k = 0; k < 2; ++k) dst[n][k] = *(const PG8_LAS bf16x8*)(lds + PG8_SB(b, h) + boff + n * 2048 + k * 1024); } while (0)
; #define PG8_MMA(ai, bj, At, Bt) do { __builtin_amdgcn_s_setprio(1); _Pragma("unroll") for (int m = 0; m < 4; ++m) _Pragma("unroll") for (int n = 0; n < 2; ++n) _Pragma("unroll") for (int k = 0; k < 2; ++k) \
;         acc[ai][bj][m][n] = __builtin_amdgcn_mfma_f32_16x16x32_bf16(Bt[n][k], At[m][k], acc[ai][bj][m][n], 0, 0, 0); __builtin_amdgcn_s_setprio(0); } while (0)
; #define PG8_WAIT_V(n) asm volatile("s_waitcnt vmcnt(" #n ")" ::: "memory")
; #define PG8_WAIT_L(n) asm volatile("s_waitcnt lgkmcnt(" #n ")" ::: "memory")
; #define PG8_BAR __builtin_amdgcn_s_barrier()
; #define PG8_SCHED __builtin_amdgcn_sched_barrier(0)
; template <class Epi, class Sched, bool ALIGN_EPI = false, bool SP2 = false, bool A_TILED = false, bool B_TILED = false>
; __device__ __forceinline__ void gemm_phase(PG8_LAS unsigned char* lds, const Gemm g, const Sched& S, const Epi& E) {
;     ...
;             PG8_WAIT_V(8); PG8_WAIT_L(0); PG8_BAR; PG8_MMA(1, 0, At, B0); PG8_MMA(1, 1, At, B1); PG8_BAR; PG8_SCHED;
;             PG8_LDB(B0, 1, 0); PG8_LDB(B1, 1, 1); PG8_SCHED; PG8_LDA(At, 1, 0); PG8_STAGE(PG8_SA(0, 1), a2 + hstepA, voffA);
;             PG8_WAIT_V(8); PG8_WAIT_L(0); PG8_BAR; PG8_MMA(0, 0, At, B0); PG8_MMA(0, 1, At, B1); PG8_BAR; PG8_SCHED;
	v_mfma_f32_16x16x32_bf16 v[60:63], v[146:149], v[178:181], v[60:63]
	v_mfma_f32_16x16x32_bf16 v[56:59], v[154:157], v[178:181], v[56:59]
	v_mfma_f32_16x16x32_bf16 v[52:55], v[146:149], v[190:193], v[52:55]
	v_mfma_f32_16x16x32_bf16 v[48:51], v[154:157], v[190:193], v[48:51]
	v_mfma_f32_16x16x32_bf16 v[44:47], v[146:149], v[198:201], v[44:47]
	v_mfma_f32_16x16x32_bf16 v[36:39], v[154:157], v[198:201], v[36:39]
	v_mfma_f32_16x16x32_bf16 v[28:31], v[146:149], v[206:209], v[28:31]
	v_mfma_f32_16x16x32_bf16 v[20:23], v[154:157], v[206:209], v[20:23]
	v_mfma_f32_16x16x32_bf16 v[60:63], v[150:153], v[182:185], v[60:63]
	v_mfma_f32_16x16x32_bf16 v[56:59], v[158:161], v[182:185], v[56:59]
	v_mfma_f32_16x16x32_bf16 v[52:55], v[150:153], v[194:197], v[52:55]
	v_mfma_f32_16x16x32_bf16 v[48:51], v[158:161], v[194:197], v[48:51]
	v_mfma_f32_16x16x32_bf16 v[44:47], v[150:153], v[202:205], v[44:47]
	v_mfma_f32_16x16x32_bf16 v[36:39], v[158:161], v[202:205], v[36:39]
	v_mfma_f32_16x16x32_bf16 v[28:31], v[150:153], v[210:213], v[28:31]
	v_mfma_f32_16x16x32_bf16 v[20:23], v[158:161], v[210:213], v[20:23]
	v_mfma_f32_16x16x32_bf16 v[40:43], v[162:165], v[178:181], v[40:43]
	v_mfma_f32_16x16x32_bf16 v[32:35], v[170:173], v[178:181], v[32:35]
	v_mfma_f32_16x16x32_bf16 v[24:27], v[162:165], v[190:193], v[24:27]
	v_mfma_f32_16x16x32_bf16 v[16:19], v[170:173], v[190:193], v[16:19]
	v_mfma_f32_16x16x32_bf16 v[12:15], v[162:165], v[198:201], v[12:15]
	v_mfma_f32_16x16x32_bf16 v[8:11], v[170:173], v[198:201], v[8:11]
	v_mfma_f32_16x16x32_bf16 v[4:7], v[162:165], v[206:209], v[4:7]
	v_mfma_f32_16x16x32_bf16 v[0:3], v[170:173], v[206:209], v[0:3]
	v_mfma_f32_16x16x32_bf16 v[40:43], v[166:169], v[182:185], v[40:43]
	v_mfma_f32_16x16x32_bf16 v[32:35], v[174:177], v[182:185], v[32:35]
	v_mfma_f32_16x16x32_bf16 v[24:27], v[166:169], v[194:197], v[24:27]
	v_mfma_f32_16x16x32_bf16 v[16:19], v[174:177], v[194:197], v[16:19]
	v_mfma_f32_16x16x32_bf16 v[12:15], v[166:169], v[202:205], v[12:15]
	v_mfma_f32_16x16x32_bf16 v[8:11], v[174:177], v[202:205], v[8:11]
	v_mfma_f32_16x16x32_bf16 v[4:7], v[166:169], v[210:213], v[4:7]
	v_mfma_f32_16x16x32_bf16 v[0:3], v[174:177], v[210:213], v[0:3]
	s_barrier
	s_add_i32 s56, 0, 0x18000
	s_add_i32 s57, 0, 0x1c000
	v_add_u32_e32 v158, s56, v142
	v_add_u32_e32 v174, s57, v142
	ds_read_b128 v[146:149], v158
	ds_read_b128 v[150:153], v158 offset:1024
	ds_read_b128 v[154:157], v158 offset:2048
	ds_read_b128 v[158:161], v158 offset:3072
	ds_read_b128 v[162:165], v174
	ds_read_b128 v[166:169], v174 offset:1024
	ds_read_b128 v[170:173], v174 offset:2048
	ds_read_b128 v[174:177], v174 offset:3072
	s_add_u32 s30, s30, 0x4000
	s_addc_u32 s31, s31, 0
	s_mov_b32 m0, s37
	v_lshl_add_u64 v[216:217], s[30:31], 0, v[130:131]
	ds_read_b128 v[178:181], v145 offset:32768
	ds_read_b128 v[182:185], v145 offset:33792
	ds_read_b128 v[190:193], v145 offset:34816
	ds_read_b128 v[194:197], v145 offset:35840
	ds_read_b128 v[198:201], v145 offset:36864
	ds_read_b128 v[202:205], v145 offset:37888
	ds_read_b128 v[206:209], v145 offset:38912
	ds_read_b128 v[210:213], v145 offset:39936
	global_load_lds_dwordx4 v[216:217], off
	v_lshl_add_u64 v[216:217], s[30:31], 0, v[132:133]
	s_mov_b32 m0, s38
	s_nop 0
	global_load_lds_dwordx4 v[216:217], off
	s_waitcnt vmcnt(8)
	s_waitcnt lgkmcnt(0)
	s_barrier
	v_mfma_f32_16x16x32_bf16 v[124:127], v[146:149], v[178:181], v[124:127]
	v_mfma_f32_16x16x32_bf16 v[120:123], v[154:157], v[178:181], v[120:123]
	v_mfma_f32_16x16x32_bf16 v[116:119], v[146:149], v[190:193], v[116:119]
	v_mfma_f32_16x16x32_bf16 v[112:115], v[154:157], v[190:193], v[112:115]
	v_mfma_f32_16x16x32_bf16 v[108:111], v[146:149], v[198:201], v[108:111]
	v_mfma_f32_16x16x32_bf16 v[100:103], v[154:157], v[198:201], v[100:103]
	v_mfma_f32_16x16x32_bf16 v[92:95], v[146:149], v[206:209], v[92:95]
	v_mfma_f32_16x16x32_bf16 v[84:87], v[154:157], v[206:209], v[84:87]
	v_mfma_f32_16x16x32_bf16 v[124:127], v[150:153], v[182:185], v[124:127]
	v_mfma_f32_16x16x32_bf16 v[120:123], v[158:161], v[182:185], v[120:123]
	v_mfma_f32_16x16x32_bf16 v[116:119], v[150:153], v[194:197], v[116:119]
	v_mfma_f32_16x16x32_bf16 v[112:115], v[158:161], v[194:197], v[112:115]
	v_mfma_f32_16x16x32_bf16 v[108:111], v[150:153], v[202:205], v[108:111]
	v_mfma_f32_16x16x32_bf16 v[100:103], v[158:161], v[202:205], v[100:103]
	v_mfma_f32_16x16x32_bf16 v[92:95], v[150:153], v[210:213], v[92:95]
	v_mfma_f32_16x16x32_bf16 v[84:87], v[158:161], v[210:213], v[84:87]
	v_mfma_f32_16x16x32_bf16 v[104:107], v[162:165], v[178:181], v[104:107]
	v_mfma_f32_16x16x32_bf16 v[96:99], v[170:173], v[178:181], v[96:99]
	v_mfma_f32_16x16x32_bf16 v[88:91], v[162:165], v[190:193], v[88:91]
	v_mfma_f32_16x16x32_bf16 v[80:83], v[170:173], v[190:193], v[80:83]
	v_mfma_f32_16x16x32_bf16 v[76:79], v[162:165], v[198:201], v[76:79]
	v_mfma_f32_16x16x32_bf16 v[72:75], v[170:173], v[198:201], v[72:75]
	v_mfma_f32_16x16x32_bf16 v[68:71], v[162:165], v[206:209], v[68:71]
	v_mfma_f32_16x16x32_bf16 v[64:67], v[170:173], v[206:209], v[64:67]
	v_mfma_f32_16x16x32_bf16 v[104:107], v[166:169], v[182:185], v[104:107]
	v_mfma_f32_16x16x32_bf16 v[96:99], v[174:177], v[182:185], v[96:99]
	v_mfma_f32_16x16x32_bf16 v[88:91], v[166:169], v[194:197], v[88:91]
	v_mfma_f32_16x16x32_bf16 v[80:83], v[174:177], v[194:197], v[80:83]
	v_mfma_f32_16x16x32_bf16 v[76:79], v[166:169], v[202:205], v[76:79]
	v_mfma_f32_16x16x32_bf16 v[72:75], v[174:177], v[202:205], v[72:75]
	v_mfma_f32_16x16x32_bf16 v[68:71], v[166:169], v[210:213], v[68:71]
	v_mfma_f32_16x16x32_bf16 v[64:67], v[174:177], v[210:213], v[64:67]
	s_barrier
; #define PG8_STAGE(bufoff, gbase, voff) do { _Pragma("unroll") for (int _i = 0; _i < 2; ++_i) \
;         __builtin_amdgcn_global_load_lds((const unsigned*)((const char*)(gbase) + (voff)[_i]), (PG8_LAS unsigned*)(lds + (bufoff) + ldsw + _i * 8192), 16, 0, 0); } while (0)
; #define PG8_LDA(dst, b, h) do { _Pragma("unroll") for (int m = 0; m < 4; ++m) _Pragma("unroll") for (int k = 0; k < 2; ++k) dst[m][k] = *(const PG8_LAS bf16x8*)(lds + PG8_SA(b, h) + aoff + m * 2048 + k * 1024); } while (0)
; #define PG8_MMA(ai, bj, At, Bt) do { __builtin_amdgcn_s_setprio(1); _Pragma("unroll") for (int m = 0; m < 4; ++m) _Pragma("unroll") for (int n = 0; n < 2; ++n) _Pragma("unroll") for (int k = 0; k < 2; ++k) \
;         acc[ai][bj][m][n] = __builtin_amdgcn_mfma_f32_16x16x32_bf16(Bt[n][k], At[m][k], acc[ai][bj][m][n], 0, 0, 0); __builtin_amdgcn_s_setprio(0); } while (0)
; #define PG8_WAIT_V(n) asm volatile("s_waitcnt vmcnt(" #n ")" ::: "memory")
; #define PG8_WAIT_L(n) asm volatile("s_waitcnt lgkmcnt(" #n ")" ::: "memory")
; #define PG8_BAR __builtin_amdgcn_s_barrier()
; #define PG8_SCHED __builtin_amdgcn_sched_barrier(0)
; template <class Epi, class Sched, bool ALIGN_EPI = false, bool SP2 = false, bool A_TILED = false, bool B_TILED = false>
; __device__ __forceinline__ void gemm_phase(PG8_LAS unsigned char* lds, const Gemm g, const Sched& S, const Epi& E) {
;     ...
;         for (int t = 0; t < nt; t += 2) {
;     ...
;             PG8_LDA(At, 1, 1); PG8_STAGE(PG8_SB(1, 0), b3, voffB); PG8_STAGE(PG8_SB(1, 1), b3 + hstepB, voffB); PG8_STAGE(PG8_SA(1, 0), a3, voffA);
;             PG8_WAIT_V(8); PG8_WAIT_L(0); PG8_BAR; PG8_MMA(1, 0, At, B0); PG8_MMA(1, 1, At, B1); PG8_BAR; PG8_SCHED;
	s_add_i32 s30, s56, s34
	v_lshl_add_u64 v[186:187], v[186:187], 0, s[12:13]
	s_mov_b32 m0, s30
	ds_read_b128 v[178:181], v145 offset:49152
	ds_read_b128 v[182:185], v145 offset:50176
	ds_read_b128 v[190:193], v145 offset:51200
	ds_read_b128 v[194:197], v145 offset:52224
	ds_read_b128 v[198:201], v145 offset:53248
	ds_read_b128 v[202:205], v145 offset:54272
	ds_read_b128 v[206:209], v145 offset:55296
	ds_read_b128 v[210:213], v145 offset:56320
	global_load_lds_dwordx4 v[186:187], off
	s_add_i32 m0, s30, 0x2000
	s_add_u32 s28, s28, 0x2b0080
	v_lshl_add_u64 v[186:187], v[214:215], 0, s[12:13]
	s_addc_u32 s29, s29, 0
	s_add_i32 s30, s57, s34
	global_load_lds_dwordx4 v[186:187], off
	v_lshl_add_u64 v[186:187], s[28:29], 0, v[128:129]
	s_mov_b32 m0, s30
	s_nop 0
	global_load_lds_dwordx4 v[186:187], off
	v_lshl_add_u64 v[186:187], s[28:29], 0, v[134:135]
	s_add_i32 m0, s30, 0x2000
	s_nop 0
	global_load_lds_dwordx4 v[186:187], off
	v_lshl_add_u64 v[186:187], s[26:27], 0, v[130:131]
	s_mov_b32 m0, s39
	s_nop 0
	global_load_lds_dwordx4 v[186:187], off
	v_lshl_add_u64 v[186:187], s[26:27], 0, v[132:133]
	s_mov_b32 m0, s40
	s_nop 0
	global_load_lds_dwordx4 v[186:187], off
	s_waitcnt vmcnt(8)
	s_waitcnt lgkmcnt(0)
	s_barrier
	v_mfma_f32_16x16x32_bf16 v[60:63], v[146:149], v[178:181], v[60:63]
	v_mfma_f32_16x16x32_bf16 v[56:59], v[154:157], v[178:181], v[56:59]
	v_mfma_f32_16x16x32_bf16 v[52:55], v[146:149], v[190:193], v[52:55]
	v_mfma_f32_16x16x32_bf16 v[48:51], v[154:157], v[190:193], v[48:51]
	v_mfma_f32_16x16x32_bf16 v[44:47], v[146:149], v[198:201], v[44:47]
	v_mfma_f32_16x16x32_bf16 v[36:39], v[154:157], v[198:201], v[36:39]
	v_mfma_f32_16x16x32_bf16 v[28:31], v[146:149], v[206:209], v[28:31]
	v_mfma_f32_16x16x32_bf16 v[20:23], v[154:157], v[206:209], v[20:23]
	v_mfma_f32_16x16x32_bf16 v[60:63], v[150:153], v[182:185], v[60:63]
	v_mfma_f32_16x16x32_bf16 v[56:59], v[158:161], v[182:185], v[56:59]
	v_mfma_f32_16x16x32_bf16 v[52:55], v[150:153], v[194:197], v[52:55]
	v_mfma_f32_16x16x32_bf16 v[48:51], v[158:161], v[194:197], v[48:51]
	v_mfma_f32_16x16x32_bf16 v[44:47], v[150:153], v[202:205], v[44:47]
	v_mfma_f32_16x16x32_bf16 v[36:39], v[158:161], v[202:205], v[36:39]
	v_mfma_f32_16x16x32_bf16 v[28:31], v[150:153], v[210:213], v[28:31]
	v_mfma_f32_16x16x32_bf16 v[20:23], v[158:161], v[210:213], v[20:23]
	v_mfma_f32_16x16x32_bf16 v[40:43], v[162:165], v[178:181], v[40:43]
	v_mfma_f32_16x16x32_bf16 v[32:35], v[170:173], v[178:181], v[32:35]
	v_mfma_f32_16x16x32_bf16 v[24:27], v[162:165], v[190:193], v[24:27]
	v_mfma_f32_16x16x32_bf16 v[16:19], v[170:173], v[190:193], v[16:19]
	v_mfma_f32_16x16x32_bf16 v[12:15], v[162:165], v[198:201], v[12:15]
	v_mfma_f32_16x16x32_bf16 v[8:11], v[170:173], v[198:201], v[8:11]
	v_mfma_f32_16x16x32_bf16 v[4:7], v[162:165], v[206:209], v[4:7]
	v_mfma_f32_16x16x32_bf16 v[0:3], v[170:173], v[206:209], v[0:3]
	v_mfma_f32_16x16x32_bf16 v[40:43], v[166:169], v[182:185], v[40:43]
	v_mfma_f32_16x16x32_bf16 v[32:35], v[174:177], v[182:185], v[32:35]
	v_mfma_f32_16x16x32_bf16 v[24:27], v[166:169], v[194:197], v[24:27]
	v_mfma_f32_16x16x32_bf16 v[16:19], v[174:177], v[194:197], v[16:19]
	v_mfma_f32_16x16x32_bf16 v[12:15], v[166:169], v[202:205], v[12:15]
	v_mfma_f32_16x16x32_bf16 v[8:11], v[174:177], v[202:205], v[8:11]
	v_mfma_f32_16x16x32_bf16 v[4:7], v[166:169], v[210:213], v[4:7]
	v_mfma_f32_16x16x32_bf16 v[0:3], v[174:177], v[210:213], v[0:3]
	s_add_u32 s53, s53, 0x100
	s_addc_u32 s54, s54, 0
	s_add_u32 s24, s24, 0x10000
	s_addc_u32 s25, s25, 0
	s_cmp_ge_i32 s55, s19
	s_mov_b32 s26, s55
	s_barrier
	s_cbranch_scc0 .LBB0_1097
	s_and_b64 vcc, exec, s[14:15]
	s_cbranch_vccz .LBB0_1100
	s_barrier
